# removed initial cooperative-groups grid.sync (census barrier does not need it); write-through sc0 sc1 stores in row-pass/prep phases to shorten barrier L2 writeback
# speedup vs baseline: 1.0045x; 1.0045x over previous
; #define LAS __attribute__((address_space(3)))
; __device__ __forceinline__ unsigned xb_add(unsigned* p, unsigned v) { return __hip_atomic_fetch_add(p, v, __ATOMIC_RELAXED, __HIP_MEMORY_SCOPE_AGENT); }
; __device__ __forceinline__ unsigned xb_xcc_id() { return (unsigned)__builtin_amdgcn_s_getreg((3 << 11) | 20) & 0xFu; }
; __device__ __forceinline__ KAP kargs() { KAP p = (KAP)__builtin_amdgcn_kernarg_segment_ptr(); asm volatile("" : "+s"(p)); return p; }
; __device__ __forceinline__ XcdBarrier xcd_barrier_post(unsigned* bar, volatile LAS unsigned* st) {
;     XcdBarrier b; b.bar = bar; b.x = xb_xcc_id(); b.st = st;
;     if (threadIdx.x == 0) (void)xb_add(&bar[XB_XCNT(b.x)], 1u);
;     return b;
; __global__ void __launch_bounds__(NTHR, 2) fwd_megakernel(KArgs args) {
;     ...
;     volatile LAS unsigned* MISC = (volatile LAS unsigned*)(ldsl + 131072 + 64);
;     if (threadIdx.x < 2) MISC[threadIdx.x] = 0u;
;     __syncthreads();
;     grid.sync();
;     XcdBarrier bar = xcd_barrier_post((unsigned*)(kargs()->ws + WS_BAR), MISC);
_Z14fwd_megakernel5KArgs:
	s_mov_b32 s87, s2
	s_load_dwordx2 s[74:75], s[0:1], 0xf8
	s_load_dword s2, s[0:1], 0x100
	s_add_u32 s6, s0, 0xf8
	v_and_b32_e32 v1, 0x3ff, v0
	s_addc_u32 s7, s1, 0
	s_movk_i32 s3, 0x3ff
	v_readfirstlane_b32 s12, v1
	v_cmp_gt_u32_e32 vcc, 2, v1
	s_and_saveexec_b64 s[4:5], vcc
	v_lshl_add_u32 v2, v1, 2, 0
	v_add_u32_e32 v2, 0x20040, v2
	v_mov_b32_e32 v3, 0
	ds_write_b32 v2, v3
	s_or_b64 exec, exec, s[4:5]
	v_lshrrev_b32_e32 v2, 20, v0
	v_lshrrev_b32_e32 v0, 10, v0
	v_or_b32_e32 v0, v0, v2
	v_and_or_b32 v0, v0, s3, v1
	v_cmp_eq_u32_e32 vcc, 0, v0
	s_waitcnt lgkmcnt(0)
	s_barrier
	s_barrier
	s_and_saveexec_b64 s[4:5], vcc
.LBB0_12:
	s_or_b64 exec, exec, s[4:5]
	s_mov_b64 s[4:5], s[0:1]
	s_barrier
	s_load_dwordx2 s[16:17], s[4:5], 0xf0
	s_getreg_b32 s3, hwreg(HW_REG_XCC_ID, 0, 4)
	v_cmp_eq_u32_e64 s[6:7], 0, v1
	s_waitcnt lgkmcnt(0)
	s_add_u32 s18, s16, 0x80000
	s_addc_u32 s19, s17, 0
	s_and_b32 s3, s3, 15
	s_mov_b64 s[4:5], exec
	v_writelane_b32 v253, s6, 0
	s_nop 1
	v_writelane_b32 v253, s7, 1
	s_and_b64 s[6:7], s[4:5], s[6:7]
	s_mov_b64 exec, s[6:7]
	s_cbranch_execz .LBB0_15
	s_mov_b64 s[6:7], exec
	v_mbcnt_lo_u32_b32 v0, s6, 0
	v_mbcnt_hi_u32_b32 v0, s7, v0
	v_cmp_eq_u32_e32 vcc, 0, v0
	s_and_b64 s[8:9], exec, vcc
	s_mov_b64 exec, s[8:9]
	s_cbranch_execz .LBB0_15
	s_lshl_b32 s8, s3, 8
	s_bcnt1_i32_b64 s6, s[6:7]
	v_mov_b32_e32 v0, s8
	v_mov_b32_e32 v1, s6
	global_atomic_add v0, v1, s[18:19] offset:1024

; #define LAS __attribute__((address_space(3)))
; __device__ __forceinline__ void pass_pre(const float* hlat, const float* hctx, const float* g, const float* mod, int sh_off, int sc_off, bf16* U, int nrows, int gw, int NGW, int lane, LAS float* lp, int tid) {
;     ...
;     for (int m0 = gw; m0 < nrows; m0 += 2 * NGW) {
;         int mr[2]; mr[0] = m0; mr[1] = m0 + NGW; const bool two = mr[1] < nrows; if (!two) mr[1] = m0;
;         f32x4 v[2][8]; float ss[2];
; #pragma unroll
;         for (int r = 0; r < 2; ++r) { const int m = mr[r]; const float* src = m < MLAT ? hlat + (size_t)m * DM : hctx + (size_t)(m - MLAT) * DM;
; #pragma unroll
;             for (int j = 0; j < 8; ++j) v[r][j] = *(const f32x4*)(src + 256 * j + 4 * lane); }
; #pragma unroll
;         for (int r = 0; r < 2; ++r) { ss[r] = 0.f;
; #pragma unroll
;             for (int j = 0; j < 8; ++j) ss[r] += (v[r][j][0] * v[r][j][0] + v[r][j][1] * v[r][j][1]) + (v[r][j][2] * v[r][j][2] + v[r][j][3] * v[r][j][3]); }
; #pragma unroll
;         for (int r = 0; r < 2; ++r) { if (r == 1 && !two) break; const int m = mr[r]; const LAS float* mv = lp + 4096 + 3 * (m < MLAT ? (m >> 13) : 2) * 2048;
;             const float rstd = rsqrtf(wave_sum(ss[r], lane) * (1.0f / DM) + EPS);
.LBB0_174:
	s_add_i32 s28, s33, s34
	s_cmpk_lt_i32 s28, 0x4200
	s_cselect_b32 s6, s28, s34
	s_add_i32 s7, s34, 0xffffc000
	s_add_u32 s8, s16, s26
	s_addc_u32 s9, s17, s27
	s_cmpk_lt_i32 s34, 0x4000
	s_cselect_b32 s31, s9, 0
	s_cselect_b32 s30, s8, s7
	s_cselect_b32 s7, s19, s21
	s_cselect_b32 s8, s18, s20
	s_lshl_b64 s[30:31], s[30:31], 13
	s_add_u32 s30, s8, s30
	s_addc_u32 s31, s7, s31
	global_load_dwordx4 v[32:35], v64, s[30:31] offset:2048
	global_load_dwordx4 v[60:63], v64, s[30:31]
	global_load_dwordx4 v[56:59], v64, s[30:31] offset:1024
	global_load_dwordx4 v[52:55], v64, s[30:31] offset:3072
	s_waitcnt vmcnt(17)
	v_lshl_add_u64 v[36:37], s[30:31], 0, v[64:65]
	v_add_co_u32_e32 v36, vcc, s2, v36
	s_ashr_i32 s7, s6, 31
	s_nop 0
	v_addc_co_u32_e32 v37, vcc, 0, v37, vcc
	global_load_dwordx4 v[44:47], v[36:37], off offset:1024
	global_load_dwordx4 v[48:51], v[36:37], off
	global_load_dwordx4 v[40:43], v[36:37], off offset:2048
	s_nop 0
	global_load_dwordx4 v[36:39], v[36:37], off offset:3072
	s_add_i32 s8, s6, 0xffffc000
	s_cmpk_lt_i32 s6, 0x4000
	s_cselect_b32 s7, s7, 0
	s_cselect_b32 s6, s6, s8
	s_cselect_b32 s8, s19, s21
	s_cselect_b32 s9, s18, s20
	s_lshl_b64 s[6:7], s[6:7], 13
	s_add_u32 s30, s9, s6
	s_addc_u32 s31, s8, s7
	s_min_i32 s6, s34, 0x4000
	s_lshr_b32 s6, s6, 13
	s_mulk_i32 s6, 0x6000
	v_add_u32_e32 v112, s6, v77
	s_cmpk_gt_i32 s28, 0x41ff
	s_waitcnt vmcnt(7)
	v_pk_mul_f32 v[80:81], v[34:35], v[34:35]
	v_pk_mul_f32 v[82:83], v[32:33], v[32:33]
	s_waitcnt vmcnt(6)
	v_mov_b32_e32 v86, v61
	s_waitcnt vmcnt(5)
	v_mov_b32_e32 v87, v57
	v_mov_b32_e32 v90, v63
	v_mov_b32_e32 v91, v59
	v_mov_b32_e32 v84, v60
	v_mov_b32_e32 v85, v56
	v_mov_b32_e32 v88, v62
	v_mov_b32_e32 v89, v58
	v_pk_mov_b32 v[94:95], v[82:83], v[80:81] op_sel:[1,0]
	v_mov_b32_e32 v83, v81
	v_pk_mul_f32 v[80:81], v[86:87], v[86:87]
	v_pk_mul_f32 v[86:87], v[90:91], v[90:91]
	v_pk_fma_f32 v[80:81], v[84:85], v[84:85], v[80:81]
	v_pk_fma_f32 v[84:85], v[88:89], v[88:89], v[86:87]
	s_waitcnt vmcnt(4)
	v_mul_f32_e32 v70, v53, v53
	v_mul_f32_e32 v92, v55, v55
	v_pk_add_f32 v[82:83], v[94:95], v[82:83]
	v_pk_add_f32 v[80:81], v[80:81], v[84:85]
	v_pk_fma_f32 v[90:91], v[52:53], v[52:53], v[70:71] op_sel_hi:[1,1,0]
	v_pk_fma_f32 v[92:93], v[54:55], v[54:55], v[92:93] op_sel_hi:[1,1,0]
	s_waitcnt vmcnt(2)
	v_mul_f32_e32 v98, v49, v49
	v_mul_f32_e32 v99, v48, v48
	v_pk_add_f32 v[82:83], v[82:83], v[82:83] op_sel:[0,1] op_sel_hi:[1,0]
	v_pk_add_f32 v[80:81], v[80:81], v[80:81] op_sel:[0,1] op_sel_hi:[1,0]
	v_pk_mul_f32 v[86:87], v[46:47], v[46:47]
	v_pk_mul_f32 v[88:89], v[44:45], v[44:45]
	v_mul_f32_e32 v91, v50, v50
	v_mul_f32_e32 v93, v51, v51
	v_mov_b32_e32 v83, v98
	v_mov_b32_e32 v81, v99
	v_pk_mov_b32 v[84:85], v[88:89], v[86:87] op_sel:[1,0]
	v_mov_b32_e32 v89, v87
	v_pk_add_f32 v[90:91], v[90:91], v[92:93]
	v_pk_add_f32 v[80:81], v[80:81], v[82:83]
	s_waitcnt vmcnt(1)
	v_mul_f32_e32 v70, v41, v41
	v_mul_f32_e32 v94, v43, v43
	v_pk_add_f32 v[84:85], v[84:85], v[88:89]
	v_pk_add_f32 v[80:81], v[80:81], v[90:91]
	s_waitcnt vmcnt(0)
	v_mul_f32_e32 v96, v38, v38
	v_mul_f32_e32 v97, v39, v39
	v_mul_f32_e32 v100, v37, v37
	v_mul_f32_e32 v101, v36, v36
	v_pk_fma_f32 v[86:87], v[40:41], v[40:41], v[70:71] op_sel_hi:[1,1,0]
	v_pk_fma_f32 v[94:95], v[42:43], v[42:43], v[94:95] op_sel_hi:[1,1,0]
	v_pk_add_f32 v[84:85], v[84:85], v[84:85] op_sel:[0,1] op_sel_hi:[1,0]
	v_pk_add_f32 v[80:81], v[80:81], v[80:81] op_sel:[0,1] op_sel_hi:[1,0]
	v_mov_b32_e32 v87, v96
	v_mov_b32_e32 v95, v97
	v_mov_b32_e32 v85, v100
	v_mov_b32_e32 v81, v101
	v_pk_add_f32 v[86:87], v[86:87], v[94:95]
	v_pk_add_f32 v[80:81], v[80:81], v[84:85]
	s_nop 0
	v_pk_add_f32 v[80:81], v[80:81], v[86:87]
	s_nop 0
	v_add_f32_e32 v70, v80, v81
	ds_bpermute_b32 v79, v71, v70
	ds_read_b128 v[80:83], v112 offset:32768
	ds_read_b128 v[84:87], v112 offset:33792
	ds_read_b128 v[88:91], v112 offset:24576
	ds_read_b128 v[92:95], v112 offset:25600
	ds_read_b128 v[96:99], v112 offset:34816
	ds_read_b128 v[100:103], v112 offset:35840
	ds_read_b128 v[104:107], v112 offset:26624
	ds_read_b128 v[108:111], v112 offset:27648
	s_waitcnt lgkmcnt(8)
	v_add_f32_e32 v70, v70, v79
	ds_bpermute_b32 v79, v72, v70
	s_waitcnt lgkmcnt(8)
	v_pk_add_f32 v[80:81], v[80:81], 1.0 op_sel_hi:[1,0]
	s_waitcnt lgkmcnt(7)
	v_pk_add_f32 v[86:87], v[86:87], 1.0 op_sel_hi:[1,0]
	s_waitcnt lgkmcnt(4)
	v_pk_add_f32 v[96:97], v[96:97], 1.0 op_sel_hi:[1,0]
	v_pk_add_f32 v[82:83], v[82:83], 1.0 op_sel_hi:[1,0]
	s_waitcnt lgkmcnt(0)
	v_add_f32_e32 v70, v70, v79
	ds_bpermute_b32 v79, v73, v70
	v_pk_add_f32 v[84:85], v[84:85], 1.0 op_sel_hi:[1,0]
	v_pk_add_f32 v[98:99], v[98:99], 1.0 op_sel_hi:[1,0]
	s_waitcnt lgkmcnt(0)
	v_add_f32_e32 v70, v70, v79
	ds_bpermute_b32 v79, v74, v70
	s_waitcnt lgkmcnt(0)
	v_add_f32_e32 v70, v70, v79
	ds_bpermute_b32 v79, v75, v70
	s_waitcnt lgkmcnt(0)
	v_add_f32_e32 v70, v70, v79
	ds_bpermute_b32 v79, v76, v70
	s_waitcnt lgkmcnt(0)
; #define LAS __attribute__((address_space(3)))
; __device__ __forceinline__ unsigned pk2(float lo, float hi) { return f2bf(lo) | (f2bf(hi) << 16); }
; __device__ __forceinline__ void store_u(bf16* urow, int lane, const f32x4 (&v)[8], float rstd, const LAS float* g, const LAS float* sh, const LAS float* sc) {
; #pragma unroll
;     for (int j = 0; j < 8; ++j) { const int ci = 256 * j + 4 * lane; const f32x4 g4 = *(const LAS f32x4*)(g + ci), s4 = *(const LAS f32x4*)(sc + ci), h4 = *(const LAS f32x4*)(sh + ci);
;         const f32x4 t = (v[j] * rstd * g4) * (1.0f + s4) + h4; v2u w; w.x = pk2(t[0], t[1]); w.y = pk2(t[2], t[3]); *(v2u*)(urow + ci) = w; }
; }
; __device__ __forceinline__ void pass_pre(const float* hlat, const float* hctx, const float* g, const float* mod, int sh_off, int sc_off, bf16* U, int nrows, int gw, int NGW, int lane, LAS float* lp, int tid) {
;     ...
;         for (int r = 0; r < 2; ++r) { if (r == 1 && !two) break; const int m = mr[r]; const LAS float* mv = lp + 4096 + 3 * (m < MLAT ? (m >> 13) : 2) * 2048;
;             const float rstd = rsqrtf(wave_sum(ss[r], lane) * (1.0f / DM) + EPS);
;             store_u(U + (size_t)m * DM, lane, v[r], rstd, lp + 2048, mv + 2048, mv + 4096); }
	v_add_f32_e32 v70, v70, v79
	v_fmamk_f32 v70, v70, 0x3a000000, v78
	v_mul_f32_e32 v79, 0x4b800000, v70
	v_cmp_gt_f32_e32 vcc, s3, v70
	s_nop 1
	v_cndmask_b32_e32 v70, v70, v79, vcc
	v_rsq_f32_e32 v70, v70
	s_nop 0
	v_mul_f32_e32 v79, 0x45800000, v70
	v_cndmask_b32_e32 v70, v70, v79, vcc
	v_pk_mul_f32 v[60:61], v[60:61], v[70:71] op_sel_hi:[1,0]
	v_pk_mul_f32 v[58:59], v[58:59], v[70:71] op_sel_hi:[1,0]
	v_pk_mul_f32 v[32:33], v[32:33], v[70:71] op_sel_hi:[1,0]
	v_pk_mul_f32 v[62:63], v[62:63], v[70:71] op_sel_hi:[1,0]
	v_pk_mul_f32 v[56:57], v[56:57], v[70:71] op_sel_hi:[1,0]
	v_pk_mul_f32 v[34:35], v[34:35], v[70:71] op_sel_hi:[1,0]
	v_pk_mul_f32 v[60:61], v[0:1], v[60:61]
	v_pk_mul_f32 v[58:59], v[6:7], v[58:59]
	v_pk_mul_f32 v[32:33], v[8:9], v[32:33]
	v_pk_mul_f32 v[54:55], v[54:55], v[70:71] op_sel_hi:[1,0]
	v_pk_mul_f32 v[62:63], v[2:3], v[62:63]
	v_pk_mul_f32 v[56:57], v[4:5], v[56:57]
	v_pk_mul_f32 v[34:35], v[10:11], v[34:35]
	v_pk_fma_f32 v[60:61], v[80:81], v[60:61], v[88:89]
	v_pk_fma_f32 v[80:81], v[86:87], v[58:59], v[94:95]
	v_pk_fma_f32 v[86:87], v[96:97], v[32:33], v[104:105]
	v_pk_mul_f32 v[32:33], v[52:53], v[70:71] op_sel_hi:[1,0]
	v_pk_fma_f32 v[62:63], v[82:83], v[62:63], v[90:91]
	v_pk_fma_f32 v[82:83], v[84:85], v[56:57], v[92:93]
	v_pk_fma_f32 v[84:85], v[98:99], v[34:35], v[106:107]
	v_pk_add_f32 v[34:35], v[102:103], 1.0 op_sel_hi:[1,0]
	v_pk_add_f32 v[52:53], v[100:101], 1.0 op_sel_hi:[1,0]
	v_pk_mul_f32 v[54:55], v[54:55], v[14:15]
	v_pk_mul_f32 v[32:33], v[32:33], v[12:13]
	v_pk_fma_f32 v[88:89], v[54:55], v[34:35], v[110:111]
	v_pk_fma_f32 v[90:91], v[32:33], v[52:53], v[108:109]
	ds_read_b128 v[32:35], v112 offset:36864
	v_pk_mul_f32 v[56:57], v[50:51], v[70:71] op_sel_hi:[1,0]
	v_pk_mul_f32 v[58:59], v[48:49], v[70:71] op_sel_hi:[1,0]
	ds_read_b128 v[48:51], v112 offset:37888
	ds_read_b128 v[52:55], v112 offset:28672
	v_pk_mul_f32 v[46:47], v[46:47], v[70:71] op_sel_hi:[1,0]
	s_waitcnt lgkmcnt(2)
	v_pk_add_f32 v[92:93], v[34:35], 1.0 op_sel_hi:[1,0]
	v_pk_add_f32 v[94:95], v[32:33], 1.0 op_sel_hi:[1,0]
	ds_read_b128 v[32:35], v112 offset:29696
	v_pk_mul_f32 v[44:45], v[44:45], v[70:71] op_sel_hi:[1,0]
	s_waitcnt lgkmcnt(2)
	v_pk_add_f32 v[50:51], v[50:51], 1.0 op_sel_hi:[1,0]
	v_pk_mul_f32 v[46:47], v[46:47], v[22:23]
	v_pk_add_f32 v[48:49], v[48:49], 1.0 op_sel_hi:[1,0]
	s_waitcnt lgkmcnt(0)
	v_pk_fma_f32 v[96:97], v[46:47], v[50:51], v[34:35]
	v_pk_mul_f32 v[34:35], v[44:45], v[20:21]
	v_pk_mul_f32 v[56:57], v[56:57], v[18:19]
	v_pk_fma_f32 v[98:99], v[34:35], v[48:49], v[32:33]
	ds_read_b128 v[32:35], v112 offset:38912
	v_pk_fma_f32 v[92:93], v[56:57], v[92:93], v[54:55]
	v_pk_mul_f32 v[54:55], v[58:59], v[16:17]
	v_pk_mul_f32 v[48:49], v[42:43], v[70:71] op_sel_hi:[1,0]
	v_pk_fma_f32 v[94:95], v[54:55], v[94:95], v[52:53]
	v_pk_mul_f32 v[50:51], v[40:41], v[70:71] op_sel_hi:[1,0]
	ds_read_b128 v[40:43], v112 offset:39936
	ds_read_b128 v[44:47], v112 offset:30720
	s_waitcnt lgkmcnt(2)
	v_pk_add_f32 v[52:53], v[34:35], 1.0 op_sel_hi:[1,0]
	v_pk_add_f32 v[54:55], v[32:33], 1.0 op_sel_hi:[1,0]
	ds_read_b128 v[32:35], v112 offset:31744
	v_pk_mul_f32 v[38:39], v[38:39], v[70:71] op_sel_hi:[1,0]
	v_pk_mul_f32 v[36:37], v[36:37], v[70:71] op_sel_hi:[1,0]
	s_waitcnt lgkmcnt(2)
	v_pk_add_f32 v[42:43], v[42:43], 1.0 op_sel_hi:[1,0]
	v_pk_mul_f32 v[38:39], v[38:39], v[30:31]
	v_pk_add_f32 v[40:41], v[40:41], 1.0 op_sel_hi:[1,0]
	s_waitcnt lgkmcnt(0)
	v_pk_fma_f32 v[104:105], v[38:39], v[42:43], v[34:35]
	v_pk_mul_f32 v[34:35], v[36:37], v[28:29]
	v_bfe_u32 v36, v62, 16, 1
	v_pk_fma_f32 v[106:107], v[34:35], v[40:41], v[32:33]
	v_bfe_u32 v34, v60, 16, 1
	v_lshl_add_u64 v[32:33], s[30:31], 0, v[64:65]
	v_add3_u32 v34, v60, v34, s4
	v_bfe_u32 v35, v61, 16, 1
	v_pk_mul_f32 v[48:49], v[48:49], v[26:27]
	v_add_co_u32_e32 v32, vcc, s2, v32
	v_add3_u32 v35, v61, v35, s4
	v_add3_u32 v36, v62, v36, s4
	v_bfe_u32 v37, v63, 16, 1
	v_lshrrev_b32_e32 v34, 16, v34
	v_pk_fma_f32 v[100:101], v[48:49], v[52:53], v[46:47]
	v_pk_mul_f32 v[46:47], v[50:51], v[24:25]
	v_addc_co_u32_e32 v33, vcc, 0, v33, vcc
	v_add3_u32 v37, v63, v37, s4
	v_and_or_b32 v108, v35, s5, v34
	v_lshrrev_b32_e32 v34, 16, v36
	v_pk_fma_f32 v[102:103], v[46:47], v[54:55], v[44:45]
	v_and_or_b32 v109, v37, s5, v34
	global_load_dwordx4 v[44:47], v[32:33], off
	global_load_dwordx4 v[40:43], v[32:33], off offset:1024
	global_load_dwordx4 v[36:39], v[32:33], off offset:2048
	s_nop 0
	global_load_dwordx4 v[32:35], v[32:33], off offset:3072
	s_nop 0
	global_load_dwordx4 v[60:63], v64, s[30:31]
	global_load_dwordx4 v[56:59], v64, s[30:31] offset:1024
	global_load_dwordx4 v[52:55], v64, s[30:31] offset:2048
	global_load_dwordx4 v[48:51], v64, s[30:31] offset:3072
	v_bfe_u32 v70, v82, 16, 1
	v_add3_u32 v70, v82, v70, s4
	v_bfe_u32 v79, v83, 16, 1
	v_bfe_u32 v82, v80, 16, 1
	v_add3_u32 v79, v83, v79, s4
	v_add3_u32 v82, v80, v82, s4
	v_bfe_u32 v80, v81, 16, 1
	v_lshrrev_b32_e32 v70, 16, v70
	v_add3_u32 v81, v81, v80, s4
	v_and_or_b32 v80, v79, s5, v70
	v_lshrrev_b32_e32 v70, 16, v82
	v_and_or_b32 v81, v81, s5, v70
	v_bfe_u32 v70, v86, 16, 1
	global_store_dwordx2 v[68:69], v[80:81], off offset:512 sc0 sc1
	v_add3_u32 v70, v86, v70, s4
	v_bfe_u32 v79, v87, 16, 1
	v_bfe_u32 v80, v84, 16, 1
	v_add3_u32 v79, v87, v79, s4
	v_add3_u32 v81, v84, v80, s4
	v_bfe_u32 v80, v85, 16, 1
	v_lshrrev_b32_e32 v70, 16, v70
	v_add3_u32 v82, v85, v80, s4
	v_and_or_b32 v80, v79, s5, v70
	v_lshrrev_b32_e32 v70, 16, v81
	v_and_or_b32 v81, v82, s5, v70
	v_bfe_u32 v70, v90, 16, 1
	global_store_dwordx2 v[68:69], v[80:81], off offset:1024 sc0 sc1
	v_add3_u32 v70, v90, v70, s4
	v_bfe_u32 v79, v91, 16, 1
; #define LAS __attribute__((address_space(3)))
; __device__ __forceinline__ unsigned pk2(float lo, float hi) { return f2bf(lo) | (f2bf(hi) << 16); }
; __device__ __forceinline__ void store_u(bf16* urow, int lane, const f32x4 (&v)[8], float rstd, const LAS float* g, const LAS float* sh, const LAS float* sc) {
; #pragma unroll
;     for (int j = 0; j < 8; ++j) { const int ci = 256 * j + 4 * lane; const f32x4 g4 = *(const LAS f32x4*)(g + ci), s4 = *(const LAS f32x4*)(sc + ci), h4 = *(const LAS f32x4*)(sh + ci);
;         const f32x4 t = (v[j] * rstd * g4) * (1.0f + s4) + h4; v2u w; w.x = pk2(t[0], t[1]); w.y = pk2(t[2], t[3]); *(v2u*)(urow + ci) = w; }
; }
; __device__ __forceinline__ void pass_pre(const float* hlat, const float* hctx, const float* g, const float* mod, int sh_off, int sc_off, bf16* U, int nrows, int gw, int NGW, int lane, LAS float* lp, int tid) {
;     ...
;         for (int r = 0; r < 2; ++r) { if (r == 1 && !two) break; const int m = mr[r]; const LAS float* mv = lp + 4096 + 3 * (m < MLAT ? (m >> 13) : 2) * 2048;
;             const float rstd = rsqrtf(wave_sum(ss[r], lane) * (1.0f / DM) + EPS);
;             store_u(U + (size_t)m * DM, lane, v[r], rstd, lp + 2048, mv + 2048, mv + 4096); }
	v_bfe_u32 v80, v88, 16, 1
	v_add3_u32 v79, v91, v79, s4
	v_add3_u32 v81, v88, v80, s4
	v_bfe_u32 v80, v89, 16, 1
	v_lshrrev_b32_e32 v70, 16, v70
	v_add3_u32 v82, v89, v80, s4
	v_and_or_b32 v80, v79, s5, v70
	v_lshrrev_b32_e32 v70, 16, v81
	v_and_or_b32 v81, v82, s5, v70
	v_bfe_u32 v70, v94, 16, 1
	global_store_dwordx2 v[68:69], v[80:81], off offset:1536 sc0 sc1
	v_add3_u32 v70, v94, v70, s4
	v_bfe_u32 v79, v95, 16, 1
	v_bfe_u32 v80, v92, 16, 1
	v_add3_u32 v79, v95, v79, s4
	v_add3_u32 v81, v92, v80, s4
	v_bfe_u32 v80, v93, 16, 1
	v_lshrrev_b32_e32 v70, 16, v70
	v_add3_u32 v82, v93, v80, s4
	v_and_or_b32 v80, v79, s5, v70
	v_lshrrev_b32_e32 v70, 16, v81
	v_and_or_b32 v81, v82, s5, v70
	v_bfe_u32 v70, v98, 16, 1
	global_store_dwordx2 v[68:69], v[80:81], off offset:2048 sc0 sc1
	v_add3_u32 v70, v98, v70, s4
	v_bfe_u32 v79, v99, 16, 1
	v_bfe_u32 v80, v96, 16, 1
	v_add3_u32 v79, v99, v79, s4
	v_add3_u32 v81, v96, v80, s4
	v_bfe_u32 v80, v97, 16, 1
	v_lshrrev_b32_e32 v70, 16, v70
	v_add3_u32 v82, v97, v80, s4
	v_and_or_b32 v80, v79, s5, v70
	v_lshrrev_b32_e32 v70, 16, v81
	v_and_or_b32 v81, v82, s5, v70
	v_bfe_u32 v70, v102, 16, 1
	global_store_dwordx2 v[68:69], v[80:81], off offset:2560 sc0 sc1
	v_add3_u32 v70, v102, v70, s4
	v_bfe_u32 v79, v103, 16, 1
	v_bfe_u32 v80, v100, 16, 1
	v_add3_u32 v79, v103, v79, s4
	v_add3_u32 v81, v100, v80, s4
	v_bfe_u32 v80, v101, 16, 1
	v_lshrrev_b32_e32 v70, 16, v70
	v_add3_u32 v82, v101, v80, s4
	v_and_or_b32 v80, v79, s5, v70
	v_lshrrev_b32_e32 v70, 16, v81
	v_and_or_b32 v81, v82, s5, v70
	v_bfe_u32 v70, v106, 16, 1
	global_store_dwordx2 v[68:69], v[80:81], off offset:3072 sc0 sc1
	v_add3_u32 v70, v106, v70, s4
	v_bfe_u32 v79, v107, 16, 1
	v_bfe_u32 v80, v104, 16, 1
	v_add3_u32 v79, v107, v79, s4
	v_add3_u32 v81, v104, v80, s4
	v_bfe_u32 v80, v105, 16, 1
	v_lshrrev_b32_e32 v70, 16, v70
	v_add3_u32 v82, v105, v80, s4
	v_and_or_b32 v80, v79, s5, v70
	v_lshrrev_b32_e32 v70, 16, v81
	v_and_or_b32 v81, v82, s5, v70
	global_store_dwordx2 v[68:69], v[108:109], off sc0 sc1
	global_store_dwordx2 v[68:69], v[80:81], off offset:3584 sc0 sc1
	s_cbranch_scc1 .LBB0_173
	s_waitcnt vmcnt(11)
	v_mov_b32_e32 v82, v61
	s_waitcnt vmcnt(10)
	v_mov_b32_e32 v83, v57
	v_mov_b32_e32 v80, v60
	v_mov_b32_e32 v81, v56
	v_pk_mul_f32 v[82:83], v[82:83], v[82:83]
	v_mov_b32_e32 v84, v63
	v_mov_b32_e32 v85, v59
	v_pk_fma_f32 v[80:81], v[80:81], v[80:81], v[82:83]
	v_mov_b32_e32 v82, v62
	v_mov_b32_e32 v83, v58
	v_pk_mul_f32 v[84:85], v[84:85], v[84:85]
	v_mul_f32_e32 v70, v44, v44
	v_pk_fma_f32 v[82:83], v[82:83], v[82:83], v[84:85]
	s_waitcnt vmcnt(9)
	v_pk_mul_f32 v[84:85], v[52:53], v[52:53]
	v_pk_add_f32 v[80:81], v[80:81], v[82:83]
	v_pk_mul_f32 v[82:83], v[54:55], v[54:55]
	v_mul_f32_e32 v79, v45, v45
	v_pk_mov_b32 v[86:87], v[84:85], v[82:83] op_sel:[1,0]
	v_mov_b32_e32 v85, v83
	v_pk_add_f32 v[82:83], v[86:87], v[84:85]
	v_pk_add_f32 v[80:81], v[80:81], v[80:81] op_sel:[0,1] op_sel_hi:[1,0]
	v_pk_add_f32 v[82:83], v[82:83], v[82:83] op_sel:[0,1] op_sel_hi:[1,0]
	v_mov_b32_e32 v81, v70
	v_mov_b32_e32 v83, v79
	s_waitcnt vmcnt(8)
	v_mul_f32_e32 v70, v49, v49
	v_mul_f32_e32 v84, v46, v46
	v_pk_add_f32 v[80:81], v[80:81], v[82:83]
	v_pk_fma_f32 v[82:83], v[48:49], v[48:49], v[70:71] op_sel_hi:[1,1,0]
	v_mul_f32_e32 v70, v51, v51
	v_mul_f32_e32 v86, v47, v47
	v_mov_b32_e32 v83, v84
	v_pk_fma_f32 v[84:85], v[50:51], v[50:51], v[70:71] op_sel_hi:[1,1,0]
	v_mul_f32_e32 v70, v32, v32
	v_mov_b32_e32 v85, v86
	v_pk_add_f32 v[82:83], v[82:83], v[84:85]
	v_pk_mul_f32 v[84:85], v[40:41], v[40:41]
	v_pk_add_f32 v[80:81], v[80:81], v[82:83]
	v_pk_mul_f32 v[82:83], v[42:43], v[42:43]
	v_mul_f32_e32 v79, v33, v33
	v_pk_mov_b32 v[86:87], v[84:85], v[82:83] op_sel:[1,0]
	v_mov_b32_e32 v85, v83
	v_pk_add_f32 v[82:83], v[86:87], v[84:85]
	v_pk_add_f32 v[80:81], v[80:81], v[80:81] op_sel:[0,1] op_sel_hi:[1,0]
	v_pk_add_f32 v[82:83], v[82:83], v[82:83] op_sel:[0,1] op_sel_hi:[1,0]
	v_mov_b32_e32 v81, v70
	v_mov_b32_e32 v83, v79
	v_mul_f32_e32 v70, v37, v37
	v_mul_f32_e32 v84, v34, v34
	v_pk_add_f32 v[80:81], v[80:81], v[82:83]
	v_pk_fma_f32 v[82:83], v[36:37], v[36:37], v[70:71] op_sel_hi:[1,1,0]
	v_mul_f32_e32 v70, v39, v39
	v_mul_f32_e32 v86, v35, v35
	v_mov_b32_e32 v83, v84
	v_pk_fma_f32 v[84:85], v[38:39], v[38:39], v[70:71] op_sel_hi:[1,1,0]
	s_min_i32 s6, s28, 0x4000
	v_mov_b32_e32 v85, v86
	v_pk_add_f32 v[82:83], v[82:83], v[84:85]
	s_lshr_b32 s6, s6, 13
	v_pk_add_f32 v[80:81], v[80:81], v[82:83]
	s_mul_i32 s8, s6, 0x6000
	v_add_f32_e32 v70, v80, v81
	ds_bpermute_b32 v79, v71, v70
	s_ashr_i32 s29, s28, 31
	s_lshl_b64 s[6:7], s[28:29], 12
	s_waitcnt lgkmcnt(0)
	v_add_f32_e32 v70, v70, v79
	ds_bpermute_b32 v79, v72, v70
	s_waitcnt lgkmcnt(0)
	v_add_f32_e32 v70, v70, v79
	ds_bpermute_b32 v79, v73, v70
	s_waitcnt lgkmcnt(0)
	v_add_f32_e32 v70, v70, v79
	ds_bpermute_b32 v79, v74, v70
	s_waitcnt lgkmcnt(0)
	v_add_f32_e32 v70, v70, v79
	ds_bpermute_b32 v79, v75, v70
	s_waitcnt lgkmcnt(0)
	v_add_f32_e32 v70, v70, v79
	ds_bpermute_b32 v79, v76, v70
	s_waitcnt lgkmcnt(0)
	v_add_f32_e32 v70, v70, v79
	v_fmamk_f32 v70, v70, 0x3a000000, v78
	v_mul_f32_e32 v79, 0x4b800000, v70
	v_cmp_gt_f32_e32 vcc, s3, v70
	s_nop 1
	v_cndmask_b32_e32 v70, v70, v79, vcc
	v_rsq_f32_e32 v70, v70
	s_nop 0
	v_mul_f32_e32 v79, 0x45800000, v70
	v_cndmask_b32_e32 v70, v70, v79, vcc
	v_add_u32_e32 v79, s8, v77
	ds_read_b128 v[80:83], v79 offset:32768
	ds_read_b128 v[84:87], v79 offset:24576
	v_pk_mul_f32 v[60:61], v[60:61], v[70:71] op_sel_hi:[1,0]
	v_pk_mul_f32 v[62:63], v[62:63], v[70:71] op_sel_hi:[1,0]
	v_pk_mul_f32 v[60:61], v[0:1], v[60:61]
	s_waitcnt lgkmcnt(1)
; #define LAS __attribute__((address_space(3)))
; __device__ __forceinline__ unsigned pk2(float lo, float hi) { return f2bf(lo) | (f2bf(hi) << 16); }
; __device__ __forceinline__ void store_u(bf16* urow, int lane, const f32x4 (&v)[8], float rstd, const LAS float* g, const LAS float* sh, const LAS float* sc) {
; #pragma unroll
;     for (int j = 0; j < 8; ++j) { const int ci = 256 * j + 4 * lane; const f32x4 g4 = *(const LAS f32x4*)(g + ci), s4 = *(const LAS f32x4*)(sc + ci), h4 = *(const LAS f32x4*)(sh + ci);
;         const f32x4 t = (v[j] * rstd * g4) * (1.0f + s4) + h4; v2u w; w.x = pk2(t[0], t[1]); w.y = pk2(t[2], t[3]); *(v2u*)(urow + ci) = w; }
; }
	v_pk_add_f32 v[94:95], v[80:81], 1.0 op_sel_hi:[1,0]
	v_pk_mul_f32 v[62:63], v[2:3], v[62:63]
	s_waitcnt lgkmcnt(0)
	v_pk_fma_f32 v[60:61], v[94:95], v[60:61], v[84:85]
	v_pk_add_f32 v[92:93], v[82:83], 1.0 op_sel_hi:[1,0]
	v_bfe_u32 v84, v60, 16, 1
	v_add3_u32 v60, v60, v84, s4
	v_bfe_u32 v84, v61, 16, 1
	ds_read_b128 v[88:91], v79 offset:33792
	ds_read_b128 v[80:83], v79 offset:25600
	v_pk_fma_f32 v[62:63], v[92:93], v[62:63], v[86:87]
	v_lshrrev_b32_e32 v60, 16, v60
	v_add3_u32 v61, v61, v84, s4
	v_and_or_b32 v84, v61, s5, v60
	v_bfe_u32 v60, v62, 16, 1
	v_add3_u32 v60, v62, v60, s4
	v_bfe_u32 v61, v63, 16, 1
	v_lshrrev_b32_e32 v60, 16, v60
	v_add3_u32 v61, v63, v61, s4
	v_and_or_b32 v85, v61, s5, v60
	v_lshl_add_u64 v[60:61], v[66:67], 0, s[6:7]
	v_pk_mul_f32 v[56:57], v[56:57], v[70:71] op_sel_hi:[1,0]
	global_store_dwordx2 v[60:61], v[84:85], off sc0 sc1
	v_pk_mul_f32 v[58:59], v[58:59], v[70:71] op_sel_hi:[1,0]
	v_pk_mul_f32 v[56:57], v[4:5], v[56:57]
	s_waitcnt lgkmcnt(1)
	v_pk_add_f32 v[84:85], v[88:89], 1.0 op_sel_hi:[1,0]
	v_pk_mul_f32 v[58:59], v[6:7], v[58:59]
	v_pk_add_f32 v[62:63], v[90:91], 1.0 op_sel_hi:[1,0]
	s_waitcnt lgkmcnt(0)
	v_pk_fma_f32 v[56:57], v[84:85], v[56:57], v[80:81]
	v_pk_fma_f32 v[58:59], v[62:63], v[58:59], v[82:83]
	v_bfe_u32 v62, v56, 16, 1
	v_add3_u32 v56, v56, v62, s4
	v_bfe_u32 v62, v57, 16, 1
	v_lshrrev_b32_e32 v56, 16, v56
	v_add3_u32 v57, v57, v62, s4
	v_and_or_b32 v56, v57, s5, v56
	v_bfe_u32 v57, v58, 16, 1
	v_add3_u32 v57, v58, v57, s4
	v_bfe_u32 v58, v59, 16, 1
	v_lshrrev_b32_e32 v57, 16, v57
	v_add3_u32 v58, v59, v58, s4
	v_and_or_b32 v57, v58, s5, v57
	global_store_dwordx2 v[60:61], v[56:57], off offset:512 sc0 sc1
	ds_read_b128 v[56:59], v79 offset:34816
	ds_read_b128 v[80:83], v79 offset:26624
	v_pk_mul_f32 v[54:55], v[54:55], v[70:71] op_sel_hi:[1,0]
	v_pk_mul_f32 v[52:53], v[52:53], v[70:71] op_sel_hi:[1,0]
	v_pk_mul_f32 v[84:85], v[10:11], v[54:55]
	v_pk_mul_f32 v[62:63], v[8:9], v[52:53]
	ds_read_b128 v[52:55], v79 offset:35840
	s_waitcnt lgkmcnt(2)
	v_pk_add_f32 v[86:87], v[58:59], 1.0 op_sel_hi:[1,0]
	v_pk_add_f32 v[88:89], v[56:57], 1.0 op_sel_hi:[1,0]
	ds_read_b128 v[56:59], v79 offset:27648
	v_pk_mul_f32 v[48:49], v[48:49], v[70:71] op_sel_hi:[1,0]
	s_waitcnt lgkmcnt(1)
	v_pk_add_f32 v[52:53], v[52:53], 1.0 op_sel_hi:[1,0]
	v_pk_mul_f32 v[48:49], v[12:13], v[48:49]
	v_pk_fma_f32 v[62:63], v[88:89], v[62:63], v[80:81]
	s_waitcnt lgkmcnt(0)
	v_pk_fma_f32 v[48:49], v[52:53], v[48:49], v[56:57]
	v_bfe_u32 v80, v62, 16, 1
	v_pk_mul_f32 v[50:51], v[50:51], v[70:71] op_sel_hi:[1,0]
	v_bfe_u32 v52, v48, 16, 1
	v_add3_u32 v62, v62, v80, s4
	v_bfe_u32 v80, v63, 16, 1
	v_pk_mul_f32 v[50:51], v[14:15], v[50:51]
	v_pk_add_f32 v[54:55], v[54:55], 1.0 op_sel_hi:[1,0]
	v_add3_u32 v48, v48, v52, s4
	v_bfe_u32 v52, v49, 16, 1
	v_pk_fma_f32 v[82:83], v[86:87], v[84:85], v[82:83]
	v_lshrrev_b32_e32 v62, 16, v62
	v_add3_u32 v63, v63, v80, s4
	v_pk_fma_f32 v[50:51], v[54:55], v[50:51], v[58:59]
	v_lshrrev_b32_e32 v48, 16, v48
	v_add3_u32 v49, v49, v52, s4
	v_and_or_b32 v62, v63, s5, v62
	v_bfe_u32 v63, v82, 16, 1
	v_and_or_b32 v48, v49, s5, v48
	v_bfe_u32 v49, v50, 16, 1
	v_add3_u32 v63, v82, v63, s4
	v_bfe_u32 v80, v83, 16, 1
	v_add3_u32 v49, v50, v49, s4
	v_bfe_u32 v50, v51, 16, 1
	v_lshrrev_b32_e32 v63, 16, v63
	v_add3_u32 v80, v83, v80, s4
	v_lshrrev_b32_e32 v49, 16, v49
	v_add3_u32 v50, v51, v50, s4
	v_and_or_b32 v63, v80, s5, v63
	v_and_or_b32 v49, v50, s5, v49
	global_store_dwordx2 v[60:61], v[62:63], off offset:1024 sc0 sc1
	global_store_dwordx2 v[60:61], v[48:49], off offset:1536 sc0 sc1
	ds_read_b128 v[48:51], v79 offset:36864
	ds_read_b128 v[52:55], v79 offset:28672
	v_pk_mul_f32 v[46:47], v[46:47], v[70:71] op_sel_hi:[1,0]
	v_pk_mul_f32 v[44:45], v[44:45], v[70:71] op_sel_hi:[1,0]
	v_pk_mul_f32 v[58:59], v[18:19], v[46:47]
	v_pk_mul_f32 v[56:57], v[16:17], v[44:45]
	ds_read_b128 v[44:47], v79 offset:37888
	s_waitcnt lgkmcnt(2)
; #define LAS __attribute__((address_space(3)))
; __device__ __forceinline__ unsigned pk2(float lo, float hi) { return f2bf(lo) | (f2bf(hi) << 16); }
; __device__ __forceinline__ void store_u(bf16* urow, int lane, const f32x4 (&v)[8], float rstd, const LAS float* g, const LAS float* sh, const LAS float* sc) {
; #pragma unroll
;     for (int j = 0; j < 8; ++j) { const int ci = 256 * j + 4 * lane; const f32x4 g4 = *(const LAS f32x4*)(g + ci), s4 = *(const LAS f32x4*)(sc + ci), h4 = *(const LAS f32x4*)(sh + ci);
;         const f32x4 t = (v[j] * rstd * g4) * (1.0f + s4) + h4; v2u w; w.x = pk2(t[0], t[1]); w.y = pk2(t[2], t[3]); *(v2u*)(urow + ci) = w; }
; }
	v_pk_add_f32 v[62:63], v[50:51], 1.0 op_sel_hi:[1,0]
	v_pk_add_f32 v[80:81], v[48:49], 1.0 op_sel_hi:[1,0]
	ds_read_b128 v[48:51], v79 offset:29696
	v_pk_mul_f32 v[40:41], v[40:41], v[70:71] op_sel_hi:[1,0]
	s_waitcnt lgkmcnt(1)
	v_pk_add_f32 v[44:45], v[44:45], 1.0 op_sel_hi:[1,0]
	v_pk_mul_f32 v[40:41], v[20:21], v[40:41]
	v_pk_fma_f32 v[52:53], v[56:57], v[80:81], v[52:53]
	s_waitcnt lgkmcnt(0)
	v_pk_fma_f32 v[40:41], v[40:41], v[44:45], v[48:49]
	v_bfe_u32 v56, v52, 16, 1
	v_pk_mul_f32 v[42:43], v[42:43], v[70:71] op_sel_hi:[1,0]
	v_bfe_u32 v44, v40, 16, 1
	v_add3_u32 v52, v52, v56, s4
	v_bfe_u32 v56, v53, 16, 1
	v_pk_mul_f32 v[42:43], v[22:23], v[42:43]
	v_pk_add_f32 v[46:47], v[46:47], 1.0 op_sel_hi:[1,0]
	v_add3_u32 v40, v40, v44, s4
	v_bfe_u32 v44, v41, 16, 1
	v_pk_fma_f32 v[54:55], v[58:59], v[62:63], v[54:55]
	v_lshrrev_b32_e32 v52, 16, v52
	v_add3_u32 v53, v53, v56, s4
	v_pk_fma_f32 v[42:43], v[42:43], v[46:47], v[50:51]
	v_lshrrev_b32_e32 v40, 16, v40
	v_add3_u32 v41, v41, v44, s4
	v_and_or_b32 v52, v53, s5, v52
	v_bfe_u32 v53, v54, 16, 1
	v_and_or_b32 v40, v41, s5, v40
	v_bfe_u32 v41, v42, 16, 1
	v_add3_u32 v53, v54, v53, s4
	v_bfe_u32 v54, v55, 16, 1
	v_add3_u32 v41, v42, v41, s4
	v_bfe_u32 v42, v43, 16, 1
	v_lshrrev_b32_e32 v53, 16, v53
	v_add3_u32 v54, v55, v54, s4
	v_lshrrev_b32_e32 v41, 16, v41
	v_add3_u32 v42, v43, v42, s4
	v_and_or_b32 v53, v54, s5, v53
	v_and_or_b32 v41, v42, s5, v41
	global_store_dwordx2 v[60:61], v[52:53], off offset:2048 sc0 sc1
	global_store_dwordx2 v[60:61], v[40:41], off offset:2560 sc0 sc1
	ds_read_b128 v[40:43], v79 offset:38912
	ds_read_b128 v[44:47], v79 offset:30720
	v_pk_mul_f32 v[38:39], v[38:39], v[70:71] op_sel_hi:[1,0]
	v_pk_mul_f32 v[36:37], v[36:37], v[70:71] op_sel_hi:[1,0]
	v_pk_mul_f32 v[50:51], v[26:27], v[38:39]
	v_pk_mul_f32 v[48:49], v[24:25], v[36:37]
	ds_read_b128 v[36:39], v79 offset:39936
	s_waitcnt lgkmcnt(2)
	v_pk_add_f32 v[52:53], v[42:43], 1.0 op_sel_hi:[1,0]
	v_pk_add_f32 v[54:55], v[40:41], 1.0 op_sel_hi:[1,0]
	ds_read_b128 v[40:43], v79 offset:31744
	v_pk_mul_f32 v[32:33], v[32:33], v[70:71] op_sel_hi:[1,0]
	s_waitcnt lgkmcnt(1)
	v_pk_add_f32 v[36:37], v[36:37], 1.0 op_sel_hi:[1,0]
	v_pk_mul_f32 v[32:33], v[28:29], v[32:33]
	v_pk_fma_f32 v[44:45], v[48:49], v[54:55], v[44:45]
	s_waitcnt lgkmcnt(0)
	v_pk_fma_f32 v[32:33], v[32:33], v[36:37], v[40:41]
	v_bfe_u32 v48, v44, 16, 1
	v_pk_mul_f32 v[34:35], v[34:35], v[70:71] op_sel_hi:[1,0]
	v_bfe_u32 v36, v32, 16, 1
	v_add3_u32 v44, v44, v48, s4
	v_bfe_u32 v48, v45, 16, 1
	v_pk_mul_f32 v[34:35], v[30:31], v[34:35]
	v_pk_add_f32 v[38:39], v[38:39], 1.0 op_sel_hi:[1,0]
	v_add3_u32 v32, v32, v36, s4
	v_bfe_u32 v36, v33, 16, 1
	v_pk_fma_f32 v[46:47], v[50:51], v[52:53], v[46:47]
	v_lshrrev_b32_e32 v44, 16, v44
	v_add3_u32 v45, v45, v48, s4
	v_pk_fma_f32 v[34:35], v[34:35], v[38:39], v[42:43]
	v_lshrrev_b32_e32 v32, 16, v32
	v_add3_u32 v33, v33, v36, s4
	v_and_or_b32 v44, v45, s5, v44
	v_bfe_u32 v45, v46, 16, 1
	v_and_or_b32 v32, v33, s5, v32
	v_bfe_u32 v33, v34, 16, 1
	v_add3_u32 v45, v46, v45, s4
	v_bfe_u32 v46, v47, 16, 1
	v_add3_u32 v33, v34, v33, s4
	v_bfe_u32 v34, v35, 16, 1
	v_lshrrev_b32_e32 v45, 16, v45
	v_add3_u32 v46, v47, v46, s4
	v_lshrrev_b32_e32 v33, 16, v33
	v_add3_u32 v34, v35, v34, s4
	v_and_or_b32 v45, v46, s5, v45
	v_and_or_b32 v33, v34, s5, v33
	global_store_dwordx2 v[60:61], v[44:45], off offset:3072 sc0 sc1
	global_store_dwordx2 v[60:61], v[32:33], off offset:3584 sc0 sc1
	s_branch .LBB0_173

; __device__ __forceinline__ unsigned pk2(float lo, float hi) { return f2bf(lo) | (f2bf(hi) << 16); }
; template <bool ROPE> __device__ __forceinline__ void heads8(bf16* hbase, bool active, const float (&ga)[8], const float (&gb)[8], const float (&cs)[8], const float (&sn)[8], int lane) {
;     const int g = lane >> 3, sub = lane & 7, ca = 8 * (sub >> 2) + (sub & 3);
;     bf16* pa = hbase + g * 128 + ca * 8; bf16* pb = pa + 32;
;     v4u ra = {0u, 0u, 0u, 0u}, rb = ra; if (active) { ra = *(const v4u*)pa; rb = *(const v4u*)pb; }
;     float x[8], y[8]; unpack8(ra, x); unpack8(rb, y);
;     float ss = 0.f;
; #pragma unroll
;     for (int i = 0; i < 8; ++i) ss += x[i] * x[i] + y[i] * y[i];
; #pragma unroll
;     for (int o = 1; o < 8; o <<= 1) ss += __int_as_float(__builtin_amdgcn_ds_bpermute((lane ^ o) << 2, __float_as_int(ss)));
;     const float rstd = rsqrtf(ss * (1.0f / 128.0f) + EPS);
; #pragma unroll
;     for (int i = 0; i < 8; ++i) { float a = x[i] * rstd * ga[i], b = y[i] * rstd * gb[i];
;         if (ROPE) { const float na = a * cs[i] - b * sn[i], nb = b * cs[i] + a * sn[i]; a = na; b = nb; }
;         x[i] = a; y[i] = b; }
;     if (active) { v4u wa, wb; wa.x = pk2(x[0], x[1]); wa.y = pk2(x[2], x[3]); wa.z = pk2(x[4], x[5]); wa.w = pk2(x[6], x[7]); wb.x = pk2(y[0], y[1]); wb.y = pk2(y[2], y[3]); wb.z = pk2(y[4], y[5]); wb.w = pk2(y[6], y[7]);
;         *(v4u*)pa = wa; *(v4u*)pb = wb; }
; }
; __device__ __forceinline__ void prep_cd(bf16* P, const float* cqn, const float* ckn, const float* dqn, const float* dkn, int gw, int NGW, int lane) {
;     ...
;         heads8<false>(row + 2560, true, gda, gdb, cs, sn, lane);
.LBB0_318:
	global_load_dwordx4 v[30:33], v[26:27], off
	global_load_dwordx4 v[34:37], v[26:27], off offset:64
	s_cmpk_gt_i32 s2, 0x3fff
	s_mov_b64 s[16:17], -1
	s_waitcnt vmcnt(1)
	v_lshlrev_b32_e32 v46, 16, v30
	s_waitcnt vmcnt(0)
	v_lshlrev_b32_e32 v42, 16, v34
	v_and_b32_e32 v34, 0xffff0000, v34
	v_and_b32_e32 v30, 0xffff0000, v30
	v_mov_b32_e32 v48, v42
	v_mov_b32_e32 v49, v34
	v_lshlrev_b32_e32 v43, 16, v35
	v_and_b32_e32 v35, 0xffff0000, v35
	v_pk_mul_f32 v[48:49], v[48:49], v[48:49]
	s_waitcnt lgkmcnt(0)
	v_mov_b32_e32 v62, v46
	v_mov_b32_e32 v63, v30
	v_lshlrev_b32_e32 v47, 16, v31
	v_and_b32_e32 v31, 0xffff0000, v31
	v_pk_fma_f32 v[48:49], v[62:63], v[62:63], v[48:49]
	v_mov_b32_e32 v62, v35
	v_mov_b32_e32 v63, v43
	v_lshlrev_b32_e32 v44, 16, v36
	v_and_b32_e32 v36, 0xffff0000, v36
	v_pk_mul_f32 v[62:63], v[62:63], v[62:63]
	v_mov_b32_e32 v64, v31
	v_mov_b32_e32 v65, v47
	v_pk_fma_f32 v[62:63], v[64:65], v[64:65], v[62:63]
	v_lshlrev_b32_e32 v64, 16, v32
	v_and_b32_e32 v32, 0xffff0000, v32
	v_mov_b32_e32 v66, v36
	v_mov_b32_e32 v67, v44
	v_add_f32_e32 v48, v48, v49
	v_lshlrev_b32_e32 v45, 16, v37
	v_and_b32_e32 v37, 0xffff0000, v37
	v_pk_mul_f32 v[66:67], v[66:67], v[66:67]
	v_mov_b32_e32 v68, v32
	v_mov_b32_e32 v69, v64
	v_add_f32_e32 v48, v63, v48
	v_lshlrev_b32_e32 v65, 16, v33
	v_and_b32_e32 v33, 0xffff0000, v33
	v_pk_fma_f32 v[66:67], v[68:69], v[68:69], v[66:67]
	v_mov_b32_e32 v68, v37
	v_mov_b32_e32 v69, v45
	v_add_f32_e32 v48, v62, v48
	v_pk_mul_f32 v[68:69], v[68:69], v[68:69]
	v_mov_b32_e32 v70, v33
	v_mov_b32_e32 v71, v65
	v_add_f32_e32 v48, v67, v48
	v_pk_fma_f32 v[68:69], v[70:71], v[70:71], v[68:69]
	v_add_f32_e32 v48, v66, v48
	v_add_f32_e32 v48, v69, v48
	v_add_f32_e32 v48, v68, v48
	ds_bpermute_b32 v49, v50, v48
	s_waitcnt lgkmcnt(0)
	v_add_f32_e32 v48, v48, v49
	ds_bpermute_b32 v49, v51, v48
	s_waitcnt lgkmcnt(0)
	v_add_f32_e32 v48, v48, v49
	ds_bpermute_b32 v49, v52, v48
	s_waitcnt lgkmcnt(0)
	v_add_f32_e32 v48, v48, v49
	v_fmamk_f32 v48, v48, 0x3c000000, v196
	v_cmp_gt_f32_e32 vcc, s78, v48
	v_mul_f32_e32 v49, 0x4b800000, v48
	s_nop 0
	v_cndmask_b32_e32 v48, v48, v49, vcc
	v_rsq_f32_e32 v48, v48
	s_nop 0
	v_mul_f32_e32 v49, 0x45800000, v48
	v_cndmask_b32_e32 v48, v48, v49, vcc
	v_pk_mul_f32 v[30:31], v[48:49], v[30:31] op_sel_hi:[0,1]
	v_pk_mul_f32 v[32:33], v[48:49], v[32:33] op_sel_hi:[0,1]
	v_pk_mul_f32 v[46:47], v[48:49], v[46:47] op_sel_hi:[0,1]
	v_pk_mul_f32 v[30:31], v[18:19], v[30:31]
	v_pk_mul_f32 v[62:63], v[48:49], v[64:65] op_sel_hi:[0,1]
	v_pk_mul_f32 v[32:33], v[22:23], v[32:33]
	v_pk_mul_f32 v[42:43], v[48:49], v[42:43] op_sel_hi:[0,1]
	v_pk_mul_f32 v[34:35], v[48:49], v[34:35] op_sel_hi:[0,1]
	v_pk_mul_f32 v[44:45], v[48:49], v[44:45] op_sel_hi:[0,1]
	v_pk_mul_f32 v[36:37], v[48:49], v[36:37] op_sel_hi:[0,1]
	v_pk_mul_f32 v[46:47], v[24:25], v[46:47]
	v_pk_mul_f32 v[62:63], v[28:29], v[62:63]
	v_bfe_u32 v48, v33, 16, 1
	v_bfe_u32 v49, v32, 16, 1
	v_bfe_u32 v61, v31, 16, 1
	v_bfe_u32 v64, v30, 16, 1
	v_add3_u32 v30, v30, v64, s79
	v_add3_u32 v31, v31, v61, s79
	v_add3_u32 v32, v32, v49, s79
	v_add3_u32 v33, v33, v48, s79
	v_bfe_u32 v48, v46, 16, 1
	v_bfe_u32 v49, v47, 16, 1
	v_bfe_u32 v61, v62, 16, 1
	v_bfe_u32 v64, v63, 16, 1
	v_add3_u32 v63, v63, v64, s79
	v_add3_u32 v61, v62, v61, s79
	v_add3_u32 v47, v47, v49, s79
	v_add3_u32 v46, v46, v48, s79
	v_pk_mul_f32 v[34:35], v[10:11], v[34:35]
	v_pk_mul_f32 v[36:37], v[14:15], v[36:37]
	v_lshrrev_b32_e32 v46, 16, v46
	v_lshrrev_b32_e32 v47, 16, v47
	v_lshrrev_b32_e32 v48, 16, v61
	v_lshrrev_b32_e32 v49, 16, v63
	v_pk_mul_f32 v[42:43], v[16:17], v[42:43]
	v_pk_mul_f32 v[44:45], v[20:21], v[44:45]
	v_and_or_b32 v33, v33, s75, v49
	v_and_or_b32 v32, v32, s75, v48
	v_and_or_b32 v31, v31, s75, v47
	v_and_or_b32 v30, v30, s75, v46
	v_bfe_u32 v46, v37, 16, 1
	v_bfe_u32 v47, v36, 16, 1
	v_bfe_u32 v48, v35, 16, 1
	v_bfe_u32 v49, v34, 16, 1
	v_add3_u32 v34, v34, v49, s79
	v_add3_u32 v35, v35, v48, s79
	v_add3_u32 v36, v36, v47, s79
	v_add3_u32 v37, v37, v46, s79
	v_bfe_u32 v46, v42, 16, 1
	v_bfe_u32 v47, v43, 16, 1
	v_bfe_u32 v48, v44, 16, 1
	v_bfe_u32 v49, v45, 16, 1
	v_add3_u32 v45, v45, v49, s79
	v_add3_u32 v44, v44, v48, s79
	v_add3_u32 v43, v43, v47, s79
	v_add3_u32 v42, v42, v46, s79
	v_lshrrev_b32_e32 v42, 16, v42
	v_lshrrev_b32_e32 v43, 16, v43
	v_lshrrev_b32_e32 v44, 16, v44
	v_lshrrev_b32_e32 v45, 16, v45
	v_and_or_b32 v37, v37, s75, v45
	v_and_or_b32 v36, v36, s75, v44
	v_and_or_b32 v35, v35, s75, v43
	v_and_or_b32 v34, v34, s75, v42
	global_store_dwordx4 v[26:27], v[30:33], off sc0 sc1
	global_store_dwordx4 v[26:27], v[34:37], off offset:64 sc0 sc1
	s_cbranch_scc0 .LBB0_324
	v_mov_b32_e32 v30, 0
	v_mov_b32_e32 v31, 0
	v_mov_b32_e32 v32, 0
	v_mov_b32_e32 v33, 0
	v_mov_b32_e32 v34, 0
	v_mov_b32_e32 v35, 0
	v_mov_b32_e32 v36, 0
	v_mov_b32_e32 v37, 0
	s_and_saveexec_b64 s[16:17], s[38:39]
	s_cbranch_execz .LBB0_321
	global_load_dwordx4 v[34:37], v[26:27], off offset:-3072
	global_load_dwordx4 v[30:33], v[26:27], off offset:-3008
; __device__ __forceinline__ unsigned pk2(float lo, float hi) { return f2bf(lo) | (f2bf(hi) << 16); }
; template <bool ROPE> __device__ __forceinline__ void heads8(bf16* hbase, bool active, const float (&ga)[8], const float (&gb)[8], const float (&cs)[8], const float (&sn)[8], int lane) {
;     const int g = lane >> 3, sub = lane & 7, ca = 8 * (sub >> 2) + (sub & 3);
;     bf16* pa = hbase + g * 128 + ca * 8; bf16* pb = pa + 32;
;     v4u ra = {0u, 0u, 0u, 0u}, rb = ra; if (active) { ra = *(const v4u*)pa; rb = *(const v4u*)pb; }
;     float x[8], y[8]; unpack8(ra, x); unpack8(rb, y);
;     float ss = 0.f;
; #pragma unroll
;     for (int i = 0; i < 8; ++i) ss += x[i] * x[i] + y[i] * y[i];
; #pragma unroll
;     for (int o = 1; o < 8; o <<= 1) ss += __int_as_float(__builtin_amdgcn_ds_bpermute((lane ^ o) << 2, __float_as_int(ss)));
;     const float rstd = rsqrtf(ss * (1.0f / 128.0f) + EPS);
; #pragma unroll
;     for (int i = 0; i < 8; ++i) { float a = x[i] * rstd * ga[i], b = y[i] * rstd * gb[i];
;         if (ROPE) { const float na = a * cs[i] - b * sn[i], nb = b * cs[i] + a * sn[i]; a = na; b = nb; }
;         x[i] = a; y[i] = b; }
;     if (active) { v4u wa, wb; wa.x = pk2(x[0], x[1]); wa.y = pk2(x[2], x[3]); wa.z = pk2(x[4], x[5]); wa.w = pk2(x[6], x[7]); wb.x = pk2(y[0], y[1]); wb.y = pk2(y[2], y[3]); wb.z = pk2(y[4], y[5]); wb.w = pk2(y[6], y[7]);
;         *(v4u*)pa = wa; *(v4u*)pb = wb; }
; }
; __device__ __forceinline__ void prep_cd(bf16* P, const float* cqn, const float* ckn, const float* dqn, const float* dkn, int gw, int NGW, int lane) {
;     ...
;         else heads8<false>(row + 1024, lane < 16, gca, gcb, cs, sn, lane);
.LBB0_321:
	s_or_b64 exec, exec, s[16:17]
	s_waitcnt vmcnt(1)
	v_lshlrev_b32_e32 v45, 16, v35
	v_lshlrev_b32_e32 v44, 16, v34
	v_and_b32_e32 v43, 0xffff0000, v35
	v_and_b32_e32 v42, 0xffff0000, v34
	v_pk_mul_f32 v[46:47], v[44:45], v[44:45]
	v_pk_mul_f32 v[48:49], v[42:43], v[42:43]
	s_waitcnt vmcnt(0)
	v_lshlrev_b32_e32 v35, 16, v31
	v_lshlrev_b32_e32 v34, 16, v30
	v_and_b32_e32 v31, 0xffff0000, v31
	v_and_b32_e32 v30, 0xffff0000, v30
	v_pk_fma_f32 v[62:63], v[34:35], v[34:35], v[46:47]
	v_pk_fma_f32 v[64:65], v[30:31], v[30:31], v[48:49]
	v_lshlrev_b32_e32 v49, 16, v37
	v_lshlrev_b32_e32 v48, 16, v36
	v_add_f32_e32 v61, v62, v64
	v_and_b32_e32 v47, 0xffff0000, v37
	v_and_b32_e32 v46, 0xffff0000, v36
	v_pk_mul_f32 v[66:67], v[48:49], v[48:49]
	v_lshlrev_b32_e32 v37, 16, v33
	v_lshlrev_b32_e32 v36, 16, v32
	v_add_f32_e32 v61, v63, v61
	v_pk_mul_f32 v[68:69], v[46:47], v[46:47]
	v_and_b32_e32 v33, 0xffff0000, v33
	v_and_b32_e32 v32, 0xffff0000, v32
	v_pk_fma_f32 v[66:67], v[36:37], v[36:37], v[66:67]
	v_add_f32_e32 v61, v65, v61
	v_pk_fma_f32 v[68:69], v[32:33], v[32:33], v[68:69]
	v_add_f32_e32 v61, v66, v61
	v_add_f32_e32 v61, v68, v61
	v_add_f32_e32 v61, v67, v61
	v_add_f32_e32 v61, v69, v61
	ds_bpermute_b32 v62, v50, v61
	s_waitcnt lgkmcnt(0)
	v_add_f32_e32 v61, v61, v62
	ds_bpermute_b32 v62, v51, v61
	s_waitcnt lgkmcnt(0)
	v_add_f32_e32 v61, v61, v62
	ds_bpermute_b32 v62, v52, v61
	s_and_saveexec_b64 s[16:17], s[38:39]
	s_cbranch_execz .LBB0_323
	s_waitcnt lgkmcnt(0)
	v_add_f32_e32 v61, v61, v62
	v_fmamk_f32 v61, v61, 0x3c000000, v196
	v_mul_f32_e32 v62, 0x4b800000, v61
	v_cmp_gt_f32_e32 vcc, s78, v61
	s_nop 1
	v_cndmask_b32_e32 v61, v61, v62, vcc
	v_rsq_f32_e32 v61, v61
	s_nop 0
	v_mul_f32_e32 v62, 0x45800000, v61
	v_cndmask_b32_e32 v62, v61, v62, vcc
	v_pk_mul_f32 v[46:47], v[62:63], v[46:47] op_sel_hi:[0,1]
	v_pk_mul_f32 v[44:45], v[62:63], v[44:45] op_sel_hi:[0,1]
	v_pk_mul_f32 v[46:47], v[6:7], v[46:47]
	v_pk_mul_f32 v[42:43], v[62:63], v[42:43] op_sel_hi:[0,1]
	v_pk_mul_f32 v[44:45], v[4:5], v[44:45]
	v_pk_mul_f32 v[48:49], v[62:63], v[48:49] op_sel_hi:[0,1]
	v_bfe_u32 v63, v46, 16, 1
	v_pk_mul_f32 v[42:43], v[40:41], v[42:43]
	v_add3_u32 v46, v46, v63, s79
	v_bfe_u32 v63, v45, 16, 1
	v_pk_mul_f32 v[48:49], v[12:13], v[48:49]
	v_bfe_u32 v61, v47, 16, 1
	v_bfe_u32 v64, v43, 16, 1
	v_bfe_u32 v65, v42, 16, 1
	v_add3_u32 v45, v45, v63, s79
	v_add3_u32 v42, v42, v65, s79
	v_add3_u32 v43, v43, v64, s79
	v_add3_u32 v47, v47, v61, s79
	v_bfe_u32 v61, v44, 16, 1
	v_bfe_u32 v64, v48, 16, 1
	v_bfe_u32 v65, v49, 16, 1
	v_lshrrev_b32_e32 v63, 16, v45
	v_add3_u32 v49, v49, v65, s79
	v_add3_u32 v48, v48, v64, s79
	v_add3_u32 v44, v44, v61, s79
	v_pk_mul_f32 v[30:31], v[62:63], v[30:31] op_sel_hi:[0,1]
	v_pk_mul_f32 v[32:33], v[62:63], v[32:33] op_sel_hi:[0,1]
	v_lshrrev_b32_e32 v61, 16, v44
	v_lshrrev_b32_e32 v44, 16, v48
	v_lshrrev_b32_e32 v45, 16, v49
	v_pk_mul_f32 v[34:35], v[62:63], v[34:35] op_sel_hi:[0,1]
	v_pk_mul_f32 v[30:31], v[38:39], v[30:31]
	v_pk_mul_f32 v[36:37], v[62:63], v[36:37] op_sel_hi:[0,1]
	v_pk_mul_f32 v[32:33], v[2:3], v[32:33]
	v_and_or_b32 v45, v47, s75, v45
	v_and_or_b32 v44, v46, s75, v44
	v_pk_mul_f32 v[34:35], v[0:1], v[34:35]
	v_pk_mul_f32 v[36:37], v[8:9], v[36:37]
	v_bfe_u32 v46, v33, 16, 1
	v_bfe_u32 v47, v32, 16, 1
	v_bfe_u32 v48, v31, 16, 1
	v_bfe_u32 v49, v30, 16, 1
	v_add3_u32 v30, v30, v49, s79
	v_add3_u32 v31, v31, v48, s79
	v_add3_u32 v32, v32, v47, s79
	v_add3_u32 v33, v33, v46, s79
	v_bfe_u32 v46, v34, 16, 1
	v_bfe_u32 v47, v35, 16, 1
	v_bfe_u32 v48, v36, 16, 1
	v_bfe_u32 v49, v37, 16, 1
	v_add3_u32 v37, v37, v49, s79
	v_add3_u32 v36, v36, v48, s79
	v_add3_u32 v35, v35, v47, s79
	v_add3_u32 v34, v34, v46, s79
	v_and_or_b32 v43, v43, s75, v63
	v_and_or_b32 v42, v42, s75, v61
	v_lshrrev_b32_e32 v34, 16, v34
	v_lshrrev_b32_e32 v35, 16, v35
	v_lshrrev_b32_e32 v36, 16, v36
	v_lshrrev_b32_e32 v37, 16, v37
	v_and_or_b32 v33, v33, s75, v37
	v_and_or_b32 v32, v32, s75, v36
	v_and_or_b32 v31, v31, s75, v35
	v_and_or_b32 v30, v30, s75, v34
	global_store_dwordx4 v[26:27], v[42:45], off offset:-3072 sc0 sc1
	global_store_dwordx4 v[26:27], v[30:33], off offset:-3008 sc0 sc1

; __device__ __forceinline__ unsigned pk2(float lo, float hi) { return f2bf(lo) | (f2bf(hi) << 16); }
; template <bool ROPE> __device__ __forceinline__ void heads8(bf16* hbase, bool active, const float (&ga)[8], const float (&gb)[8], const float (&cs)[8], const float (&sn)[8], int lane) {
;     const int g = lane >> 3, sub = lane & 7, ca = 8 * (sub >> 2) + (sub & 3);
;     bf16* pa = hbase + g * 128 + ca * 8; bf16* pb = pa + 32;
;     v4u ra = {0u, 0u, 0u, 0u}, rb = ra; if (active) { ra = *(const v4u*)pa; rb = *(const v4u*)pb; }
;     float x[8], y[8]; unpack8(ra, x); unpack8(rb, y);
;     float ss = 0.f;
; #pragma unroll
;     for (int i = 0; i < 8; ++i) ss += x[i] * x[i] + y[i] * y[i];
; #pragma unroll
;     for (int o = 1; o < 8; o <<= 1) ss += __int_as_float(__builtin_amdgcn_ds_bpermute((lane ^ o) << 2, __float_as_int(ss)));
;     const float rstd = rsqrtf(ss * (1.0f / 128.0f) + EPS);
; #pragma unroll
;     for (int i = 0; i < 8; ++i) { float a = x[i] * rstd * ga[i], b = y[i] * rstd * gb[i];
;         if (ROPE) { const float na = a * cs[i] - b * sn[i], nb = b * cs[i] + a * sn[i]; a = na; b = nb; }
;         x[i] = a; y[i] = b; }
;     if (active) { v4u wa, wb; wa.x = pk2(x[0], x[1]); wa.y = pk2(x[2], x[3]); wa.z = pk2(x[4], x[5]); wa.w = pk2(x[6], x[7]); wb.x = pk2(y[0], y[1]); wb.y = pk2(y[2], y[3]); wb.z = pk2(y[4], y[5]); wb.w = pk2(y[6], y[7]);
;         *(v4u*)pa = wa; *(v4u*)pb = wb; }
; }
; __device__ __forceinline__ void rope_tab8(float (&cs)[8], float (&sn)[8], float prow, float pcol, int lane) {
;     const int sub = lane & 7; const float pos = (sub >> 2) ? pcol : prow;
; #pragma unroll
;     for (int i = 0; i < 8; ++i) rope_cs(pos, 8 * (sub & 3) + i, 1.0f / 32.0f, cs[i], sn[i]);
; }
; __device__ __forceinline__ void prep_cd(bf16* P, const float* cqn, const float* ckn, const float* dqn, const float* dkn, int gw, int NGW, int lane) {
;     ...
;         if (lat) { rope_tab8(cs, sn, pr, pc, lane); heads8<true>(row + 1024, lane < 16, gca, gcb, cs, sn, lane); }
.LBB0_327:
	s_or_b64 exec, exec, s[16:17]
	s_waitcnt vmcnt(1)
	v_lshlrev_b32_e32 v45, 16, v35
	v_lshlrev_b32_e32 v44, 16, v34
	v_and_b32_e32 v35, 0xffff0000, v35
	v_and_b32_e32 v34, 0xffff0000, v34
	s_waitcnt vmcnt(0)
	v_lshlrev_b32_e32 v49, 16, v31
	v_lshlrev_b32_e32 v48, 16, v30
	v_and_b32_e32 v47, 0xffff0000, v31
	v_and_b32_e32 v46, 0xffff0000, v30
	v_pk_mul_f32 v[30:31], v[44:45], v[44:45]
	v_lshlrev_b32_e32 v43, 16, v37
	s_waitcnt lgkmcnt(0)
	v_pk_fma_f32 v[62:63], v[48:49], v[48:49], v[30:31]
	v_pk_mul_f32 v[30:31], v[34:35], v[34:35]
	v_lshlrev_b32_e32 v42, 16, v36
	v_pk_fma_f32 v[64:65], v[46:47], v[46:47], v[30:31]
	v_and_b32_e32 v31, 0xffff0000, v37
	v_add_f32_e32 v61, v62, v64
	v_and_b32_e32 v30, 0xffff0000, v36
	v_lshlrev_b32_e32 v37, 16, v33
	v_lshlrev_b32_e32 v36, 16, v32
	v_pk_mul_f32 v[66:67], v[42:43], v[42:43]
	v_add_f32_e32 v61, v63, v61
	v_and_b32_e32 v33, 0xffff0000, v33
	v_and_b32_e32 v32, 0xffff0000, v32
	v_pk_fma_f32 v[66:67], v[36:37], v[36:37], v[66:67]
	v_pk_mul_f32 v[68:69], v[30:31], v[30:31]
	v_add_f32_e32 v61, v65, v61
	v_pk_fma_f32 v[68:69], v[32:33], v[32:33], v[68:69]
	v_add_f32_e32 v61, v66, v61
	v_add_f32_e32 v61, v68, v61
	v_add_f32_e32 v61, v67, v61
	v_add_f32_e32 v61, v69, v61
	ds_bpermute_b32 v62, v50, v61
	s_waitcnt lgkmcnt(0)
	v_add_f32_e32 v61, v61, v62
	ds_bpermute_b32 v62, v51, v61
	s_waitcnt lgkmcnt(0)
	v_add_f32_e32 v61, v61, v62
	ds_bpermute_b32 v62, v52, v61
	s_and_saveexec_b64 s[16:17], s[38:39]
	s_cbranch_execz .LBB0_316
	s_and_b32 s4, s2, 63
	s_bfe_u32 s5, s2, 0x70006
	v_mov_b32_e32 v63, s4
	v_mov_b32_e32 v64, s5
	v_cndmask_b32_e64 v63, v63, v64, s[40:41]
	v_cvt_f32_ubyte0_e32 v63, v63
	v_mul_f32_e32 v64, v53, v63
	v_mul_f32_e32 v72, v57, v63
	v_mul_f32_e32 v65, 0.15915494, v64
	v_mul_f32_e32 v73, 0.15915494, v72
	v_rndne_f32_e32 v65, v65
	v_rndne_f32_e32 v73, v73
	v_fma_f32 v65, v64, 0.15915494, -v65
	v_fma_f32 v73, v72, 0.15915494, -v73
	v_sin_f32_e32 v64, v65
	v_cos_f32_e32 v66, v65
	v_mul_f32_e32 v65, v54, v63
	v_sin_f32_e32 v72, v73
	v_cos_f32_e32 v74, v73
	v_mul_f32_e32 v73, v58, v63
	s_waitcnt lgkmcnt(0)
	v_add_f32_e32 v61, v61, v62
	v_mul_f32_e32 v67, 0.15915494, v65
	v_mul_f32_e32 v75, 0.15915494, v73
	v_fmamk_f32 v61, v61, 0x3c000000, v196
	v_rndne_f32_e32 v67, v67
	v_rndne_f32_e32 v75, v75
	v_mul_f32_e32 v62, 0x4b800000, v61
	v_cmp_gt_f32_e32 vcc, s78, v61
	v_fma_f32 v65, v65, 0.15915494, -v67
	v_fma_f32 v73, v73, 0.15915494, -v75
	v_cndmask_b32_e32 v61, v61, v62, vcc
	v_sin_f32_e32 v68, v65
	v_cos_f32_e32 v70, v65
	v_mul_f32_e32 v65, v55, v63
	v_mul_f32_e32 v69, v56, v63
	v_sin_f32_e32 v76, v73
	v_cos_f32_e32 v78, v73
	v_mul_f32_e32 v73, v59, v63
	v_mul_f32_e32 v63, v60, v63
	v_rsq_f32_e32 v61, v61
	v_mul_f32_e32 v67, 0.15915494, v65
	v_mul_f32_e32 v77, 0.15915494, v63
	v_rndne_f32_e32 v67, v67
	v_mul_f32_e32 v71, 0.15915494, v69
	v_rndne_f32_e32 v77, v77
	v_fma_f32 v67, v65, 0.15915494, -v67
	v_rndne_f32_e32 v71, v71
	v_fma_f32 v62, v63, 0.15915494, -v77
	v_sin_f32_e32 v65, v67
	v_fma_f32 v71, v69, 0.15915494, -v71
	v_mul_f32_e32 v75, 0.15915494, v73
	v_sin_f32_e32 v77, v62
	v_cos_f32_e32 v79, v62
	v_mul_f32_e32 v62, 0x45800000, v61
	v_cos_f32_e32 v67, v67
	v_sin_f32_e32 v69, v71
	v_rndne_f32_e32 v75, v75
	v_cndmask_b32_e32 v62, v61, v62, vcc
	v_cos_f32_e32 v71, v71
	v_fma_f32 v75, v73, 0.15915494, -v75
	v_pk_mul_f32 v[44:45], v[62:63], v[44:45] op_sel_hi:[0,1]
	v_sin_f32_e32 v73, v75
	v_pk_mul_f32 v[48:49], v[62:63], v[48:49] op_sel_hi:[0,1]
	v_pk_mul_f32 v[44:45], v[4:5], v[44:45]
	v_pk_mul_f32 v[34:35], v[62:63], v[34:35] op_sel_hi:[0,1]
	v_cos_f32_e32 v75, v75
	v_pk_mul_f32 v[48:49], v[0:1], v[48:49]
	v_pk_mul_f32 v[80:81], v[64:65], v[44:45]
	v_pk_mul_f32 v[46:47], v[62:63], v[46:47] op_sel_hi:[0,1]
	v_pk_mul_f32 v[34:35], v[40:41], v[34:35]
	v_pk_mul_f32 v[30:31], v[62:63], v[30:31] op_sel_hi:[0,1]
	v_pk_fma_f32 v[80:81], v[66:67], v[48:49], v[80:81]
	v_pk_mul_f32 v[46:47], v[38:39], v[46:47]
	v_pk_mul_f32 v[82:83], v[68:69], v[34:35]
	v_pk_mul_f32 v[48:49], v[64:65], v[48:49]
	v_pk_mul_f32 v[42:43], v[62:63], v[42:43] op_sel_hi:[0,1]
	v_pk_mul_f32 v[32:33], v[62:63], v[32:33] op_sel_hi:[0,1]
	v_pk_mul_f32 v[30:31], v[6:7], v[30:31]
	v_pk_fma_f32 v[82:83], v[70:71], v[46:47], v[82:83]
	v_pk_fma_f32 v[44:45], v[66:67], v[44:45], v[48:49] neg_lo:[0,0,1] neg_hi:[0,0,1]
	v_pk_mul_f32 v[46:47], v[68:69], v[46:47]
	v_pk_mul_f32 v[36:37], v[62:63], v[36:37] op_sel_hi:[0,1]
	v_pk_mul_f32 v[42:43], v[12:13], v[42:43]
	v_pk_mul_f32 v[32:33], v[2:3], v[32:33]
	v_pk_mul_f32 v[48:49], v[76:77], v[30:31]
	v_pk_fma_f32 v[34:35], v[70:71], v[34:35], v[46:47] neg_lo:[0,0,1] neg_hi:[0,0,1]
	v_pk_mul_f32 v[36:37], v[8:9], v[36:37]
	v_pk_mul_f32 v[46:47], v[72:73], v[42:43]
	v_pk_fma_f32 v[48:49], v[78:79], v[32:33], v[48:49]
	v_pk_mul_f32 v[32:33], v[76:77], v[32:33]
	v_pk_fma_f32 v[46:47], v[74:75], v[36:37], v[46:47]
	v_pk_mul_f32 v[36:37], v[72:73], v[36:37]
	v_pk_fma_f32 v[30:31], v[78:79], v[30:31], v[32:33] neg_lo:[0,0,1] neg_hi:[0,0,1]
	v_pk_fma_f32 v[36:37], v[74:75], v[42:43], v[36:37] neg_lo:[0,0,1] neg_hi:[0,0,1]
	v_bfe_u32 v32, v31, 16, 1
	v_bfe_u32 v33, v30, 16, 1
	v_bfe_u32 v42, v35, 16, 1
	v_bfe_u32 v43, v34, 16, 1
	v_add3_u32 v34, v34, v43, s79
	v_add3_u32 v35, v35, v42, s79
	v_add3_u32 v30, v30, v33, s79
	v_add3_u32 v31, v31, v32, s79
	v_bfe_u32 v32, v44, 16, 1
	v_bfe_u32 v33, v45, 16, 1
	v_bfe_u32 v42, v36, 16, 1
	v_bfe_u32 v43, v37, 16, 1
	v_add3_u32 v37, v37, v43, s79
	v_add3_u32 v36, v36, v42, s79
	v_add3_u32 v33, v45, v33, s79
	v_add3_u32 v32, v44, v32, s79
	v_lshrrev_b32_e32 v42, 16, v32
	v_lshrrev_b32_e32 v43, 16, v33
	v_lshrrev_b32_e32 v32, 16, v36
	v_lshrrev_b32_e32 v33, 16, v37
	v_bfe_u32 v36, v83, 16, 1
	v_bfe_u32 v37, v82, 16, 1
	v_and_or_b32 v33, v31, s75, v33
	v_and_or_b32 v32, v30, s75, v32
	v_and_or_b32 v31, v35, s75, v43
	v_and_or_b32 v30, v34, s75, v42
	v_add3_u32 v42, v82, v37, s79
	v_add3_u32 v43, v83, v36, s79
	v_bfe_u32 v36, v80, 16, 1
	v_bfe_u32 v37, v81, 16, 1
	v_bfe_u32 v44, v46, 16, 1
	v_bfe_u32 v45, v47, 16, 1
	v_bfe_u32 v34, v49, 16, 1
	v_bfe_u32 v35, v48, 16, 1
	v_add3_u32 v45, v47, v45, s79
	v_add3_u32 v44, v46, v44, s79
	v_add3_u32 v37, v81, v37, s79
	v_add3_u32 v36, v80, v36, s79
	v_add3_u32 v35, v48, v35, s79
	v_add3_u32 v34, v49, v34, s79
	v_lshrrev_b32_e32 v46, 16, v36
	v_lshrrev_b32_e32 v47, 16, v37
	v_lshrrev_b32_e32 v36, 16, v44
	v_lshrrev_b32_e32 v37, 16, v45
	v_and_or_b32 v37, v34, s75, v37
	v_and_or_b32 v36, v35, s75, v36
	v_and_or_b32 v35, v43, s75, v47
	v_and_or_b32 v34, v42, s75, v46
	global_store_dwordx4 v[26:27], v[30:33], off offset:-3072 sc0 sc1
	global_store_dwordx4 v[26:27], v[34:37], off offset:-3008 sc0 sc1
	s_branch .LBB0_316

; __device__ __forceinline__ unsigned pk2(float lo, float hi) { return f2bf(lo) | (f2bf(hi) << 16); }
; __device__ __forceinline__ void prep_ab(bf16* P, const float* aqn, const float* akn, const float* bqn, const float* bkvn, int gw, int NGW, int lane) {
;     ...
;         { float ss = 0.f;
; #pragma unroll
;           for (int i = 0; i < 8; ++i) ss += c1[i] * c1[i];
;           const float rstd = rsqrtf(wave_sum(ss, lane) * (1.0f / 512.0f) + EPS);
;           v4u w; w.x = pk2(c1[0] * rstd * q0[0], c1[1] * rstd * q0[1]); w.y = pk2(c1[2] * rstd * q0[2], c1[3] * rstd * q0[3]); w.z = pk2(c1[4] * rstd * q1[0], c1[5] * rstd * q1[1]); w.w = pk2(c1[6] * rstd * q1[2], c1[7] * rstd * q1[3]);
;           *(v4u*)(row + 1536 + 8 * lane) = w; }
;         { float ss = 0.f;
; #pragma unroll
;           for (int i = 0; i < 8; ++i) ss += c2[i] * c2[i];
;           const float rstd = rsqrtf(wave_sum(ss, lane) * (1.0f / 512.0f) + EPS);
;           v4u w; w.x = pk2(c2[0] * rstd * k0[0], c2[1] * rstd * k0[1]); w.y = pk2(c2[2] * rstd * k0[2], c2[3] * rstd * k0[3]); w.z = pk2(c2[4] * rstd * k1[0], c2[5] * rstd * k1[1]); w.w = pk2(c2[6] * rstd * k1[2], c2[7] * rstd * k1[3]);
;           *(v4u*)(row + 2048 + 8 * lane) = w; }
.LBB0_569:
	s_waitcnt vmcnt(1)
	v_lshlrev_b32_e32 v38, 16, v34
	v_and_b32_e32 v34, 0xffff0000, v34
	s_waitcnt vmcnt(0)
	v_and_b32_e32 v44, 0xffff0000, v30
	v_lshlrev_b32_e32 v42, 16, v30
	v_mov_b32_e32 v62, v44
	v_mov_b32_e32 v63, v34
	v_lshlrev_b32_e32 v39, 16, v35
	v_lshlrev_b32_e32 v40, 16, v36
	v_and_b32_e32 v36, 0xffff0000, v36
	v_lshlrev_b32_e32 v43, 16, v31
	v_lshlrev_b32_e32 v54, 16, v32
	v_and_b32_e32 v56, 0xffff0000, v32
	v_mov_b32_e32 v60, v42
	v_mov_b32_e32 v61, v38
	v_pk_mul_f32 v[62:63], v[62:63], v[62:63]
	v_and_b32_e32 v35, 0xffff0000, v35
	v_and_b32_e32 v45, 0xffff0000, v31
	v_mov_b32_e32 v30, v36
	v_mov_b32_e32 v31, v40
	v_mov_b32_e32 v58, v56
	v_mov_b32_e32 v59, v54
	v_pk_fma_f32 v[60:61], v[60:61], v[60:61], v[62:63]
	v_mov_b32_e32 v62, v43
	v_mov_b32_e32 v63, v39
	v_pk_mul_f32 v[30:31], v[30:31], v[30:31]
	v_pk_mul_f32 v[58:59], v[58:59], v[58:59]
	v_pk_fma_f32 v[60:61], v[62:63], v[62:63], v[60:61]
	v_mov_b32_e32 v62, v45
	v_mov_b32_e32 v63, v35
	v_lshlrev_b32_e32 v41, 16, v37
	v_and_b32_e32 v37, 0xffff0000, v37
	v_lshlrev_b32_e32 v55, 16, v33
	v_and_b32_e32 v57, 0xffff0000, v33
	v_pk_fma_f32 v[60:61], v[62:63], v[62:63], v[60:61]
	v_mov_b32_e32 v62, v59
	v_mov_b32_e32 v63, v31
	v_mov_b32_e32 v32, v37
	v_mov_b32_e32 v33, v41
	v_pk_add_f32 v[60:61], v[62:63], v[60:61]
	v_mov_b32_e32 v62, v57
	v_mov_b32_e32 v63, v55
	v_pk_mul_f32 v[32:33], v[32:33], v[32:33]
	v_pk_mul_f32 v[62:63], v[62:63], v[62:63]
	v_mov_b32_e32 v59, v30
	v_pk_add_f32 v[30:31], v[58:59], v[60:61]
	v_mov_b32_e32 v58, v63
	v_mov_b32_e32 v59, v33
	v_pk_add_f32 v[30:31], v[58:59], v[30:31]
	v_mov_b32_e32 v63, v32
	v_pk_add_f32 v[30:31], v[62:63], v[30:31]
	ds_bpermute_b32 v33, v66, v31
	ds_bpermute_b32 v32, v66, v30
	s_mov_b32 s4, 0x3b000000
	s_add_i32 s2, s2, s33
	s_waitcnt lgkmcnt(0)
	v_pk_add_f32 v[30:31], v[30:31], v[32:33]
	ds_bpermute_b32 v33, v67, v31
	ds_bpermute_b32 v32, v67, v30
	s_waitcnt lgkmcnt(0)
	v_pk_add_f32 v[30:31], v[30:31], v[32:33]
	ds_bpermute_b32 v33, v68, v31
	ds_bpermute_b32 v32, v68, v30
	s_waitcnt lgkmcnt(0)
	v_pk_add_f32 v[30:31], v[30:31], v[32:33]
	ds_bpermute_b32 v33, v69, v31
	ds_bpermute_b32 v32, v69, v30
	s_waitcnt lgkmcnt(0)
	v_pk_add_f32 v[30:31], v[30:31], v[32:33]
	ds_bpermute_b32 v33, v70, v31
	ds_bpermute_b32 v32, v70, v30
	s_waitcnt lgkmcnt(0)
	v_pk_add_f32 v[30:31], v[30:31], v[32:33]
	ds_bpermute_b32 v33, v71, v31
	ds_bpermute_b32 v32, v71, v30
	s_waitcnt lgkmcnt(0)
	v_pk_add_f32 v[30:31], v[30:31], v[32:33]
	s_nop 0
	v_pk_fma_f32 v[30:31], v[30:31], s[4:5], v[196:197] op_sel_hi:[1,0,0]
	s_mov_b64 s[4:5], 0x13e00c00
	v_mul_f32_e32 v32, 0x4b800000, v31
	v_cmp_gt_f32_e32 vcc, s78, v31
	v_lshl_add_u64 v[58:59], v[52:53], 0, s[4:5]
	s_mov_b64 s[4:5], 0x13e01000
	v_cndmask_b32_e32 v31, v31, v32, vcc
	v_rsq_f32_e32 v31, v31
	v_lshl_add_u64 v[52:53], v[52:53], 0, s[4:5]
	s_mul_i32 s4, s33, 0x1600
	s_add_u32 s16, s16, s4
	v_mul_f32_e32 v32, 0x45800000, v31
	v_cndmask_b32_e32 v32, v31, v32, vcc
	v_pk_mul_f32 v[38:39], v[32:33], v[38:39] op_sel_hi:[0,1]
	v_pk_mul_f32 v[34:35], v[32:33], v[34:35] op_sel_hi:[0,1]
	v_pk_mul_f32 v[40:41], v[32:33], v[40:41] op_sel_hi:[0,1]
	v_pk_mul_f32 v[32:33], v[32:33], v[36:37] op_sel_hi:[0,1]
	v_pk_mul_f32 v[34:35], v[46:47], v[34:35]
	v_pk_mul_f32 v[32:33], v[2:3], v[32:33]
	v_pk_mul_f32 v[38:39], v[0:1], v[38:39]
	v_pk_mul_f32 v[40:41], v[4:5], v[40:41]
	v_bfe_u32 v31, v33, 16, 1
	v_bfe_u32 v60, v34, 16, 1
	v_add3_u32 v34, v34, v60, s79
	v_add3_u32 v31, v33, v31, s79
	v_bfe_u32 v33, v38, 16, 1
	v_bfe_u32 v60, v41, 16, 1
	v_bfe_u32 v37, v35, 16, 1
	v_add3_u32 v41, v41, v60, s79
	v_add3_u32 v33, v38, v33, s79
	v_add3_u32 v35, v35, v37, s79
	v_bfe_u32 v37, v40, 16, 1
	v_lshrrev_b32_e32 v38, 16, v33
	v_lshrrev_b32_e32 v33, 16, v41
	v_bfe_u32 v36, v32, 16, 1
	v_add3_u32 v37, v40, v37, s79
	v_and_or_b32 v33, v31, s75, v33
	v_mul_f32_e32 v31, 0x4b800000, v30
	v_cmp_gt_f32_e32 vcc, s78, v30
	v_add3_u32 v32, v32, v36, s79
	v_lshrrev_b32_e32 v37, 16, v37
	v_cndmask_b32_e32 v30, v30, v31, vcc
	v_bfe_u32 v36, v39, 16, 1
	v_and_or_b32 v32, v32, s75, v37
	v_rsq_f32_e32 v37, v30
	v_add3_u32 v36, v39, v36, s79
	v_lshrrev_b32_e32 v36, 16, v36
	v_and_or_b32 v31, v35, s75, v36
	v_and_or_b32 v30, v34, s75, v38
	global_store_dwordx4 v[58:59], v[30:33], off sc0 sc1
	s_mul_hi_i32 s4, s33, 0x1600
	s_addc_u32 s17, s17, s4
	v_mul_f32_e32 v30, 0x45800000, v37
	v_cndmask_b32_e32 v30, v37, v30, vcc
	v_pk_mul_f32 v[32:33], v[30:31], v[42:43] op_sel_hi:[0,1]
	v_pk_mul_f32 v[34:35], v[30:31], v[44:45] op_sel_hi:[0,1]
	v_pk_mul_f32 v[36:37], v[30:31], v[54:55] op_sel_hi:[0,1]
	v_pk_mul_f32 v[30:31], v[30:31], v[56:57] op_sel_hi:[0,1]
	v_pk_mul_f32 v[34:35], v[6:7], v[34:35]
	v_pk_mul_f32 v[30:31], v[14:15], v[30:31]
	v_pk_mul_f32 v[32:33], v[12:13], v[32:33]
	v_pk_mul_f32 v[36:37], v[8:9], v[36:37]
	v_bfe_u32 v38, v31, 16, 1
	v_bfe_u32 v39, v30, 16, 1
	v_bfe_u32 v40, v35, 16, 1
	v_bfe_u32 v41, v34, 16, 1
	v_add3_u32 v34, v34, v41, s79
	v_add3_u32 v35, v35, v40, s79
	v_add3_u32 v30, v30, v39, s79
	v_add3_u32 v31, v31, v38, s79
	v_bfe_u32 v38, v32, 16, 1
	v_bfe_u32 v39, v33, 16, 1
	v_bfe_u32 v40, v36, 16, 1
	v_bfe_u32 v41, v37, 16, 1
	v_add3_u32 v37, v37, v41, s79
	v_add3_u32 v36, v36, v40, s79
	v_add3_u32 v33, v33, v39, s79
	v_add3_u32 v32, v32, v38, s79
	v_lshrrev_b32_e32 v38, 16, v32
	v_lshrrev_b32_e32 v39, 16, v33
	v_lshrrev_b32_e32 v32, 16, v36
	v_lshrrev_b32_e32 v33, 16, v37
	v_and_or_b32 v33, v31, s75, v33
	v_and_or_b32 v32, v30, s75, v32
	v_and_or_b32 v31, v35, s75, v39
	v_and_or_b32 v30, v34, s75, v38
	s_cmpk_lt_i32 s2, 0x4200
	global_store_dwordx4 v[52:53], v[30:33], off sc0 sc1
	s_cbranch_scc0 .LBB0_583
; __device__ __forceinline__ unsigned f2bf(float f) { unsigned u = __builtin_bit_cast(unsigned, f); return (u + 0x7fffu + ((u >> 16) & 1u)) >> 16; }
; __device__ __forceinline__ float bf2f(bf16 v) { return __uint_as_float(((unsigned)v) << 16); }
; __device__ __forceinline__ void rope64(bf16* p, float prow, float pcol, int l32) {
;     const int j = l32 & 15, s = (l32 >> 4) & 1, ia = 32 * s + j, ib = ia + 16;
;     const float x = bf2f(p[ia]), y = bf2f(p[ib]); float cs, sn; rope_cs(s ? pcol : prow, j, 1.0f / 16.0f, cs, sn);
;     p[ia] = (bf16)f2bf(x * cs - y * sn); p[ib] = (bf16)f2bf(y * cs + x * sn);
; }
; __device__ __forceinline__ void prep_ab(bf16* P, const float* aqn, const float* akn, const float* bqn, const float* bkvn, int gw, int NGW, int lane) {
;     ...
;     for (int m = gw; m < MALL; m += NGW) {
;         bf16* row = P + (size_t)m * N_IN0; const bool lat = m < MLAT; const int t = m & (SEQ - 1); const float pr = (float)(t >> 6), pc = (float)(t & 63);
;         float c1[8], c2[8];
;         unpack8(*(const v4u*)(row + 1536 + 8 * lane), c1); unpack8(*(const v4u*)(row + 2048 + 8 * lane), c2);
;         if (lat && lane < 32) rope64(row + 2560, pr, pc, lane);
.LBB0_570:
	v_lshl_add_u64 v[52:53], s[16:17], 0, v[26:27]
	v_add_co_u32_e32 v30, vcc, 0x13e00000, v52
	s_cmpk_gt_i32 s2, 0x3fff
	s_nop 0
	v_addc_co_u32_e32 v31, vcc, 0, v53, vcc
	v_add_co_u32_e32 v32, vcc, 0x13e01000, v52
	s_cselect_b64 s[18:19], -1, 0
	s_nop 0
	v_addc_co_u32_e32 v33, vcc, 0, v53, vcc
	global_load_dwordx4 v[34:37], v[30:31], off offset:3072
	s_nop 0
	global_load_dwordx4 v[30:33], v[32:33], off
	s_cmpk_lt_i32 s2, 0x4000
	s_cselect_b64 s[4:5], -1, 0
	s_bfe_u32 s6, s2, 0x70006
	v_cvt_f32_ubyte0_e32 v81, s6
	s_and_b32 s6, s2, 63
	v_cvt_f32_ubyte0_e32 v82, s6
	s_and_b64 s[4:5], s[4:5], s[38:39]
	s_and_saveexec_b64 s[20:21], s[4:5]
	s_cbranch_execz .LBB0_572
	v_lshl_add_u64 v[38:39], s[16:17], 0, v[50:51]
	v_add_co_u32_e32 v38, vcc, 0x13e01000, v38
	v_cndmask_b32_e64 v42, v82, v81, s[40:41]
	s_nop 0
	v_addc_co_u32_e32 v39, vcc, 0, v39, vcc
	global_load_ushort v40, v[38:39], off offset:1024
	global_load_ushort v41, v[38:39], off offset:1056
	v_mul_f32_e32 v42, v72, v42
	v_mul_f32_e32 v43, 0.15915494, v42
	v_rndne_f32_e32 v43, v43
	v_fma_f32 v42, v42, 0.15915494, -v43
	v_sin_f32_e32 v43, v42
	v_cos_f32_e32 v42, v42
	s_waitcnt vmcnt(1)
	v_lshlrev_b32_e32 v40, 16, v40
	s_waitcnt vmcnt(0)
	v_lshlrev_b32_e32 v41, 16, v41
	v_mul_f32_e32 v44, v43, v41
	v_mul_f32_e32 v41, v42, v41
	v_fma_f32 v42, v42, v40, -v44
	v_fmac_f32_e32 v41, v43, v40
	v_bfe_u32 v40, v42, 16, 1
	v_bfe_u32 v43, v41, 16, 1
	v_add3_u32 v40, v42, v40, s79
	v_add3_u32 v41, v41, v43, s79
	global_store_short_d16_hi v[38:39], v40, off offset:1024 sc0 sc1
	global_store_short_d16_hi v[38:39], v41, off offset:1056 sc0 sc1

; __device__ __forceinline__ unsigned pk2(float lo, float hi) { return f2bf(lo) | (f2bf(hi) << 16); }
; template <bool ROPE> __device__ __forceinline__ void heads8(bf16* hbase, bool active, const float (&ga)[8], const float (&gb)[8], const float (&cs)[8], const float (&sn)[8], int lane) {
;     const int g = lane >> 3, sub = lane & 7, ca = 8 * (sub >> 2) + (sub & 3);
;     bf16* pa = hbase + g * 128 + ca * 8; bf16* pb = pa + 32;
;     v4u ra = {0u, 0u, 0u, 0u}, rb = ra; if (active) { ra = *(const v4u*)pa; rb = *(const v4u*)pb; }
;     float x[8], y[8]; unpack8(ra, x); unpack8(rb, y);
;     float ss = 0.f;
; #pragma unroll
;     for (int i = 0; i < 8; ++i) ss += x[i] * x[i] + y[i] * y[i];
; #pragma unroll
;     for (int o = 1; o < 8; o <<= 1) ss += __int_as_float(__builtin_amdgcn_ds_bpermute((lane ^ o) << 2, __float_as_int(ss)));
;     const float rstd = rsqrtf(ss * (1.0f / 128.0f) + EPS);
; #pragma unroll
;     for (int i = 0; i < 8; ++i) { float a = x[i] * rstd * ga[i], b = y[i] * rstd * gb[i];
;         if (ROPE) { const float na = a * cs[i] - b * sn[i], nb = b * cs[i] + a * sn[i]; a = na; b = nb; }
;         x[i] = a; y[i] = b; }
;     if (active) { v4u wa, wb; wa.x = pk2(x[0], x[1]); wa.y = pk2(x[2], x[3]); wa.z = pk2(x[4], x[5]); wa.w = pk2(x[6], x[7]); wb.x = pk2(y[0], y[1]); wb.y = pk2(y[2], y[3]); wb.z = pk2(y[4], y[5]); wb.w = pk2(y[6], y[7]);
;         *(v4u*)pa = wa; *(v4u*)pb = wb; }
; }
; __device__ __forceinline__ void prep_ab(bf16* P, const float* aqn, const float* akn, const float* bqn, const float* bkvn, int gw, int NGW, int lane) {
;     ...
;         else {
; #pragma unroll
;             for (int i = 0; i < 8; ++i) { cs[i] = 1.f; sn[i] = 0.f; }
;             heads8<false>(row + 1024, lane < 16, ga, gb, cs, sn, lane); }
.LBB0_575:
	s_or_b64 exec, exec, s[18:19]
	s_waitcnt vmcnt(1)
	v_lshlrev_b32_e32 v61, 16, v43
	v_lshlrev_b32_e32 v60, 16, v42
	v_and_b32_e32 v59, 0xffff0000, v43
	v_and_b32_e32 v58, 0xffff0000, v42
	v_pk_mul_f32 v[62:63], v[60:61], v[60:61]
	v_pk_mul_f32 v[64:65], v[58:59], v[58:59]
	s_waitcnt vmcnt(0)
	v_lshlrev_b32_e32 v43, 16, v39
	v_lshlrev_b32_e32 v42, 16, v38
	v_and_b32_e32 v39, 0xffff0000, v39
	v_and_b32_e32 v38, 0xffff0000, v38
	v_pk_fma_f32 v[84:85], v[42:43], v[42:43], v[62:63]
	v_pk_fma_f32 v[86:87], v[38:39], v[38:39], v[64:65]
	v_lshlrev_b32_e32 v65, 16, v45
	v_lshlrev_b32_e32 v64, 16, v44
	v_add_f32_e32 v83, v84, v86
	v_and_b32_e32 v63, 0xffff0000, v45
	v_and_b32_e32 v62, 0xffff0000, v44
	v_pk_mul_f32 v[88:89], v[64:65], v[64:65]
	v_lshlrev_b32_e32 v45, 16, v41
	v_lshlrev_b32_e32 v44, 16, v40
	v_add_f32_e32 v83, v85, v83
	v_pk_mul_f32 v[90:91], v[62:63], v[62:63]
	v_and_b32_e32 v41, 0xffff0000, v41
	v_and_b32_e32 v40, 0xffff0000, v40
	v_pk_fma_f32 v[88:89], v[44:45], v[44:45], v[88:89]
	v_add_f32_e32 v83, v87, v83
	v_pk_fma_f32 v[90:91], v[40:41], v[40:41], v[90:91]
	v_add_f32_e32 v83, v88, v83
	v_add_f32_e32 v83, v90, v83
	v_add_f32_e32 v83, v89, v83
	v_add_f32_e32 v83, v91, v83
	ds_bpermute_b32 v84, v66, v83
	s_waitcnt lgkmcnt(0)
	v_add_f32_e32 v83, v83, v84
	ds_bpermute_b32 v84, v67, v83
	s_waitcnt lgkmcnt(0)
	v_add_f32_e32 v83, v83, v84
	ds_bpermute_b32 v84, v68, v83
	s_and_saveexec_b64 s[18:19], s[40:41]
	s_cbranch_execz .LBB0_577
	s_waitcnt lgkmcnt(0)
	v_add_f32_e32 v83, v83, v84
	v_fmamk_f32 v83, v83, 0x3c000000, v196
	v_mul_f32_e32 v84, 0x4b800000, v83
	v_cmp_gt_f32_e32 vcc, s78, v83
	s_nop 1
	v_cndmask_b32_e32 v83, v83, v84, vcc
	v_rsq_f32_e32 v83, v83
	s_nop 0
	v_mul_f32_e32 v84, 0x45800000, v83
	v_cndmask_b32_e32 v84, v83, v84, vcc
	v_pk_mul_f32 v[62:63], v[84:85], v[62:63] op_sel_hi:[0,1]
	v_pk_mul_f32 v[60:61], v[84:85], v[60:61] op_sel_hi:[0,1]
	v_pk_mul_f32 v[62:63], v[22:23], v[62:63]
	v_pk_mul_f32 v[58:59], v[84:85], v[58:59] op_sel_hi:[0,1]
	v_pk_mul_f32 v[60:61], v[20:21], v[60:61]
	v_pk_mul_f32 v[64:65], v[84:85], v[64:65] op_sel_hi:[0,1]
	v_bfe_u32 v85, v62, 16, 1
	v_pk_mul_f32 v[58:59], v[48:49], v[58:59]
	v_add3_u32 v62, v62, v85, s79
	v_bfe_u32 v85, v61, 16, 1
	v_pk_mul_f32 v[64:65], v[28:29], v[64:65]
	v_bfe_u32 v83, v63, 16, 1
	v_bfe_u32 v86, v59, 16, 1
	v_bfe_u32 v87, v58, 16, 1
	v_add3_u32 v61, v61, v85, s79
	v_add3_u32 v58, v58, v87, s79
	v_add3_u32 v59, v59, v86, s79
	v_add3_u32 v63, v63, v83, s79
	v_bfe_u32 v83, v60, 16, 1
	v_bfe_u32 v86, v64, 16, 1
	v_bfe_u32 v87, v65, 16, 1
	v_lshrrev_b32_e32 v85, 16, v61
	v_add3_u32 v65, v65, v87, s79
	v_add3_u32 v64, v64, v86, s79
	v_add3_u32 v60, v60, v83, s79
	v_pk_mul_f32 v[38:39], v[84:85], v[38:39] op_sel_hi:[0,1]
	v_pk_mul_f32 v[40:41], v[84:85], v[40:41] op_sel_hi:[0,1]
	v_lshrrev_b32_e32 v83, 16, v60
	v_lshrrev_b32_e32 v60, 16, v64
	v_lshrrev_b32_e32 v61, 16, v65
	v_pk_mul_f32 v[42:43], v[84:85], v[42:43] op_sel_hi:[0,1]
	v_pk_mul_f32 v[38:39], v[10:11], v[38:39]
	v_pk_mul_f32 v[44:45], v[84:85], v[44:45] op_sel_hi:[0,1]
	v_pk_mul_f32 v[40:41], v[18:19], v[40:41]
	v_and_or_b32 v61, v63, s75, v61
	v_and_or_b32 v60, v62, s75, v60
	v_pk_mul_f32 v[42:43], v[16:17], v[42:43]
	v_pk_mul_f32 v[44:45], v[24:25], v[44:45]
	v_bfe_u32 v62, v41, 16, 1
	v_bfe_u32 v63, v40, 16, 1
	v_bfe_u32 v64, v39, 16, 1
	v_bfe_u32 v65, v38, 16, 1
	v_add3_u32 v38, v38, v65, s79
	v_add3_u32 v39, v39, v64, s79
	v_add3_u32 v40, v40, v63, s79
	v_add3_u32 v41, v41, v62, s79
	v_bfe_u32 v62, v42, 16, 1
	v_bfe_u32 v63, v43, 16, 1
	v_bfe_u32 v64, v44, 16, 1
	v_bfe_u32 v65, v45, 16, 1
	v_add3_u32 v45, v45, v65, s79
	v_add3_u32 v44, v44, v64, s79
	v_add3_u32 v43, v43, v63, s79
	v_add3_u32 v42, v42, v62, s79
	v_and_or_b32 v59, v59, s75, v85
	v_and_or_b32 v58, v58, s75, v83
	v_lshrrev_b32_e32 v42, 16, v42
	v_lshrrev_b32_e32 v43, 16, v43
	v_lshrrev_b32_e32 v44, 16, v44
	v_lshrrev_b32_e32 v45, 16, v45
	v_and_or_b32 v41, v41, s75, v45
	v_and_or_b32 v40, v40, s75, v44
	v_and_or_b32 v39, v39, s75, v43
	v_and_or_b32 v38, v38, s75, v42
	global_store_dwordx4 v[54:55], v[58:61], off sc0 sc1
	global_store_dwordx4 v[56:57], v[38:41], off sc0 sc1

; __device__ __forceinline__ unsigned pk2(float lo, float hi) { return f2bf(lo) | (f2bf(hi) << 16); }
; template <bool ROPE> __device__ __forceinline__ void heads8(bf16* hbase, bool active, const float (&ga)[8], const float (&gb)[8], const float (&cs)[8], const float (&sn)[8], int lane) {
;     const int g = lane >> 3, sub = lane & 7, ca = 8 * (sub >> 2) + (sub & 3);
;     bf16* pa = hbase + g * 128 + ca * 8; bf16* pb = pa + 32;
;     v4u ra = {0u, 0u, 0u, 0u}, rb = ra; if (active) { ra = *(const v4u*)pa; rb = *(const v4u*)pb; }
;     float x[8], y[8]; unpack8(ra, x); unpack8(rb, y);
;     float ss = 0.f;
; #pragma unroll
;     for (int i = 0; i < 8; ++i) ss += x[i] * x[i] + y[i] * y[i];
; #pragma unroll
;     for (int o = 1; o < 8; o <<= 1) ss += __int_as_float(__builtin_amdgcn_ds_bpermute((lane ^ o) << 2, __float_as_int(ss)));
;     const float rstd = rsqrtf(ss * (1.0f / 128.0f) + EPS);
; #pragma unroll
;     for (int i = 0; i < 8; ++i) { float a = x[i] * rstd * ga[i], b = y[i] * rstd * gb[i];
;         if (ROPE) { const float na = a * cs[i] - b * sn[i], nb = b * cs[i] + a * sn[i]; a = na; b = nb; }
;         x[i] = a; y[i] = b; }
;     if (active) { v4u wa, wb; wa.x = pk2(x[0], x[1]); wa.y = pk2(x[2], x[3]); wa.z = pk2(x[4], x[5]); wa.w = pk2(x[6], x[7]); wb.x = pk2(y[0], y[1]); wb.y = pk2(y[2], y[3]); wb.z = pk2(y[4], y[5]); wb.w = pk2(y[6], y[7]);
;         *(v4u*)pa = wa; *(v4u*)pb = wb; }
; }
; __device__ __forceinline__ void rope_tab8(float (&cs)[8], float (&sn)[8], float prow, float pcol, int lane) {
;     const int sub = lane & 7; const float pos = (sub >> 2) ? pcol : prow;
; #pragma unroll
;     for (int i = 0; i < 8; ++i) rope_cs(pos, 8 * (sub & 3) + i, 1.0f / 32.0f, cs[i], sn[i]);
; }
; __device__ __forceinline__ void prep_ab(bf16* P, const float* aqn, const float* akn, const float* bqn, const float* bkvn, int gw, int NGW, int lane) {
;     ...
;         if (lat) { rope_tab8(cs, sn, pr, pc, lane); heads8<true>(row + 1024, lane < 16, ga, gb, cs, sn, lane); }
.LBB0_581:
	s_or_b64 exec, exec, s[18:19]
	s_waitcnt vmcnt(1)
	v_lshlrev_b32_e32 v61, 16, v43
	v_lshlrev_b32_e32 v60, 16, v42
	v_and_b32_e32 v43, 0xffff0000, v43
	v_and_b32_e32 v42, 0xffff0000, v42
	s_waitcnt vmcnt(0)
	v_lshlrev_b32_e32 v65, 16, v39
	v_lshlrev_b32_e32 v64, 16, v38
	v_and_b32_e32 v63, 0xffff0000, v39
	v_and_b32_e32 v62, 0xffff0000, v38
	v_pk_mul_f32 v[38:39], v[60:61], v[60:61]
	v_lshlrev_b32_e32 v59, 16, v45
	s_waitcnt lgkmcnt(0)
	v_pk_fma_f32 v[84:85], v[64:65], v[64:65], v[38:39]
	v_pk_mul_f32 v[38:39], v[42:43], v[42:43]
	v_lshlrev_b32_e32 v58, 16, v44
	v_pk_fma_f32 v[86:87], v[62:63], v[62:63], v[38:39]
	v_and_b32_e32 v39, 0xffff0000, v45
	v_add_f32_e32 v83, v84, v86
	v_and_b32_e32 v38, 0xffff0000, v44
	v_lshlrev_b32_e32 v45, 16, v41
	v_lshlrev_b32_e32 v44, 16, v40
	v_pk_mul_f32 v[88:89], v[58:59], v[58:59]
	v_add_f32_e32 v83, v85, v83
	v_and_b32_e32 v41, 0xffff0000, v41
	v_and_b32_e32 v40, 0xffff0000, v40
	v_pk_fma_f32 v[88:89], v[44:45], v[44:45], v[88:89]
	v_pk_mul_f32 v[90:91], v[38:39], v[38:39]
	v_add_f32_e32 v83, v87, v83
	v_pk_fma_f32 v[90:91], v[40:41], v[40:41], v[90:91]
	v_add_f32_e32 v83, v88, v83
	v_add_f32_e32 v83, v90, v83
	v_add_f32_e32 v83, v89, v83
	v_add_f32_e32 v83, v91, v83
	ds_bpermute_b32 v84, v66, v83
	s_waitcnt lgkmcnt(0)
	v_add_f32_e32 v83, v83, v84
	ds_bpermute_b32 v84, v67, v83
	s_waitcnt lgkmcnt(0)
	v_add_f32_e32 v83, v83, v84
	ds_bpermute_b32 v84, v68, v83
	s_and_saveexec_b64 s[18:19], s[40:41]
	s_cbranch_execz .LBB0_568
	v_cndmask_b32_e64 v81, v82, v81, s[42:43]
	v_mul_f32_e32 v82, v73, v81
	v_mul_f32_e32 v85, 0.15915494, v82
	v_rndne_f32_e32 v85, v85
	v_fma_f32 v82, v82, 0.15915494, -v85
	v_sin_f32_e32 v86, v82
	v_cos_f32_e32 v88, v82
	v_mul_f32_e32 v82, v74, v81
	v_mul_f32_e32 v85, 0.15915494, v82
	v_rndne_f32_e32 v85, v85
	v_fma_f32 v82, v82, 0.15915494, -v85
	v_sin_f32_e32 v90, v82
	v_cos_f32_e32 v92, v82
	v_mul_f32_e32 v82, v75, v81
	v_mul_f32_e32 v85, 0.15915494, v82
	v_rndne_f32_e32 v85, v85
	v_fma_f32 v82, v82, 0.15915494, -v85
	v_sin_f32_e32 v87, v82
	v_cos_f32_e32 v89, v82
	v_mul_f32_e32 v82, v76, v81
	v_mul_f32_e32 v85, 0.15915494, v82
	v_rndne_f32_e32 v85, v85
	v_fma_f32 v82, v82, 0.15915494, -v85
	v_sin_f32_e32 v91, v82
	v_cos_f32_e32 v93, v82
	v_mul_f32_e32 v82, v77, v81
	v_mul_f32_e32 v85, 0.15915494, v82
	v_rndne_f32_e32 v85, v85
	v_fma_f32 v82, v82, 0.15915494, -v85
	v_sin_f32_e32 v94, v82
	v_cos_f32_e32 v96, v82
	v_mul_f32_e32 v82, v78, v81
	v_mul_f32_e32 v85, 0.15915494, v82
	v_rndne_f32_e32 v85, v85
	v_fma_f32 v85, v82, 0.15915494, -v85
	s_waitcnt lgkmcnt(0)
	v_add_f32_e32 v83, v83, v84
	v_sin_f32_e32 v82, v85
	v_cos_f32_e32 v98, v85
	v_mul_f32_e32 v85, v79, v81
	v_fmamk_f32 v83, v83, 0x3c000000, v196
	v_mul_f32_e32 v95, 0.15915494, v85
	v_mul_f32_e32 v84, 0x4b800000, v83
	v_cmp_gt_f32_e32 vcc, s78, v83
	v_rndne_f32_e32 v95, v95
	v_fma_f32 v85, v85, 0.15915494, -v95
	v_cndmask_b32_e32 v83, v83, v84, vcc
	v_mul_f32_e32 v81, v80, v81
	v_rsq_f32_e32 v84, v83
	v_sin_f32_e32 v95, v85
	v_cos_f32_e32 v97, v85
	v_mul_f32_e32 v85, 0.15915494, v81
	v_rndne_f32_e32 v85, v85
	v_fma_f32 v81, v81, 0.15915494, -v85
	v_sin_f32_e32 v83, v81
	v_cos_f32_e32 v99, v81
	v_mul_f32_e32 v81, 0x45800000, v84
	v_cndmask_b32_e32 v84, v84, v81, vcc
	v_pk_mul_f32 v[60:61], v[84:85], v[60:61] op_sel_hi:[0,1]
	v_pk_mul_f32 v[64:65], v[84:85], v[64:65] op_sel_hi:[0,1]
	v_pk_mul_f32 v[60:61], v[20:21], v[60:61]
	v_pk_mul_f32 v[42:43], v[84:85], v[42:43] op_sel_hi:[0,1]
	v_pk_mul_f32 v[64:65], v[16:17], v[64:65]
	v_pk_mul_f32 v[100:101], v[86:87], v[60:61]
	v_pk_mul_f32 v[62:63], v[84:85], v[62:63] op_sel_hi:[0,1]
	v_pk_mul_f32 v[42:43], v[48:49], v[42:43]
	v_pk_mul_f32 v[38:39], v[84:85], v[38:39] op_sel_hi:[0,1]
	v_pk_fma_f32 v[100:101], v[88:89], v[64:65], v[100:101]
	v_pk_mul_f32 v[62:63], v[10:11], v[62:63]
	v_pk_mul_f32 v[102:103], v[90:91], v[42:43]
	v_pk_mul_f32 v[64:65], v[86:87], v[64:65]
	v_pk_mul_f32 v[58:59], v[84:85], v[58:59] op_sel_hi:[0,1]
	v_pk_mul_f32 v[40:41], v[84:85], v[40:41] op_sel_hi:[0,1]
	v_pk_mul_f32 v[38:39], v[22:23], v[38:39]
	v_pk_fma_f32 v[102:103], v[92:93], v[62:63], v[102:103]
	v_pk_fma_f32 v[60:61], v[88:89], v[60:61], v[64:65] neg_lo:[0,0,1] neg_hi:[0,0,1]
	v_pk_mul_f32 v[62:63], v[90:91], v[62:63]
	v_pk_mul_f32 v[44:45], v[84:85], v[44:45] op_sel_hi:[0,1]
	v_pk_mul_f32 v[58:59], v[28:29], v[58:59]
	v_pk_mul_f32 v[40:41], v[18:19], v[40:41]
	v_pk_mul_f32 v[64:65], v[82:83], v[38:39]
	v_pk_fma_f32 v[42:43], v[92:93], v[42:43], v[62:63] neg_lo:[0,0,1] neg_hi:[0,0,1]
	v_pk_mul_f32 v[44:45], v[24:25], v[44:45]
	v_pk_mul_f32 v[62:63], v[94:95], v[58:59]
	v_pk_fma_f32 v[64:65], v[98:99], v[40:41], v[64:65]
	v_pk_mul_f32 v[40:41], v[82:83], v[40:41]
	v_pk_fma_f32 v[62:63], v[96:97], v[44:45], v[62:63]
	v_pk_mul_f32 v[44:45], v[94:95], v[44:45]
	v_pk_fma_f32 v[38:39], v[98:99], v[38:39], v[40:41] neg_lo:[0,0,1] neg_hi:[0,0,1]
	v_pk_fma_f32 v[44:45], v[96:97], v[58:59], v[44:45] neg_lo:[0,0,1] neg_hi:[0,0,1]
	v_bfe_u32 v40, v39, 16, 1
	v_bfe_u32 v41, v38, 16, 1
	v_bfe_u32 v58, v43, 16, 1
	v_bfe_u32 v59, v42, 16, 1
	v_add3_u32 v42, v42, v59, s79
	v_add3_u32 v43, v43, v58, s79
	v_add3_u32 v38, v38, v41, s79
	v_add3_u32 v39, v39, v40, s79
	v_bfe_u32 v40, v60, 16, 1
	v_bfe_u32 v41, v61, 16, 1
	v_bfe_u32 v58, v44, 16, 1
	v_bfe_u32 v59, v45, 16, 1
	v_add3_u32 v45, v45, v59, s79
	v_add3_u32 v44, v44, v58, s79
	v_add3_u32 v41, v61, v41, s79
	v_add3_u32 v40, v60, v40, s79
	v_lshrrev_b32_e32 v58, 16, v40
	v_lshrrev_b32_e32 v59, 16, v41
	v_lshrrev_b32_e32 v40, 16, v44
	v_lshrrev_b32_e32 v41, 16, v45
	v_bfe_u32 v44, v103, 16, 1
	v_bfe_u32 v45, v102, 16, 1
	v_and_or_b32 v41, v39, s75, v41
	v_and_or_b32 v40, v38, s75, v40
	v_and_or_b32 v39, v43, s75, v59
	v_and_or_b32 v38, v42, s75, v58
	v_add3_u32 v58, v102, v45, s79
	v_add3_u32 v59, v103, v44, s79
	v_bfe_u32 v44, v100, 16, 1
	v_bfe_u32 v45, v101, 16, 1
	v_bfe_u32 v60, v62, 16, 1
	v_bfe_u32 v61, v63, 16, 1
	v_bfe_u32 v42, v65, 16, 1
	v_bfe_u32 v43, v64, 16, 1
	v_add3_u32 v61, v63, v61, s79
	v_add3_u32 v60, v62, v60, s79
	v_add3_u32 v45, v101, v45, s79
	v_add3_u32 v44, v100, v44, s79
	v_add3_u32 v43, v64, v43, s79
	v_add3_u32 v42, v65, v42, s79
	v_lshrrev_b32_e32 v62, 16, v44
	v_lshrrev_b32_e32 v63, 16, v45
	v_lshrrev_b32_e32 v44, 16, v60
	v_lshrrev_b32_e32 v45, 16, v61
	v_and_or_b32 v45, v42, s75, v45
	v_and_or_b32 v44, v43, s75, v44
	v_and_or_b32 v43, v59, s75, v63
	v_and_or_b32 v42, v58, s75, v62
	global_store_dwordx4 v[54:55], v[38:41], off sc0 sc1
	global_store_dwordx4 v[56:57], v[42:45], off sc0 sc1
	s_branch .LBB0_568

; #define LAS __attribute__((address_space(3)))
; __device__ __forceinline__ unsigned pk2(float lo, float hi) { return f2bf(lo) | (f2bf(hi) << 16); }
; __device__ __forceinline__ void pass_post(const bf16* o16, const float* opart, const float* hlat, const float* hctx, const bf16* h16in, float* olat, float* octx, bf16* h16out, const float* gpost, const float* mod, int gt_off, ...
;     ...
;         for (int r = 0; r < 2; ++r) { const int m = mr[r]; if (r == 1 && !two) break;
;             float* hd = m < MLAT ? olat + (size_t)m * DM : octx + (size_t)(m - MLAT) * DM; const int vi = (m < MLAT ? (m >> 13) : 2); const LAS float* mv = lp + 4096 + 3 * vi * 2048;
;             const float rstd = rsqrtf(wave_sum(ss[r], lane) * (1.0f / DM) + EPS); float s2 = 0.f;
; #pragma unroll
;             for (int j = 0; j < 8; ++j) { const int ci = 256 * j + 4 * lane; const f32x4 g4 = *(const LAS f32x4*)(lp + ci), t4 = *(const LAS f32x4*)(mv + ci);
;                 const f32x4 nv = hh[r][j] + t4 * (v[r][j] * rstd * g4); v[r][j] = nv;
;                 if (h16out) { v2u w; w.x = pk2(nv[0], nv[1]); w.y = pk2(nv[2], nv[3]); *(v2u*)(h16out + (size_t)m * DM + ci) = w; } else *(f32x4*)(hd + ci) = nv;
;                 s2 += (nv[0] * nv[0] + nv[1] * nv[1]) + (nv[2] * nv[2] + nv[3] * nv[3]); }
;             if (U) { const float rstd2 = rsqrtf(wave_sum(s2, lane) * (1.0f / DM) + EPS); store_u(U + (size_t)m * DM, lane, v[r], rstd2, lp + 2048, mv + 2048, mv + 4096); }
;         }
.LBB0_969:
	v_mov_b32_e32 v130, v117
	v_mov_b32_e32 v131, v121
	v_mov_b32_e32 v128, v116
	v_mov_b32_e32 v129, v120
	v_pk_mul_f32 v[130:131], v[130:131], v[130:131]
	v_mov_b32_e32 v132, v119
	v_mov_b32_e32 v133, v123
	v_pk_fma_f32 v[128:129], v[128:129], v[128:129], v[130:131]
	v_mov_b32_e32 v130, v118
	v_mov_b32_e32 v131, v122
	v_pk_mul_f32 v[132:133], v[132:133], v[132:133]
	s_and_b64 s[6:7], exec, s[46:47]
	v_pk_fma_f32 v[130:131], v[130:131], v[130:131], v[132:133]
	v_pk_mul_f32 v[132:133], v[112:113], v[112:113]
	v_pk_add_f32 v[128:129], v[128:129], v[130:131]
	v_pk_mul_f32 v[130:131], v[114:115], v[114:115]
	v_pk_add_f32 v[128:129], v[128:129], v[128:129] op_sel_hi:[0,1]
	v_pk_mov_b32 v[134:135], v[132:133], v[130:131] op_sel:[1,0]
	v_mov_b32_e32 v133, v131
	v_mul_f32_e32 v128, v104, v104
	v_pk_add_f32 v[130:131], v[134:135], v[132:133]
	v_pk_fma_f32 v[132:133], v[104:105], v[104:105], v[128:129] op_sel_hi:[1,1,0]
	v_mul_f32_e32 v128, v106, v106
	v_pk_add_f32 v[130:131], v[130:131], v[130:131] op_sel_hi:[0,1]
	v_pk_fma_f32 v[134:135], v[106:107], v[106:107], v[128:129] op_sel_hi:[1,1,0]
	v_mul_f32_e32 v132, v108, v108
	v_mul_f32_e32 v134, v109, v109
	v_mul_f32_e32 v130, v110, v110
	v_mul_f32_e32 v128, v111, v111
	v_pk_add_f32 v[132:133], v[132:133], v[134:135]
	v_pk_add_f32 v[128:129], v[130:131], v[128:129]
	v_pk_mul_f32 v[130:131], v[98:99], v[98:99]
	v_pk_add_f32 v[128:129], v[132:133], v[128:129]
	v_pk_mul_f32 v[132:133], v[96:97], v[96:97]
	v_pk_add_f32 v[128:129], v[128:129], v[128:129] op_sel_hi:[0,1]
	v_pk_mov_b32 v[134:135], v[132:133], v[130:131] op_sel:[1,0]
	v_mov_b32_e32 v133, v131
	v_mul_f32_e32 v128, v100, v100
	v_pk_add_f32 v[130:131], v[134:135], v[132:133]
	v_pk_fma_f32 v[132:133], v[100:101], v[100:101], v[128:129] op_sel_hi:[1,1,0]
	v_mul_f32_e32 v128, v102, v102
	v_pk_add_f32 v[130:131], v[130:131], v[130:131] op_sel_hi:[0,1]
	v_pk_fma_f32 v[134:135], v[102:103], v[102:103], v[128:129] op_sel_hi:[1,1,0]
	v_mul_f32_e32 v132, v124, v124
	v_mul_f32_e32 v134, v125, v125
	v_mul_f32_e32 v130, v126, v126
	v_mul_f32_e32 v128, v127, v127
	v_pk_add_f32 v[132:133], v[132:133], v[134:135]
	v_pk_add_f32 v[128:129], v[130:131], v[128:129]
	s_cselect_b32 s7, s57, 0
	v_pk_add_f32 v[128:129], v[132:133], v[128:129]
	s_cselect_b32 s6, s56, s30
	v_add_f32_e32 v128, v128, v129
	ds_bpermute_b32 v129, v193, v128
	s_cselect_b32 s8, s17, s19
	s_cselect_b32 s9, s16, s18
	s_lshl_b64 s[6:7], s[6:7], 13
	s_add_u32 s6, s9, s6
	s_waitcnt lgkmcnt(0)
	v_add_f32_e32 v128, v128, v129
	ds_bpermute_b32 v129, v205, v128
	s_addc_u32 s7, s8, s7
	global_load_dwordx4 v[168:171], v194, s[6:7]
	global_load_dwordx4 v[164:167], v194, s[6:7] offset:1024
	global_load_dwordx4 v[152:155], v194, s[6:7] offset:2048
	global_load_dwordx4 v[148:151], v194, s[6:7] offset:3072
	s_waitcnt lgkmcnt(0)
	v_add_f32_e32 v130, v128, v129
	ds_bpermute_b32 v131, v207, v130
	v_lshl_add_u64 v[128:129], s[6:7], 0, v[194:195]
	s_movk_i32 s6, 0x1000
	v_add_co_u32_e32 v128, vcc, s6, v128
	s_waitcnt lgkmcnt(0)
	v_add_f32_e32 v130, v130, v131
	ds_bpermute_b32 v131, v209, v130
	v_addc_co_u32_e32 v129, vcc, 0, v129, vcc
	s_and_b64 s[6:7], s[54:55], exec
	s_cselect_b32 s5, s5, 0
	s_waitcnt lgkmcnt(0)
	v_add_f32_e32 v130, v130, v131
	ds_bpermute_b32 v131, v219, v130
	s_cselect_b32 s4, s4, s61
	s_min_i32 s6, s61, 0x4000
	s_lshr_b32 s6, s6, 13
	s_mulk_i32 s6, 0x6000
	s_waitcnt lgkmcnt(0)
	v_add_f32_e32 v194, v130, v131
	ds_bpermute_b32 v197, v220, v194
	v_add_u32_e32 v218, s6, v221
	global_load_dwordx4 v[140:143], v[128:129], off
	global_load_dwordx4 v[136:139], v[128:129], off offset:1024
	global_load_dwordx4 v[132:135], v[128:129], off offset:2048
	ds_read_b128 v[222:225], v218 offset:16384
	s_lshl_b64 s[54:55], s[4:5], 12
	s_waitcnt lgkmcnt(1)
	v_add_f32_e32 v194, v194, v197
	v_fmamk_f32 v194, v194, 0x3a000000, v196
	v_cmp_gt_f32_e32 vcc, s78, v194
	v_mul_f32_e32 v197, 0x4b800000, v194
	global_load_dwordx4 v[128:131], v[128:129], off offset:3072
	v_cndmask_b32_e32 v194, v194, v197, vcc
	v_rsq_f32_e32 v194, v194
	s_nop 0
	v_mul_f32_e32 v197, 0x45800000, v194
	v_cndmask_b32_e32 v194, v194, v197, vcc
	v_pk_mul_f32 v[120:121], v[120:121], v[194:195] op_sel_hi:[1,0]
	v_pk_mul_f32 v[122:123], v[122:123], v[194:195] op_sel_hi:[1,0]
	v_pk_mul_f32 v[226:227], v[0:1], v[120:121]
	v_pk_mul_f32 v[120:121], v[2:3], v[122:123]
	s_waitcnt vmcnt(15) lgkmcnt(0)
	v_pk_fma_f32 v[122:123], v[222:223], v[226:227], v[188:189]
	v_pk_fma_f32 v[120:121], v[224:225], v[120:121], v[190:191]
	v_bfe_u32 v188, v122, 16, 1
	v_add3_u32 v188, v122, v188, s79
	v_bfe_u32 v189, v123, 16, 1
	v_lshrrev_b32_e32 v188, 16, v188
	v_add3_u32 v189, v123, v189, s79
	v_and_or_b32 v190, v189, s75, v188
	v_bfe_u32 v188, v120, 16, 1
	ds_read_b128 v[222:225], v218 offset:17408
	v_add3_u32 v188, v120, v188, s79
	v_bfe_u32 v189, v121, 16, 1
	v_lshrrev_b32_e32 v188, 16, v188
	v_add3_u32 v189, v121, v189, s79
	v_and_or_b32 v191, v189, s75, v188
	v_lshl_add_u64 v[188:189], v[212:213], 0, s[54:55]
	v_pk_mul_f32 v[116:117], v[116:117], v[194:195] op_sel_hi:[1,0]
	global_store_dwordx2 v[188:189], v[190:191], off sc0 sc1
	v_pk_mul_f32 v[118:119], v[118:119], v[194:195] op_sel_hi:[1,0]
	v_pk_mul_f32 v[190:191], v[4:5], v[116:117]
	v_pk_mul_f32 v[116:117], v[6:7], v[118:119]
	s_waitcnt vmcnt(15) lgkmcnt(0)
; #define LAS __attribute__((address_space(3)))
; __device__ __forceinline__ unsigned pk2(float lo, float hi) { return f2bf(lo) | (f2bf(hi) << 16); }
; __device__ __forceinline__ void pass_post(const bf16* o16, const float* opart, const float* hlat, const float* hctx, const bf16* h16in, float* olat, float* octx, bf16* h16out, const float* gpost, const float* mod, int gt_off, ...
;     ...
;             const float rstd = rsqrtf(wave_sum(ss[r], lane) * (1.0f / DM) + EPS); float s2 = 0.f;
; #pragma unroll
;             for (int j = 0; j < 8; ++j) { const int ci = 256 * j + 4 * lane; const f32x4 g4 = *(const LAS f32x4*)(lp + ci), t4 = *(const LAS f32x4*)(mv + ci);
;                 const f32x4 nv = hh[r][j] + t4 * (v[r][j] * rstd * g4); v[r][j] = nv;
;                 if (h16out) { v2u w; w.x = pk2(nv[0], nv[1]); w.y = pk2(nv[2], nv[3]); *(v2u*)(h16out + (size_t)m * DM + ci) = w; } else *(f32x4*)(hd + ci) = nv;
;                 s2 += (nv[0] * nv[0] + nv[1] * nv[1]) + (nv[2] * nv[2] + nv[3] * nv[3]); }
;             if (U) { const float rstd2 = rsqrtf(wave_sum(s2, lane) * (1.0f / DM) + EPS); store_u(U + (size_t)m * DM, lane, v[r], rstd2, lp + 2048, mv + 2048, mv + 4096); }
	v_pk_fma_f32 v[118:119], v[222:223], v[190:191], v[184:185]
	v_pk_fma_f32 v[116:117], v[224:225], v[116:117], v[186:187]
	v_bfe_u32 v184, v118, 16, 1
	v_add3_u32 v184, v118, v184, s79
	v_bfe_u32 v185, v119, 16, 1
	v_lshrrev_b32_e32 v184, 16, v184
	v_add3_u32 v185, v119, v185, s79
	v_and_or_b32 v184, v185, s75, v184
	v_bfe_u32 v185, v116, 16, 1
	v_add3_u32 v185, v116, v185, s79
	v_bfe_u32 v186, v117, 16, 1
	v_lshrrev_b32_e32 v185, 16, v185
	v_add3_u32 v186, v117, v186, s79
	v_and_or_b32 v185, v186, s75, v185
	v_mov_b32_e32 v186, v123
	v_mov_b32_e32 v187, v119
	global_store_dwordx2 v[188:189], v[184:185], off offset:512 sc0 sc1
	v_mov_b32_e32 v184, v122
	v_mov_b32_e32 v185, v118
	v_pk_mul_f32 v[186:187], v[186:187], v[186:187]
	v_mov_b32_e32 v190, v121
	v_mov_b32_e32 v191, v117
	v_pk_fma_f32 v[184:185], v[184:185], v[184:185], v[186:187]
	v_mov_b32_e32 v186, v120
	v_mov_b32_e32 v187, v116
	v_pk_mul_f32 v[190:191], v[190:191], v[190:191]
	v_pk_mul_f32 v[112:113], v[112:113], v[194:195] op_sel_hi:[1,0]
	v_pk_fma_f32 v[186:187], v[186:187], v[186:187], v[190:191]
	v_pk_mul_f32 v[114:115], v[114:115], v[194:195] op_sel_hi:[1,0]
	v_pk_add_f32 v[184:185], v[184:185], v[186:187]
	v_pk_mul_f32 v[222:223], v[8:9], v[112:113]
	v_pk_add_f32 v[190:191], v[184:185], v[184:185] op_sel_hi:[0,1]
	ds_read_b128 v[184:187], v218 offset:18432
	v_pk_mul_f32 v[112:113], v[10:11], v[114:115]
	v_pk_mul_f32 v[104:105], v[104:105], v[194:195] op_sel_hi:[1,0]
	v_pk_mul_f32 v[106:107], v[106:107], v[194:195] op_sel_hi:[1,0]
	v_pk_mul_f32 v[108:109], v[108:109], v[194:195] op_sel_hi:[1,0]
	s_waitcnt vmcnt(15) lgkmcnt(0)
	v_pk_fma_f32 v[114:115], v[184:185], v[222:223], v[180:181]
	v_pk_fma_f32 v[112:113], v[186:187], v[112:113], v[182:183]
	v_bfe_u32 v180, v114, 16, 1
	v_add3_u32 v180, v114, v180, s79
	v_bfe_u32 v181, v115, 16, 1
	v_lshrrev_b32_e32 v180, 16, v180
	v_add3_u32 v181, v115, v181, s79
	v_and_or_b32 v180, v181, s75, v180
	v_bfe_u32 v181, v112, 16, 1
	v_add3_u32 v181, v112, v181, s79
	v_bfe_u32 v182, v113, 16, 1
	v_lshrrev_b32_e32 v181, 16, v181
	v_add3_u32 v182, v113, v182, s79
	v_and_or_b32 v181, v182, s75, v181
	global_store_dwordx2 v[188:189], v[180:181], off offset:1024 sc0 sc1
	v_pk_mul_f32 v[180:181], v[112:113], v[112:113]
	v_pk_mul_f32 v[182:183], v[114:115], v[114:115]
	v_pk_mul_f32 v[186:187], v[12:13], v[104:105]
	v_pk_mov_b32 v[184:185], v[182:183], v[180:181] op_sel:[1,0]
	v_mov_b32_e32 v183, v181
	v_pk_add_f32 v[180:181], v[184:185], v[182:183]
	v_pk_mul_f32 v[104:105], v[14:15], v[106:107]
	v_pk_add_f32 v[184:185], v[180:181], v[180:181] op_sel_hi:[0,1]
	ds_read_b128 v[180:183], v218 offset:19456
	v_pk_mul_f32 v[110:111], v[110:111], v[194:195] op_sel_hi:[1,0]
	v_pk_mul_f32 v[96:97], v[96:97], v[194:195] op_sel_hi:[1,0]
	v_pk_mul_f32 v[98:99], v[98:99], v[194:195] op_sel_hi:[1,0]
	v_pk_mul_f32 v[96:97], v[96:97], v[20:21]
	s_waitcnt vmcnt(15) lgkmcnt(0)
	v_pk_fma_f32 v[106:107], v[180:181], v[186:187], v[176:177]
	v_pk_fma_f32 v[104:105], v[182:183], v[104:105], v[178:179]
	v_bfe_u32 v176, v106, 16, 1
	v_add3_u32 v176, v106, v176, s79
	v_bfe_u32 v177, v107, 16, 1
	v_lshrrev_b32_e32 v176, 16, v176
	v_add3_u32 v177, v107, v177, s79
	v_and_or_b32 v176, v177, s75, v176
	v_bfe_u32 v177, v104, 16, 1
	v_add3_u32 v177, v104, v177, s79
	v_bfe_u32 v178, v105, 16, 1
	v_lshrrev_b32_e32 v177, 16, v177
	v_add3_u32 v178, v105, v178, s79
	v_and_or_b32 v177, v178, s75, v177
	global_store_dwordx2 v[188:189], v[176:177], off offset:1536 sc0 sc1
	v_mul_f32_e32 v176, v106, v106
	v_pk_fma_f32 v[180:181], v[106:107], v[106:107], v[176:177] op_sel_hi:[1,1,0]
	v_mul_f32_e32 v176, v104, v104
	v_pk_fma_f32 v[182:183], v[104:105], v[104:105], v[176:177] op_sel_hi:[1,1,0]
	ds_read_b128 v[176:179], v218 offset:20480
	v_pk_mul_f32 v[186:187], v[108:109], v[16:17]
	v_pk_mul_f32 v[108:109], v[110:111], v[18:19]
	v_pk_mul_f32 v[98:99], v[98:99], v[22:23]
	v_pk_mul_f32 v[102:103], v[102:103], v[194:195] op_sel_hi:[1,0]
	s_waitcnt vmcnt(15) lgkmcnt(0)
	v_pk_fma_f32 v[110:111], v[176:177], v[186:187], v[172:173]
	v_pk_fma_f32 v[108:109], v[178:179], v[108:109], v[174:175]
	v_bfe_u32 v172, v110, 16, 1
	v_add3_u32 v172, v110, v172, s79
	v_bfe_u32 v173, v111, 16, 1
	v_lshrrev_b32_e32 v172, 16, v172
	v_add3_u32 v173, v111, v173, s79
	v_and_or_b32 v172, v173, s75, v172
	v_bfe_u32 v173, v108, 16, 1
	v_add3_u32 v173, v108, v173, s79
	v_bfe_u32 v174, v109, 16, 1
	v_lshrrev_b32_e32 v173, 16, v173
	v_add3_u32 v174, v109, v174, s79
	v_and_or_b32 v173, v174, s75, v173
	v_mul_f32_e32 v180, v110, v110
	v_mul_f32_e32 v182, v111, v111
	v_mul_f32_e32 v184, v108, v108
	v_mul_f32_e32 v190, v109, v109
	global_store_dwordx2 v[188:189], v[172:173], off offset:2048 sc0 sc1
	v_pk_add_f32 v[172:173], v[180:181], v[182:183]
	v_pk_add_f32 v[174:175], v[184:185], v[190:191]
	v_pk_mul_f32 v[100:101], v[100:101], v[194:195] op_sel_hi:[1,0]
	v_pk_add_f32 v[172:173], v[172:173], v[174:175]
	ds_read_b128 v[174:177], v218 offset:21504
	v_pk_mul_f32 v[178:179], v[100:101], v[24:25]
	v_pk_mul_f32 v[100:101], v[102:103], v[26:27]
	s_waitcnt vmcnt(15) lgkmcnt(0)
	v_pk_fma_f32 v[160:161], v[174:175], v[96:97], v[160:161]
	s_nop 0
	v_bfe_u32 v96, v160, 16, 1
	v_add3_u32 v96, v160, v96, s79
	v_bfe_u32 v97, v161, 16, 1
	v_pk_fma_f32 v[162:163], v[176:177], v[98:99], v[162:163]
	v_lshrrev_b32_e32 v96, 16, v96
	v_add3_u32 v97, v161, v97, s79
	v_and_or_b32 v174, v97, s75, v96
	v_bfe_u32 v96, v162, 16, 1
	v_add3_u32 v96, v162, v96, s79
	v_bfe_u32 v97, v163, 16, 1
	v_lshrrev_b32_e32 v96, 16, v96
	v_add3_u32 v97, v163, v97, s79
	v_and_or_b32 v175, v97, s75, v96
	v_pk_mul_f32 v[96:97], v[160:161], v[160:161]
	v_pk_mul_f32 v[98:99], v[162:163], v[162:163]
	global_store_dwordx2 v[188:189], v[174:175], off offset:2560 sc0 sc1
	v_pk_mov_b32 v[176:177], v[96:97], v[98:99] op_sel:[1,0]
	v_mov_b32_e32 v97, v99
	v_pk_add_f32 v[176:177], v[176:177], v[96:97]
	ds_read_b128 v[96:99], v218 offset:22528
	s_waitcnt vmcnt(15) lgkmcnt(0)
; #define LAS __attribute__((address_space(3)))
; __device__ __forceinline__ unsigned pk2(float lo, float hi) { return f2bf(lo) | (f2bf(hi) << 16); }
; __device__ __forceinline__ void store_u(bf16* urow, int lane, const f32x4 (&v)[8], float rstd, const LAS float* g, const LAS float* sh, const LAS float* sc) {
; #pragma unroll
;     for (int j = 0; j < 8; ++j) { const int ci = 256 * j + 4 * lane; const f32x4 g4 = *(const LAS f32x4*)(g + ci), s4 = *(const LAS f32x4*)(sc + ci), h4 = *(const LAS f32x4*)(sh + ci);
;         const f32x4 t = (v[j] * rstd * g4) * (1.0f + s4) + h4; v2u w; w.x = pk2(t[0], t[1]); w.y = pk2(t[2], t[3]); *(v2u*)(urow + ci) = w; }
; }
; __device__ __forceinline__ void pass_post(const bf16* o16, const float* opart, const float* hlat, const float* hctx, const bf16* h16in, float* olat, float* octx, bf16* h16out, const float* gpost, const float* mod, int gt_off, ...
;     ...
;             const float rstd = rsqrtf(wave_sum(ss[r], lane) * (1.0f / DM) + EPS); float s2 = 0.f;
; #pragma unroll
;             for (int j = 0; j < 8; ++j) { const int ci = 256 * j + 4 * lane; const f32x4 g4 = *(const LAS f32x4*)(lp + ci), t4 = *(const LAS f32x4*)(mv + ci);
;                 const f32x4 nv = hh[r][j] + t4 * (v[r][j] * rstd * g4); v[r][j] = nv;
;                 if (h16out) { v2u w; w.x = pk2(nv[0], nv[1]); w.y = pk2(nv[2], nv[3]); *(v2u*)(h16out + (size_t)m * DM + ci) = w; } else *(f32x4*)(hd + ci) = nv;
;                 s2 += (nv[0] * nv[0] + nv[1] * nv[1]) + (nv[2] * nv[2] + nv[3] * nv[3]); }
;             if (U) { const float rstd2 = rsqrtf(wave_sum(s2, lane) * (1.0f / DM) + EPS); store_u(U + (size_t)m * DM, lane, v[r], rstd2, lp + 2048, mv + 2048, mv + 4096); }
;         }
	v_pk_fma_f32 v[100:101], v[98:99], v[100:101], v[158:159]
	v_pk_fma_f32 v[102:103], v[96:97], v[178:179], v[156:157]
	ds_read_b128 v[156:159], v218 offset:23552
	v_pk_mul_f32 v[98:99], v[124:125], v[194:195] op_sel_hi:[1,0]
	v_pk_mul_f32 v[96:97], v[126:127], v[194:195] op_sel_hi:[1,0]
	v_pk_mul_f32 v[98:99], v[98:99], v[28:29]
	v_pk_add_f32 v[124:125], v[172:173], v[172:173] op_sel:[0,1] op_sel_hi:[1,0]
	s_waitcnt vmcnt(14) lgkmcnt(0)
	v_pk_fma_f32 v[98:99], v[156:157], v[98:99], v[144:145]
	v_pk_mul_f32 v[96:97], v[96:97], v[30:31]
	v_mul_f32_e32 v126, v98, v98
	v_mul_f32_e32 v144, v99, v99
	v_mov_b32_e32 v125, v126
	v_pk_add_f32 v[126:127], v[176:177], v[176:177] op_sel:[0,1] op_sel_hi:[1,0]
	v_pk_fma_f32 v[96:97], v[158:159], v[96:97], v[146:147]
	v_mov_b32_e32 v127, v144
	v_pk_add_f32 v[124:125], v[124:125], v[126:127]
	v_mul_f32_e32 v126, v103, v103
	v_mul_f32_e32 v145, v96, v96
	v_pk_fma_f32 v[126:127], v[102:103], v[102:103], v[126:127] op_sel_hi:[1,1,0]
	v_mul_f32_e32 v144, v101, v101
	v_mul_f32_e32 v146, v97, v97
	v_mov_b32_e32 v127, v145
	v_pk_fma_f32 v[144:145], v[100:101], v[100:101], v[144:145] op_sel_hi:[1,1,0]
	s_nop 0
	v_mov_b32_e32 v145, v146
	v_pk_add_f32 v[126:127], v[126:127], v[144:145]
	v_bfe_u32 v144, v101, 16, 1
	v_pk_add_f32 v[124:125], v[124:125], v[126:127]
	v_bfe_u32 v126, v102, 16, 1
	v_add_f32_e32 v124, v124, v125
	ds_bpermute_b32 v125, v193, v124
	v_add3_u32 v126, v102, v126, s79
	v_lshrrev_b32_e32 v126, 16, v126
	v_add3_u32 v144, v101, v144, s79
	s_waitcnt lgkmcnt(0)
	v_add_f32_e32 v125, v124, v125
	ds_bpermute_b32 v127, v205, v125
	v_bfe_u32 v124, v103, 16, 1
	v_add3_u32 v124, v103, v124, s79
	v_and_or_b32 v124, v124, s75, v126
	v_bfe_u32 v126, v100, 16, 1
	s_waitcnt lgkmcnt(0)
	v_add_f32_e32 v125, v125, v127
	ds_bpermute_b32 v127, v207, v125
	v_add3_u32 v126, v100, v126, s79
	v_lshrrev_b32_e32 v126, 16, v126
	s_waitcnt lgkmcnt(0)
	v_add_f32_e32 v127, v125, v127
	ds_bpermute_b32 v145, v209, v127
	v_and_or_b32 v125, v144, s75, v126
	global_store_dwordx2 v[188:189], v[124:125], off offset:3072 sc0 sc1
	v_bfe_u32 v124, v98, 16, 1
	v_add3_u32 v124, v98, v124, s79
	s_waitcnt lgkmcnt(0)
	v_add_f32_e32 v125, v127, v145
	ds_bpermute_b32 v126, v219, v125
	v_bfe_u32 v127, v99, 16, 1
	v_lshrrev_b32_e32 v124, 16, v124
	v_add3_u32 v127, v99, v127, s79
	v_and_or_b32 v124, v127, s75, v124
	s_waitcnt lgkmcnt(0)
	v_add_f32_e32 v125, v125, v126
	ds_bpermute_b32 v126, v220, v125
	v_bfe_u32 v127, v96, 16, 1
	v_add3_u32 v127, v96, v127, s79
	v_bfe_u32 v144, v97, 16, 1
	v_lshrrev_b32_e32 v127, 16, v127
	s_waitcnt lgkmcnt(0)
	v_add_f32_e32 v125, v125, v126
	v_fmamk_f32 v125, v125, 0x3a000000, v196
	v_cmp_gt_f32_e32 vcc, s78, v125
	v_mul_f32_e32 v126, 0x4b800000, v125
	s_nop 0
	v_cndmask_b32_e32 v125, v125, v126, vcc
	v_rsq_f32_e32 v126, v125
	v_add3_u32 v125, v97, v144, s79
	v_and_or_b32 v125, v125, s75, v127
	global_store_dwordx2 v[188:189], v[124:125], off offset:3584 sc0 sc1
	ds_read_b128 v[144:147], v218 offset:32768
	ds_read_b128 v[156:159], v218 offset:24576
	v_mul_f32_e32 v124, 0x45800000, v126
	v_cndmask_b32_e32 v124, v126, v124, vcc
	v_pk_mul_f32 v[122:123], v[122:123], v[124:125] op_sel_hi:[1,0]
	s_waitcnt lgkmcnt(1)
	v_pk_add_f32 v[144:145], v[144:145], 1.0 op_sel_hi:[1,0]
	v_pk_mul_f32 v[122:123], v[32:33], v[122:123]
	v_pk_mul_f32 v[120:121], v[120:121], v[124:125] op_sel_hi:[1,0]
	s_waitcnt lgkmcnt(0)
	v_pk_fma_f32 v[122:123], v[144:145], v[122:123], v[156:157]
	v_pk_mul_f32 v[120:121], v[34:35], v[120:121]
	v_bfe_u32 v125, v122, 16, 1
	v_pk_add_f32 v[126:127], v[146:147], 1.0 op_sel_hi:[1,0]
	v_add3_u32 v122, v122, v125, s79
	v_bfe_u32 v125, v123, 16, 1
	v_pk_fma_f32 v[120:121], v[126:127], v[120:121], v[158:159]
	v_lshrrev_b32_e32 v122, 16, v122
	v_add3_u32 v123, v123, v125, s79
	v_and_or_b32 v122, v123, s75, v122
	v_bfe_u32 v123, v120, 16, 1
	v_add3_u32 v120, v120, v123, s79
	v_bfe_u32 v123, v121, 16, 1
	v_lshrrev_b32_e32 v120, 16, v120
	v_add3_u32 v121, v121, v123, s79
	v_and_or_b32 v123, v121, s75, v120
	v_lshl_add_u64 v[120:121], v[214:215], 0, s[54:55]
	global_store_dwordx2 v[120:121], v[122:123], off sc0 sc1
	ds_read_b128 v[144:147], v218 offset:33792
	ds_read_b128 v[156:159], v218 offset:25600
	v_pk_mul_f32 v[118:119], v[118:119], v[124:125] op_sel_hi:[1,0]
	v_pk_mul_f32 v[116:117], v[116:117], v[124:125] op_sel_hi:[1,0]
	v_pk_mul_f32 v[118:119], v[36:37], v[118:119]
	s_waitcnt lgkmcnt(1)
	v_pk_add_f32 v[126:127], v[144:145], 1.0 op_sel_hi:[1,0]
	v_pk_mul_f32 v[116:117], v[38:39], v[116:117]
	v_pk_add_f32 v[122:123], v[146:147], 1.0 op_sel_hi:[1,0]
	s_waitcnt lgkmcnt(0)
	v_pk_fma_f32 v[118:119], v[126:127], v[118:119], v[156:157]
	v_pk_fma_f32 v[116:117], v[122:123], v[116:117], v[158:159]
	v_bfe_u32 v122, v118, 16, 1
	v_add3_u32 v118, v118, v122, s79
	v_bfe_u32 v122, v119, 16, 1
	v_lshrrev_b32_e32 v118, 16, v118
	v_add3_u32 v119, v119, v122, s79
	v_and_or_b32 v118, v119, s75, v118
	v_bfe_u32 v119, v116, 16, 1
	v_add3_u32 v116, v116, v119, s79
	v_bfe_u32 v119, v117, 16, 1
	v_lshrrev_b32_e32 v116, 16, v116
	v_add3_u32 v117, v117, v119, s79
	v_and_or_b32 v119, v117, s75, v116
	global_store_dwordx2 v[120:121], v[118:119], off offset:512 sc0 sc1
	ds_read_b128 v[116:119], v218 offset:34816
	ds_read_b128 v[144:147], v218 offset:26624
	v_pk_mul_f32 v[114:115], v[114:115], v[124:125] op_sel_hi:[1,0]
	v_pk_mul_f32 v[112:113], v[112:113], v[124:125] op_sel_hi:[1,0]
	v_pk_mul_f32 v[114:115], v[40:41], v[114:115]
	s_waitcnt lgkmcnt(1)
	v_pk_add_f32 v[116:117], v[116:117], 1.0 op_sel_hi:[1,0]
	v_pk_mul_f32 v[112:113], v[42:43], v[112:113]
	s_waitcnt lgkmcnt(0)
; #define LAS __attribute__((address_space(3)))
; __device__ __forceinline__ unsigned pk2(float lo, float hi) { return f2bf(lo) | (f2bf(hi) << 16); }
; __device__ __forceinline__ void store_u(bf16* urow, int lane, const f32x4 (&v)[8], float rstd, const LAS float* g, const LAS float* sh, const LAS float* sc) {
; #pragma unroll
;     for (int j = 0; j < 8; ++j) { const int ci = 256 * j + 4 * lane; const f32x4 g4 = *(const LAS f32x4*)(g + ci), s4 = *(const LAS f32x4*)(sc + ci), h4 = *(const LAS f32x4*)(sh + ci);
;         const f32x4 t = (v[j] * rstd * g4) * (1.0f + s4) + h4; v2u w; w.x = pk2(t[0], t[1]); w.y = pk2(t[2], t[3]); *(v2u*)(urow + ci) = w; }
; }
	v_pk_fma_f32 v[114:115], v[116:117], v[114:115], v[144:145]
	v_pk_add_f32 v[118:119], v[118:119], 1.0 op_sel_hi:[1,0]
	v_bfe_u32 v116, v114, 16, 1
	v_add3_u32 v114, v114, v116, s79
	v_bfe_u32 v116, v115, 16, 1
	v_pk_fma_f32 v[112:113], v[118:119], v[112:113], v[146:147]
	v_lshrrev_b32_e32 v114, 16, v114
	v_add3_u32 v115, v115, v116, s79
	v_and_or_b32 v114, v115, s75, v114
	v_bfe_u32 v115, v112, 16, 1
	v_add3_u32 v112, v112, v115, s79
	v_bfe_u32 v115, v113, 16, 1
	v_lshrrev_b32_e32 v112, 16, v112
	v_add3_u32 v113, v113, v115, s79
	v_and_or_b32 v115, v113, s75, v112
	global_store_dwordx2 v[120:121], v[114:115], off offset:1024 sc0 sc1
	ds_read_b128 v[112:115], v218 offset:35840
	ds_read_b128 v[116:119], v218 offset:27648
	v_pk_mul_f32 v[106:107], v[106:107], v[124:125] op_sel_hi:[1,0]
	v_pk_mul_f32 v[104:105], v[104:105], v[124:125] op_sel_hi:[1,0]
	v_pk_mul_f32 v[106:107], v[44:45], v[106:107]
	s_waitcnt lgkmcnt(1)
	v_pk_add_f32 v[112:113], v[112:113], 1.0 op_sel_hi:[1,0]
	v_pk_mul_f32 v[104:105], v[46:47], v[104:105]
	s_waitcnt lgkmcnt(0)
	v_pk_fma_f32 v[106:107], v[112:113], v[106:107], v[116:117]
	v_pk_add_f32 v[114:115], v[114:115], 1.0 op_sel_hi:[1,0]
	v_bfe_u32 v112, v106, 16, 1
	v_add3_u32 v106, v106, v112, s79
	v_bfe_u32 v112, v107, 16, 1
	v_pk_fma_f32 v[104:105], v[114:115], v[104:105], v[118:119]
	v_lshrrev_b32_e32 v106, 16, v106
	v_add3_u32 v107, v107, v112, s79
	v_and_or_b32 v106, v107, s75, v106
	v_bfe_u32 v107, v104, 16, 1
	v_add3_u32 v104, v104, v107, s79
	v_bfe_u32 v107, v105, 16, 1
	v_lshrrev_b32_e32 v104, 16, v104
	v_add3_u32 v105, v105, v107, s79
	v_and_or_b32 v107, v105, s75, v104
	global_store_dwordx2 v[120:121], v[106:107], off offset:1536 sc0 sc1
	ds_read_b128 v[104:107], v218 offset:36864
	ds_read_b128 v[112:115], v218 offset:28672
	v_pk_mul_f32 v[110:111], v[110:111], v[124:125] op_sel_hi:[1,0]
	v_pk_mul_f32 v[108:109], v[108:109], v[124:125] op_sel_hi:[1,0]
	v_pk_mul_f32 v[110:111], v[110:111], v[48:49]
	s_waitcnt lgkmcnt(1)
	v_pk_add_f32 v[104:105], v[104:105], 1.0 op_sel_hi:[1,0]
	v_pk_mul_f32 v[108:109], v[108:109], v[50:51]
	v_pk_add_f32 v[106:107], v[106:107], 1.0 op_sel_hi:[1,0]
	s_waitcnt lgkmcnt(0)
	v_pk_fma_f32 v[104:105], v[110:111], v[104:105], v[112:113]
	v_pk_fma_f32 v[106:107], v[108:109], v[106:107], v[114:115]
	v_bfe_u32 v108, v104, 16, 1
	v_add3_u32 v104, v104, v108, s79
	v_bfe_u32 v108, v105, 16, 1
	v_lshrrev_b32_e32 v104, 16, v104
	v_add3_u32 v105, v105, v108, s79
	v_and_or_b32 v104, v105, s75, v104
	v_bfe_u32 v105, v106, 16, 1
	v_add3_u32 v105, v106, v105, s79
	v_bfe_u32 v106, v107, 16, 1
	v_lshrrev_b32_e32 v105, 16, v105
	v_add3_u32 v106, v107, v106, s79
	v_and_or_b32 v105, v106, s75, v105
	global_store_dwordx2 v[120:121], v[104:105], off offset:2048 sc0 sc1
	ds_read_b128 v[104:107], v218 offset:37888
	ds_read_b128 v[108:111], v218 offset:29696
	v_pk_mul_f32 v[114:115], v[160:161], v[124:125] op_sel_hi:[1,0]
	v_pk_mul_f32 v[112:113], v[162:163], v[124:125] op_sel_hi:[1,0]
	v_pk_mul_f32 v[114:115], v[114:115], v[52:53]
	s_waitcnt lgkmcnt(1)
	v_pk_add_f32 v[104:105], v[104:105], 1.0 op_sel_hi:[1,0]
	v_pk_mul_f32 v[112:113], v[112:113], v[54:55]
	s_waitcnt lgkmcnt(0)
	v_pk_fma_f32 v[104:105], v[114:115], v[104:105], v[108:109]
	v_pk_add_f32 v[106:107], v[106:107], 1.0 op_sel_hi:[1,0]
	v_bfe_u32 v108, v104, 16, 1
	v_add3_u32 v104, v104, v108, s79
	v_bfe_u32 v108, v105, 16, 1
	v_pk_fma_f32 v[106:107], v[112:113], v[106:107], v[110:111]
	v_lshrrev_b32_e32 v104, 16, v104
	v_add3_u32 v105, v105, v108, s79
	v_and_or_b32 v104, v105, s75, v104
	v_bfe_u32 v105, v106, 16, 1
	v_add3_u32 v105, v106, v105, s79
	v_bfe_u32 v106, v107, 16, 1
	v_lshrrev_b32_e32 v105, 16, v105
	v_add3_u32 v106, v107, v106, s79
	v_and_or_b32 v105, v106, s75, v105
	global_store_dwordx2 v[120:121], v[104:105], off offset:2560 sc0 sc1
	ds_read_b128 v[104:107], v218 offset:38912
	ds_read_b128 v[108:111], v218 offset:30720
	v_pk_mul_f32 v[102:103], v[102:103], v[124:125] op_sel_hi:[1,0]
	v_pk_mul_f32 v[100:101], v[100:101], v[124:125] op_sel_hi:[1,0]
	v_pk_mul_f32 v[102:103], v[102:103], v[56:57]
	s_waitcnt lgkmcnt(1)
	v_pk_add_f32 v[104:105], v[104:105], 1.0 op_sel_hi:[1,0]
	v_pk_mul_f32 v[100:101], v[100:101], v[58:59]
	s_waitcnt lgkmcnt(0)
	v_pk_fma_f32 v[102:103], v[102:103], v[104:105], v[108:109]
	v_pk_add_f32 v[106:107], v[106:107], 1.0 op_sel_hi:[1,0]
	v_bfe_u32 v104, v102, 16, 1
	v_add3_u32 v102, v102, v104, s79
	v_bfe_u32 v104, v103, 16, 1
	v_pk_fma_f32 v[100:101], v[100:101], v[106:107], v[110:111]
	v_lshrrev_b32_e32 v102, 16, v102
	v_add3_u32 v103, v103, v104, s79
	v_and_or_b32 v102, v103, s75, v102
	v_bfe_u32 v103, v100, 16, 1
	v_add3_u32 v100, v100, v103, s79
	v_bfe_u32 v103, v101, 16, 1
	v_lshrrev_b32_e32 v100, 16, v100
	v_add3_u32 v101, v101, v103, s79
	v_and_or_b32 v103, v101, s75, v100
	global_store_dwordx2 v[120:121], v[102:103], off offset:3072 sc0 sc1
	ds_read_b128 v[100:103], v218 offset:39936
	ds_read_b128 v[104:107], v218 offset:31744
	v_pk_mul_f32 v[98:99], v[98:99], v[124:125] op_sel_hi:[1,0]
	v_pk_mul_f32 v[96:97], v[96:97], v[124:125] op_sel_hi:[1,0]
	v_pk_mul_f32 v[98:99], v[98:99], v[60:61]
	s_waitcnt lgkmcnt(1)
	v_pk_add_f32 v[100:101], v[100:101], 1.0 op_sel_hi:[1,0]
	v_pk_mul_f32 v[96:97], v[96:97], v[62:63]
	s_waitcnt lgkmcnt(0)
	v_pk_fma_f32 v[98:99], v[98:99], v[100:101], v[104:105]
	v_pk_add_f32 v[102:103], v[102:103], 1.0 op_sel_hi:[1,0]
	v_bfe_u32 v100, v98, 16, 1
	v_add3_u32 v98, v98, v100, s79
	v_bfe_u32 v100, v99, 16, 1
	v_pk_fma_f32 v[96:97], v[96:97], v[102:103], v[106:107]
	v_lshrrev_b32_e32 v98, 16, v98
	v_add3_u32 v99, v99, v100, s79
	v_and_or_b32 v98, v99, s75, v98
	v_bfe_u32 v99, v96, 16, 1
	v_add3_u32 v96, v96, v99, s79
	v_bfe_u32 v99, v97, 16, 1
	v_lshrrev_b32_e32 v96, 16, v96
	v_add3_u32 v97, v97, v99, s79
	v_and_or_b32 v99, v97, s75, v96
	s_andn2_b64 vcc, exec, s[52:53]
	global_store_dwordx2 v[120:121], v[98:99], off offset:3584 sc0 sc1
	s_cbranch_vccnz .LBB0_960
; #define LAS __attribute__((address_space(3)))
; __device__ __forceinline__ unsigned pk2(float lo, float hi) { return f2bf(lo) | (f2bf(hi) << 16); }
; __device__ __forceinline__ void pass_post(const bf16* o16, const float* opart, const float* hlat, const float* hctx, const bf16* h16in, float* olat, float* octx, bf16* h16out, const float* gpost, const float* mod, int gt_off, ...
;     ...
; #pragma unroll
;         for (int r = 0; r < 2; ++r)
; #pragma unroll
;             for (int j = 0; j < 8; ++j) ss[r] += (v[r][j][0] * v[r][j][0] + v[r][j][1] * v[r][j][1]) + (v[r][j][2] * v[r][j][2] + v[r][j][3] * v[r][j][3]);
; #pragma unroll
;         for (int r = 0; r < 2; ++r) { const int m = mr[r]; if (r == 1 && !two) break;
;             float* hd = m < MLAT ? olat + (size_t)m * DM : octx + (size_t)(m - MLAT) * DM; const int vi = (m < MLAT ? (m >> 13) : 2); const LAS float* mv = lp + 4096 + 3 * vi * 2048;
;             const float rstd = rsqrtf(wave_sum(ss[r], lane) * (1.0f / DM) + EPS); float s2 = 0.f;
; #pragma unroll
;             for (int j = 0; j < 8; ++j) { const int ci = 256 * j + 4 * lane; const f32x4 g4 = *(const LAS f32x4*)(lp + ci), t4 = *(const LAS f32x4*)(mv + ci);
;                 const f32x4 nv = hh[r][j] + t4 * (v[r][j] * rstd * g4); v[r][j] = nv;
;                 if (h16out) { v2u w; w.x = pk2(nv[0], nv[1]); w.y = pk2(nv[2], nv[3]); *(v2u*)(h16out + (size_t)m * DM + ci) = w; } else *(f32x4*)(hd + ci) = nv;
;                 s2 += (nv[0] * nv[0] + nv[1] * nv[1]) + (nv[2] * nv[2] + nv[3] * nv[3]); }
;             if (U) { const float rstd2 = rsqrtf(wave_sum(s2, lane) * (1.0f / DM) + EPS); store_u(U + (size_t)m * DM, lane, v[r], rstd2, lp + 2048, mv + 2048, mv + 4096); }
	v_pk_mul_f32 v[122:123], v[70:71], v[70:71]
	v_pk_mul_f32 v[124:125], v[68:69], v[68:69]
	v_mul_f32_e32 v104, v88, v88
	v_pk_mov_b32 v[126:127], v[124:125], v[122:123] op_sel:[1,0]
	v_mov_b32_e32 v125, v123
	v_pk_add_f32 v[122:123], v[126:127], v[124:125]
	v_mov_b32_e32 v126, v73
	v_mov_b32_e32 v127, v65
	v_pk_fma_f32 v[104:105], v[88:89], v[88:89], v[104:105] op_sel_hi:[1,1,0]
	v_mov_b32_e32 v124, v72
	v_mov_b32_e32 v125, v64
	v_pk_mul_f32 v[126:127], v[126:127], v[126:127]
	v_mov_b32_e32 v144, v75
	v_mov_b32_e32 v145, v67
	v_mul_f32_e32 v104, v90, v90
	v_pk_fma_f32 v[124:125], v[124:125], v[124:125], v[126:127]
	v_mov_b32_e32 v126, v74
	v_mov_b32_e32 v127, v66
	v_pk_mul_f32 v[144:145], v[144:145], v[144:145]
	v_pk_fma_f32 v[106:107], v[90:91], v[90:91], v[104:105] op_sel_hi:[1,1,0]
	v_mul_f32_e32 v104, v76, v76
	v_pk_fma_f32 v[126:127], v[126:127], v[126:127], v[144:145]
	v_pk_mul_f32 v[108:109], v[86:87], v[86:87]
	v_pk_mul_f32 v[110:111], v[84:85], v[84:85]
	v_pk_fma_f32 v[118:119], v[76:77], v[76:77], v[104:105] op_sel_hi:[1,1,0]
	v_mul_f32_e32 v104, v78, v78
	v_pk_add_f32 v[124:125], v[124:125], v[126:127]
	v_pk_mov_b32 v[112:113], v[110:111], v[108:109] op_sel:[1,0]
	v_mov_b32_e32 v111, v109
	v_pk_fma_f32 v[120:121], v[78:79], v[78:79], v[104:105] op_sel_hi:[1,1,0]
	v_pk_add_f32 v[122:123], v[122:123], v[122:123] op_sel_hi:[0,1]
	v_pk_add_f32 v[124:125], v[124:125], v[124:125] op_sel_hi:[0,1]
	v_pk_add_f32 v[108:109], v[112:113], v[110:111]
	v_mul_f32_e32 v110, v80, v80
	v_mul_f32_e32 v112, v81, v81
	v_mul_f32_e32 v114, v82, v82
	v_mul_f32_e32 v116, v83, v83
	v_mov_b32_e32 v111, v119
	v_mov_b32_e32 v113, v121
	v_mov_b32_e32 v115, v123
	v_mov_b32_e32 v117, v125
	v_pk_add_f32 v[110:111], v[110:111], v[112:113]
	v_pk_add_f32 v[112:113], v[114:115], v[116:117]
	v_pk_add_f32 v[108:109], v[108:109], v[108:109] op_sel_hi:[0,1]
	v_pk_add_f32 v[110:111], v[110:111], v[112:113]
	v_mul_f32_e32 v96, v92, v92
	v_pk_add_f32 v[110:111], v[110:111], v[110:111] op_sel_hi:[0,1]
	v_mul_f32_e32 v98, v93, v93
	v_mul_f32_e32 v100, v94, v94
	v_mul_f32_e32 v102, v95, v95
	v_mov_b32_e32 v97, v105
	v_mov_b32_e32 v99, v107
	v_mov_b32_e32 v101, v109
	v_mov_b32_e32 v103, v111
	v_pk_add_f32 v[96:97], v[96:97], v[98:99]
	v_pk_add_f32 v[98:99], v[100:101], v[102:103]
	s_ashr_i32 s6, s38, 31
	v_pk_add_f32 v[96:97], v[96:97], v[98:99]
	s_and_b64 s[4:5], exec, s[46:47]
	v_add_f32_e32 v96, v96, v97
	ds_bpermute_b32 v97, v193, v96
	s_cselect_b32 s5, s6, 0
	s_cselect_b32 s4, s38, s38
	s_min_i32 s6, s38, 0x4000
	s_lshr_b32 s6, s6, 13
	s_waitcnt lgkmcnt(0)
	v_add_f32_e32 v96, v96, v97
	ds_bpermute_b32 v97, v205, v96
	s_mulk_i32 s6, 0x6000
	v_add_u32_e32 v107, s6, v221
	ds_read_b128 v[98:101], v107 offset:16384
	ds_read_b128 v[102:105], v107 offset:17408
	s_waitcnt lgkmcnt(2)
	v_add_f32_e32 v96, v96, v97
	ds_bpermute_b32 v97, v207, v96
	s_lshl_b64 s[46:47], s[4:5], 12
	ds_read_b128 v[108:111], v107 offset:19456
	s_waitcnt lgkmcnt(1)
	v_add_f32_e32 v96, v96, v97
	ds_bpermute_b32 v97, v209, v96
	s_waitcnt lgkmcnt(0)
	v_add_f32_e32 v96, v96, v97
	ds_bpermute_b32 v97, v219, v96
	s_waitcnt lgkmcnt(0)
	v_add_f32_e32 v96, v96, v97
	ds_bpermute_b32 v97, v220, v96
	s_waitcnt lgkmcnt(0)
	v_add_f32_e32 v96, v96, v97
	v_fmamk_f32 v96, v96, 0x3a000000, v196
	v_mul_f32_e32 v97, 0x4b800000, v96
	v_cmp_gt_f32_e32 vcc, s78, v96
	s_nop 1
	v_cndmask_b32_e32 v96, v96, v97, vcc
	v_rsq_f32_e32 v96, v96
	s_nop 0
	v_mul_f32_e32 v97, 0x45800000, v96
	v_cndmask_b32_e32 v106, v96, v97, vcc
	v_pk_mul_f32 v[64:65], v[64:65], v[106:107] op_sel_hi:[1,0]
	v_pk_mul_f32 v[66:67], v[66:67], v[106:107] op_sel_hi:[1,0]
	v_pk_mul_f32 v[64:65], v[0:1], v[64:65]
	v_pk_mul_f32 v[66:67], v[2:3], v[66:67]
	s_waitcnt vmcnt(23)
	v_pk_fma_f32 v[98:99], v[98:99], v[64:65], v[168:169]
	v_pk_fma_f32 v[96:97], v[100:101], v[66:67], v[170:171]
	v_bfe_u32 v64, v98, 16, 1
	v_add3_u32 v64, v98, v64, s79
	v_bfe_u32 v65, v99, 16, 1
	v_lshrrev_b32_e32 v64, 16, v64
	v_add3_u32 v65, v99, v65, s79
	v_and_or_b32 v64, v65, s75, v64
	v_bfe_u32 v65, v96, 16, 1
	v_add3_u32 v65, v96, v65, s79
	v_bfe_u32 v66, v97, 16, 1
	v_lshrrev_b32_e32 v65, 16, v65
	v_add3_u32 v66, v97, v66, s79
	v_and_or_b32 v65, v66, s75, v65
	v_pk_mul_f32 v[66:67], v[72:73], v[106:107] op_sel_hi:[1,0]
	v_lshl_add_u64 v[100:101], v[212:213], 0, s[46:47]
	v_pk_mul_f32 v[66:67], v[4:5], v[66:67]
	global_store_dwordx2 v[100:101], v[64:65], off sc0 sc1
	s_waitcnt vmcnt(23)
	v_pk_fma_f32 v[66:67], v[102:103], v[66:67], v[164:165]
	v_pk_mul_f32 v[64:65], v[74:75], v[106:107] op_sel_hi:[1,0]
	v_bfe_u32 v72, v66, 16, 1
	v_pk_mul_f32 v[64:65], v[6:7], v[64:65]
	v_add3_u32 v72, v66, v72, s79
	v_bfe_u32 v73, v67, 16, 1
	v_pk_fma_f32 v[64:65], v[104:105], v[64:65], v[166:167]
	v_lshrrev_b32_e32 v72, 16, v72
	v_add3_u32 v73, v67, v73, s79
	v_and_or_b32 v72, v73, s75, v72
	v_bfe_u32 v73, v64, 16, 1
	v_add3_u32 v73, v64, v73, s79
	v_bfe_u32 v74, v65, 16, 1
	v_lshrrev_b32_e32 v73, 16, v73
	v_add3_u32 v74, v65, v74, s79
	v_and_or_b32 v73, v74, s75, v73
	v_mov_b32_e32 v74, v99
	v_mov_b32_e32 v75, v67
	global_store_dwordx2 v[100:101], v[72:73], off offset:512 sc0 sc1
	v_mov_b32_e32 v72, v98
	v_mov_b32_e32 v73, v66
	v_pk_mul_f32 v[74:75], v[74:75], v[74:75]
	v_mov_b32_e32 v102, v97
	v_mov_b32_e32 v103, v65
	v_pk_fma_f32 v[72:73], v[72:73], v[72:73], v[74:75]
	v_mov_b32_e32 v74, v96
	v_mov_b32_e32 v75, v64
	v_pk_mul_f32 v[102:103], v[102:103], v[102:103]
	v_pk_mul_f32 v[68:69], v[68:69], v[106:107] op_sel_hi:[1,0]
	v_pk_fma_f32 v[74:75], v[74:75], v[74:75], v[102:103]
	ds_read_b128 v[102:105], v107 offset:18432
	v_pk_mul_f32 v[68:69], v[8:9], v[68:69]
	v_pk_add_f32 v[72:73], v[72:73], v[74:75]
	v_pk_mul_f32 v[70:71], v[70:71], v[106:107] op_sel_hi:[1,0]
	v_pk_add_f32 v[112:113], v[72:73], v[72:73] op_sel_hi:[0,1]
	s_waitcnt vmcnt(23) lgkmcnt(0)
; #define LAS __attribute__((address_space(3)))
; __device__ __forceinline__ unsigned pk2(float lo, float hi) { return f2bf(lo) | (f2bf(hi) << 16); }
; __device__ __forceinline__ void pass_post(const bf16* o16, const float* opart, const float* hlat, const float* hctx, const bf16* h16in, float* olat, float* octx, bf16* h16out, const float* gpost, const float* mod, int gt_off, ...
;     ...
;             const float rstd = rsqrtf(wave_sum(ss[r], lane) * (1.0f / DM) + EPS); float s2 = 0.f;
; #pragma unroll
;             for (int j = 0; j < 8; ++j) { const int ci = 256 * j + 4 * lane; const f32x4 g4 = *(const LAS f32x4*)(lp + ci), t4 = *(const LAS f32x4*)(mv + ci);
;                 const f32x4 nv = hh[r][j] + t4 * (v[r][j] * rstd * g4); v[r][j] = nv;
;                 if (h16out) { v2u w; w.x = pk2(nv[0], nv[1]); w.y = pk2(nv[2], nv[3]); *(v2u*)(h16out + (size_t)m * DM + ci) = w; } else *(f32x4*)(hd + ci) = nv;
;                 s2 += (nv[0] * nv[0] + nv[1] * nv[1]) + (nv[2] * nv[2] + nv[3] * nv[3]); }
;             if (U) { const float rstd2 = rsqrtf(wave_sum(s2, lane) * (1.0f / DM) + EPS); store_u(U + (size_t)m * DM, lane, v[r], rstd2, lp + 2048, mv + 2048, mv + 4096); }
	v_pk_fma_f32 v[74:75], v[102:103], v[68:69], v[152:153]
	v_pk_mul_f32 v[70:71], v[10:11], v[70:71]
	v_bfe_u32 v68, v74, 16, 1
	v_add3_u32 v68, v74, v68, s79
	v_bfe_u32 v69, v75, 16, 1
	v_pk_fma_f32 v[72:73], v[104:105], v[70:71], v[154:155]
	v_lshrrev_b32_e32 v68, 16, v68
	v_add3_u32 v69, v75, v69, s79
	v_and_or_b32 v68, v69, s75, v68
	v_bfe_u32 v69, v72, 16, 1
	v_add3_u32 v69, v72, v69, s79
	v_bfe_u32 v70, v73, 16, 1
	v_lshrrev_b32_e32 v69, 16, v69
	v_add3_u32 v70, v73, v70, s79
	v_and_or_b32 v69, v70, s75, v69
	global_store_dwordx2 v[100:101], v[68:69], off offset:1024 sc0 sc1
	v_pk_mul_f32 v[68:69], v[72:73], v[72:73]
	v_pk_mul_f32 v[70:71], v[74:75], v[74:75]
	v_pk_mul_f32 v[80:81], v[80:81], v[106:107] op_sel_hi:[1,0]
	v_pk_mov_b32 v[102:103], v[70:71], v[68:69] op_sel:[1,0]
	v_mov_b32_e32 v71, v69
	v_pk_add_f32 v[68:69], v[102:103], v[70:71]
	v_pk_mul_f32 v[70:71], v[76:77], v[106:107] op_sel_hi:[1,0]
	v_pk_add_f32 v[114:115], v[68:69], v[68:69] op_sel_hi:[0,1]
	v_pk_mul_f32 v[70:71], v[12:13], v[70:71]
	v_pk_mul_f32 v[68:69], v[78:79], v[106:107] op_sel_hi:[1,0]
	s_waitcnt vmcnt(23)
	v_pk_fma_f32 v[70:71], v[108:109], v[70:71], v[148:149]
	v_pk_mul_f32 v[68:69], v[14:15], v[68:69]
	v_bfe_u32 v76, v70, 16, 1
	v_add3_u32 v76, v70, v76, s79
	v_bfe_u32 v77, v71, 16, 1
	v_pk_fma_f32 v[68:69], v[110:111], v[68:69], v[150:151]
	v_lshrrev_b32_e32 v76, 16, v76
	v_add3_u32 v77, v71, v77, s79
	v_and_or_b32 v76, v77, s75, v76
	v_bfe_u32 v77, v68, 16, 1
	v_add3_u32 v77, v68, v77, s79
	v_bfe_u32 v78, v69, 16, 1
	v_lshrrev_b32_e32 v77, 16, v77
	v_add3_u32 v78, v69, v78, s79
	v_and_or_b32 v77, v78, s75, v77
	global_store_dwordx2 v[100:101], v[76:77], off offset:1536 sc0 sc1
	v_mul_f32_e32 v76, v70, v70
	v_pk_fma_f32 v[116:117], v[70:71], v[70:71], v[76:77] op_sel_hi:[1,1,0]
	v_mul_f32_e32 v76, v68, v68
	v_pk_fma_f32 v[118:119], v[68:69], v[68:69], v[76:77] op_sel_hi:[1,1,0]
	ds_read_b128 v[76:79], v107 offset:20480
	ds_read_b128 v[108:111], v107 offset:21504
	v_pk_mul_f32 v[80:81], v[16:17], v[80:81]
	v_pk_mul_f32 v[82:83], v[82:83], v[106:107] op_sel_hi:[1,0]
	s_waitcnt vmcnt(23) lgkmcnt(1)
	v_pk_fma_f32 v[104:105], v[76:77], v[80:81], v[140:141]
	s_nop 0
	v_bfe_u32 v76, v104, 16, 1
	v_pk_mul_f32 v[82:83], v[18:19], v[82:83]
	v_add3_u32 v76, v104, v76, s79
	v_bfe_u32 v77, v105, 16, 1
	v_pk_fma_f32 v[102:103], v[78:79], v[82:83], v[142:143]
	v_lshrrev_b32_e32 v76, 16, v76
	v_add3_u32 v77, v105, v77, s79
	v_and_or_b32 v76, v77, s75, v76
	v_bfe_u32 v77, v102, 16, 1
	v_add3_u32 v77, v102, v77, s79
	v_bfe_u32 v78, v103, 16, 1
	v_lshrrev_b32_e32 v77, 16, v77
	v_add3_u32 v78, v103, v78, s79
	v_and_or_b32 v77, v78, s75, v77
	v_mul_f32_e32 v116, v104, v104
	v_mul_f32_e32 v118, v105, v105
	v_mul_f32_e32 v114, v102, v102
	v_mul_f32_e32 v112, v103, v103
	global_store_dwordx2 v[100:101], v[76:77], off offset:2048 sc0 sc1
	v_pk_add_f32 v[76:77], v[116:117], v[118:119]
	v_pk_add_f32 v[78:79], v[114:115], v[112:113]
	s_nop 0
	v_pk_add_f32 v[76:77], v[76:77], v[78:79]
	v_pk_mul_f32 v[78:79], v[84:85], v[106:107] op_sel_hi:[1,0]
	v_pk_add_f32 v[112:113], v[76:77], v[76:77] op_sel_hi:[0,1]
	v_pk_mul_f32 v[76:77], v[86:87], v[106:107] op_sel_hi:[1,0]
	v_pk_mul_f32 v[78:79], v[20:21], v[78:79]
	v_pk_mul_f32 v[76:77], v[22:23], v[76:77]
	s_waitcnt vmcnt(23) lgkmcnt(0)
	v_pk_fma_f32 v[82:83], v[108:109], v[78:79], v[136:137]
	v_pk_fma_f32 v[80:81], v[110:111], v[76:77], v[138:139]
	v_bfe_u32 v76, v82, 16, 1
	v_add3_u32 v76, v82, v76, s79
	v_bfe_u32 v77, v83, 16, 1
	v_lshrrev_b32_e32 v76, 16, v76
	v_add3_u32 v77, v83, v77, s79
	v_and_or_b32 v108, v77, s75, v76
	v_bfe_u32 v76, v80, 16, 1
	v_add3_u32 v76, v80, v76, s79
	v_bfe_u32 v77, v81, 16, 1
	v_lshrrev_b32_e32 v76, 16, v76
	v_add3_u32 v77, v81, v77, s79
	v_and_or_b32 v109, v77, s75, v76
	v_pk_mul_f32 v[76:77], v[80:81], v[80:81]
	v_pk_mul_f32 v[78:79], v[82:83], v[82:83]
	v_pk_mul_f32 v[86:87], v[88:89], v[106:107] op_sel_hi:[1,0]
	v_pk_mov_b32 v[84:85], v[78:79], v[76:77] op_sel:[1,0]
	v_mov_b32_e32 v79, v77
	v_pk_add_f32 v[76:77], v[84:85], v[78:79]
	v_pk_mul_f32 v[84:85], v[90:91], v[106:107] op_sel_hi:[1,0]
	v_pk_add_f32 v[110:111], v[76:77], v[76:77] op_sel_hi:[0,1]
	ds_read_b128 v[76:79], v107 offset:22528
	ds_read_b128 v[88:91], v107 offset:23552
	v_pk_mul_f32 v[86:87], v[24:25], v[86:87]
	v_pk_mul_f32 v[84:85], v[26:27], v[84:85]
	global_store_dwordx2 v[100:101], v[108:109], off offset:2560 sc0 sc1
	s_waitcnt vmcnt(23) lgkmcnt(1)
	v_pk_fma_f32 v[86:87], v[76:77], v[86:87], v[132:133]
	v_pk_fma_f32 v[84:85], v[78:79], v[84:85], v[134:135]
	v_mul_f32_e32 v76, v86, v86
	v_pk_fma_f32 v[114:115], v[86:87], v[86:87], v[76:77] op_sel_hi:[1,1,0]
	v_mul_f32_e32 v76, v84, v84
	v_pk_fma_f32 v[116:117], v[84:85], v[84:85], v[76:77] op_sel_hi:[1,1,0]
	v_pk_mul_f32 v[76:77], v[94:95], v[106:107] op_sel_hi:[1,0]
	v_pk_mul_f32 v[78:79], v[92:93], v[106:107] op_sel_hi:[1,0]
	v_pk_mul_f32 v[76:77], v[30:31], v[76:77]
	v_pk_mul_f32 v[78:79], v[28:29], v[78:79]
	s_waitcnt vmcnt(22) lgkmcnt(0)
	v_pk_fma_f32 v[76:77], v[76:77], v[90:91], v[130:131]
	v_pk_fma_f32 v[78:79], v[78:79], v[88:89], v[128:129]
	v_mul_f32_e32 v110, v76, v76
	v_mul_f32_e32 v114, v78, v78
	v_mul_f32_e32 v116, v79, v79
	v_mul_f32_e32 v112, v77, v77
	v_pk_add_f32 v[88:89], v[114:115], v[116:117]
	v_pk_add_f32 v[90:91], v[110:111], v[112:113]
	v_bfe_u32 v92, v85, 16, 1
	v_pk_add_f32 v[88:89], v[88:89], v[90:91]
	v_bfe_u32 v90, v86, 16, 1
	v_add_f32_e32 v88, v88, v89
	ds_bpermute_b32 v89, v193, v88
	v_add3_u32 v90, v86, v90, s79
	v_lshrrev_b32_e32 v90, 16, v90
	v_add3_u32 v92, v85, v92, s79
	s_waitcnt lgkmcnt(0)
; #define LAS __attribute__((address_space(3)))
; __device__ __forceinline__ unsigned pk2(float lo, float hi) { return f2bf(lo) | (f2bf(hi) << 16); }
; __device__ __forceinline__ void store_u(bf16* urow, int lane, const f32x4 (&v)[8], float rstd, const LAS float* g, const LAS float* sh, const LAS float* sc) {
; #pragma unroll
;     for (int j = 0; j < 8; ++j) { const int ci = 256 * j + 4 * lane; const f32x4 g4 = *(const LAS f32x4*)(g + ci), s4 = *(const LAS f32x4*)(sc + ci), h4 = *(const LAS f32x4*)(sh + ci);
;         const f32x4 t = (v[j] * rstd * g4) * (1.0f + s4) + h4; v2u w; w.x = pk2(t[0], t[1]); w.y = pk2(t[2], t[3]); *(v2u*)(urow + ci) = w; }
; }
; __device__ __forceinline__ void pass_post(const bf16* o16, const float* opart, const float* hlat, const float* hctx, const bf16* h16in, float* olat, float* octx, bf16* h16out, const float* gpost, const float* mod, int gt_off, ...
;     ...
;             const float rstd = rsqrtf(wave_sum(ss[r], lane) * (1.0f / DM) + EPS); float s2 = 0.f;
; #pragma unroll
;             for (int j = 0; j < 8; ++j) { const int ci = 256 * j + 4 * lane; const f32x4 g4 = *(const LAS f32x4*)(lp + ci), t4 = *(const LAS f32x4*)(mv + ci);
;                 const f32x4 nv = hh[r][j] + t4 * (v[r][j] * rstd * g4); v[r][j] = nv;
;                 if (h16out) { v2u w; w.x = pk2(nv[0], nv[1]); w.y = pk2(nv[2], nv[3]); *(v2u*)(h16out + (size_t)m * DM + ci) = w; } else *(f32x4*)(hd + ci) = nv;
;                 s2 += (nv[0] * nv[0] + nv[1] * nv[1]) + (nv[2] * nv[2] + nv[3] * nv[3]); }
;             if (U) { const float rstd2 = rsqrtf(wave_sum(s2, lane) * (1.0f / DM) + EPS); store_u(U + (size_t)m * DM, lane, v[r], rstd2, lp + 2048, mv + 2048, mv + 4096); }
;         }
	v_add_f32_e32 v89, v88, v89
	ds_bpermute_b32 v91, v205, v89
	v_bfe_u32 v88, v87, 16, 1
	v_add3_u32 v88, v87, v88, s79
	v_and_or_b32 v88, v88, s75, v90
	v_bfe_u32 v90, v84, 16, 1
	s_waitcnt lgkmcnt(0)
	v_add_f32_e32 v89, v89, v91
	ds_bpermute_b32 v91, v207, v89
	v_add3_u32 v90, v84, v90, s79
	v_lshrrev_b32_e32 v90, 16, v90
	s_waitcnt lgkmcnt(0)
	v_add_f32_e32 v91, v89, v91
	ds_bpermute_b32 v93, v209, v91
	v_and_or_b32 v89, v92, s75, v90
	global_store_dwordx2 v[100:101], v[88:89], off offset:3072 sc0 sc1
	v_bfe_u32 v88, v78, 16, 1
	v_add3_u32 v88, v78, v88, s79
	s_waitcnt lgkmcnt(0)
	v_add_f32_e32 v89, v91, v93
	ds_bpermute_b32 v90, v219, v89
	v_bfe_u32 v91, v79, 16, 1
	v_lshrrev_b32_e32 v88, 16, v88
	v_add3_u32 v91, v79, v91, s79
	v_and_or_b32 v88, v91, s75, v88
	s_waitcnt lgkmcnt(0)
	v_add_f32_e32 v89, v89, v90
	ds_bpermute_b32 v90, v220, v89
	v_bfe_u32 v91, v76, 16, 1
	v_add3_u32 v91, v76, v91, s79
	v_bfe_u32 v92, v77, 16, 1
	v_lshrrev_b32_e32 v91, 16, v91
	s_waitcnt lgkmcnt(0)
	v_add_f32_e32 v89, v89, v90
	v_fmamk_f32 v89, v89, 0x3a000000, v196
	v_mul_f32_e32 v90, 0x4b800000, v89
	v_cmp_gt_f32_e32 vcc, s78, v89
	s_nop 1
	v_cndmask_b32_e32 v89, v89, v90, vcc
	v_rsq_f32_e32 v90, v89
	v_add3_u32 v89, v77, v92, s79
	v_and_or_b32 v89, v89, s75, v91
	global_store_dwordx2 v[100:101], v[88:89], off offset:3584 sc0 sc1
	v_mul_f32_e32 v88, 0x45800000, v90
	v_cndmask_b32_e32 v88, v90, v88, vcc
	ds_read_b128 v[90:93], v107 offset:32768
	ds_read_b128 v[108:111], v107 offset:24576
	v_pk_mul_f32 v[94:95], v[96:97], v[88:89] op_sel_hi:[1,0]
	v_pk_mul_f32 v[96:97], v[98:99], v[88:89] op_sel_hi:[1,0]
	v_pk_mul_f32 v[114:115], v[34:35], v[94:95]
	v_pk_mul_f32 v[112:113], v[32:33], v[96:97]
	s_waitcnt lgkmcnt(1)
	v_pk_add_f32 v[90:91], v[90:91], 1.0 op_sel_hi:[1,0]
	v_pk_add_f32 v[92:93], v[92:93], 1.0 op_sel_hi:[1,0]
	s_waitcnt lgkmcnt(0)
	v_pk_fma_f32 v[90:91], v[90:91], v[112:113], v[108:109]
	ds_read_b128 v[94:97], v107 offset:33792
	ds_read_b128 v[98:101], v107 offset:25600
	v_bfe_u32 v89, v90, 16, 1
	v_add3_u32 v89, v90, v89, s79
	v_bfe_u32 v90, v91, 16, 1
	v_pk_fma_f32 v[92:93], v[92:93], v[114:115], v[110:111]
	v_lshrrev_b32_e32 v89, 16, v89
	v_add3_u32 v90, v91, v90, s79
	v_and_or_b32 v108, v90, s75, v89
	v_bfe_u32 v89, v92, 16, 1
	v_add3_u32 v89, v92, v89, s79
	v_lshrrev_b32_e32 v89, 16, v89
	v_pk_mul_f32 v[66:67], v[66:67], v[88:89] op_sel_hi:[1,0]
	v_bfe_u32 v90, v93, 16, 1
	v_pk_mul_f32 v[66:67], v[36:37], v[66:67]
	s_waitcnt lgkmcnt(1)
	v_pk_add_f32 v[94:95], v[94:95], 1.0 op_sel_hi:[1,0]
	v_add3_u32 v90, v93, v90, s79
	s_waitcnt lgkmcnt(0)
	v_pk_fma_f32 v[66:67], v[94:95], v[66:67], v[98:99]
	v_and_or_b32 v109, v90, s75, v89
	v_pk_mul_f32 v[64:65], v[64:65], v[88:89] op_sel_hi:[1,0]
	v_bfe_u32 v89, v66, 16, 1
	v_pk_mul_f32 v[64:65], v[38:39], v[64:65]
	v_pk_add_f32 v[92:93], v[96:97], 1.0 op_sel_hi:[1,0]
	v_add3_u32 v66, v66, v89, s79
	v_bfe_u32 v89, v67, 16, 1
	v_pk_fma_f32 v[64:65], v[92:93], v[64:65], v[100:101]
	v_lshrrev_b32_e32 v66, 16, v66
	v_add3_u32 v67, v67, v89, s79
	v_and_or_b32 v66, v67, s75, v66
	v_bfe_u32 v67, v64, 16, 1
	v_add3_u32 v64, v64, v67, s79
	v_bfe_u32 v67, v65, 16, 1
	v_lshrrev_b32_e32 v64, 16, v64
	v_add3_u32 v65, v65, v67, s79
	v_lshl_add_u64 v[90:91], v[214:215], 0, s[46:47]
	v_and_or_b32 v67, v65, s75, v64
	global_store_dwordx2 v[90:91], v[108:109], off sc0 sc1
	global_store_dwordx2 v[90:91], v[66:67], off offset:512 sc0 sc1
	ds_read_b128 v[64:67], v107 offset:34816
	ds_read_b128 v[92:95], v107 offset:26624
	v_pk_mul_f32 v[74:75], v[74:75], v[88:89] op_sel_hi:[1,0]
	v_pk_mul_f32 v[72:73], v[72:73], v[88:89] op_sel_hi:[1,0]
	v_pk_mul_f32 v[96:97], v[40:41], v[74:75]
	s_waitcnt lgkmcnt(1)
	v_pk_add_f32 v[108:109], v[64:65], 1.0 op_sel_hi:[1,0]
	v_pk_mul_f32 v[98:99], v[42:43], v[72:73]
	s_waitcnt lgkmcnt(0)
	v_pk_fma_f32 v[92:93], v[108:109], v[96:97], v[92:93]
	v_pk_add_f32 v[100:101], v[66:67], 1.0 op_sel_hi:[1,0]
	v_bfe_u32 v89, v92, 16, 1
	v_add3_u32 v89, v92, v89, s79
	v_bfe_u32 v92, v93, 16, 1
	ds_read_b128 v[72:75], v107 offset:35840
	ds_read_b128 v[64:67], v107 offset:27648
	v_pk_fma_f32 v[94:95], v[100:101], v[98:99], v[94:95]
	v_lshrrev_b32_e32 v89, 16, v89
	v_add3_u32 v92, v93, v92, s79
	v_and_or_b32 v92, v92, s75, v89
	v_bfe_u32 v89, v94, 16, 1
	v_add3_u32 v89, v94, v89, s79
	v_lshrrev_b32_e32 v89, 16, v89
	v_pk_mul_f32 v[70:71], v[70:71], v[88:89] op_sel_hi:[1,0]
	v_pk_mul_f32 v[68:69], v[68:69], v[88:89] op_sel_hi:[1,0]
	v_pk_mul_f32 v[70:71], v[44:45], v[70:71]
	s_waitcnt lgkmcnt(1)
	v_pk_add_f32 v[72:73], v[72:73], 1.0 op_sel_hi:[1,0]
	v_pk_mul_f32 v[68:69], v[46:47], v[68:69]
	v_pk_add_f32 v[74:75], v[74:75], 1.0 op_sel_hi:[1,0]
	s_waitcnt lgkmcnt(0)
; #define LAS __attribute__((address_space(3)))
; __device__ __forceinline__ unsigned pk2(float lo, float hi) { return f2bf(lo) | (f2bf(hi) << 16); }
; __device__ __forceinline__ void store_u(bf16* urow, int lane, const f32x4 (&v)[8], float rstd, const LAS float* g, const LAS float* sh, const LAS float* sc) {
; #pragma unroll
;     for (int j = 0; j < 8; ++j) { const int ci = 256 * j + 4 * lane; const f32x4 g4 = *(const LAS f32x4*)(g + ci), s4 = *(const LAS f32x4*)(sc + ci), h4 = *(const LAS f32x4*)(sh + ci);
;         const f32x4 t = (v[j] * rstd * g4) * (1.0f + s4) + h4; v2u w; w.x = pk2(t[0], t[1]); w.y = pk2(t[2], t[3]); *(v2u*)(urow + ci) = w; }
; }
	v_pk_fma_f32 v[64:65], v[72:73], v[70:71], v[64:65]
	v_pk_fma_f32 v[66:67], v[74:75], v[68:69], v[66:67]
	v_bfe_u32 v68, v64, 16, 1
	v_add3_u32 v64, v64, v68, s79
	v_bfe_u32 v68, v65, 16, 1
	v_lshrrev_b32_e32 v64, 16, v64
	v_add3_u32 v65, v65, v68, s79
	v_and_or_b32 v64, v65, s75, v64
	v_bfe_u32 v65, v66, 16, 1
	v_bfe_u32 v93, v95, 16, 1
	v_add3_u32 v65, v66, v65, s79
	v_bfe_u32 v66, v67, 16, 1
	v_add3_u32 v93, v95, v93, s79
	v_lshrrev_b32_e32 v65, 16, v65
	v_add3_u32 v66, v67, v66, s79
	v_and_or_b32 v93, v93, s75, v89
	v_and_or_b32 v65, v66, s75, v65
	global_store_dwordx2 v[90:91], v[92:93], off offset:1024 sc0 sc1
	global_store_dwordx2 v[90:91], v[64:65], off offset:1536 sc0 sc1
	ds_read_b128 v[64:67], v107 offset:36864
	ds_read_b128 v[68:71], v107 offset:28672
	v_pk_mul_f32 v[74:75], v[104:105], v[88:89] op_sel_hi:[1,0]
	v_pk_mul_f32 v[72:73], v[102:103], v[88:89] op_sel_hi:[1,0]
	v_pk_mul_f32 v[92:93], v[48:49], v[74:75]
	s_waitcnt lgkmcnt(1)
	v_pk_add_f32 v[98:99], v[64:65], 1.0 op_sel_hi:[1,0]
	v_pk_mul_f32 v[94:95], v[50:51], v[72:73]
	s_waitcnt lgkmcnt(0)
	v_pk_fma_f32 v[68:69], v[98:99], v[92:93], v[68:69]
	v_pk_add_f32 v[96:97], v[66:67], 1.0 op_sel_hi:[1,0]
	v_bfe_u32 v89, v68, 16, 1
	v_add3_u32 v68, v68, v89, s79
	v_bfe_u32 v89, v69, 16, 1
	ds_read_b128 v[72:75], v107 offset:37888
	ds_read_b128 v[64:67], v107 offset:29696
	v_pk_fma_f32 v[70:71], v[96:97], v[94:95], v[70:71]
	v_lshrrev_b32_e32 v68, 16, v68
	v_add3_u32 v69, v69, v89, s79
	v_and_or_b32 v68, v69, s75, v68
	v_bfe_u32 v69, v70, 16, 1
	v_add3_u32 v69, v70, v69, s79
	v_bfe_u32 v70, v71, 16, 1
	v_lshrrev_b32_e32 v69, 16, v69
	v_add3_u32 v70, v71, v70, s79
	v_and_or_b32 v69, v70, s75, v69
	v_pk_mul_f32 v[70:71], v[82:83], v[88:89] op_sel_hi:[1,0]
	global_store_dwordx2 v[90:91], v[68:69], off offset:2048 sc0 sc1
	v_pk_mul_f32 v[68:69], v[80:81], v[88:89] op_sel_hi:[1,0]
	v_pk_mul_f32 v[70:71], v[52:53], v[70:71]
	s_waitcnt lgkmcnt(1)
	v_pk_add_f32 v[72:73], v[72:73], 1.0 op_sel_hi:[1,0]
	v_pk_mul_f32 v[68:69], v[54:55], v[68:69]
	v_pk_add_f32 v[74:75], v[74:75], 1.0 op_sel_hi:[1,0]
	s_waitcnt lgkmcnt(0)
	v_pk_fma_f32 v[64:65], v[72:73], v[70:71], v[64:65]
	v_pk_fma_f32 v[66:67], v[74:75], v[68:69], v[66:67]
	v_bfe_u32 v68, v64, 16, 1
	v_add3_u32 v64, v64, v68, s79
	v_bfe_u32 v68, v65, 16, 1
	v_lshrrev_b32_e32 v64, 16, v64
	v_add3_u32 v65, v65, v68, s79
	v_and_or_b32 v64, v65, s75, v64
	v_bfe_u32 v65, v66, 16, 1
	v_add3_u32 v65, v66, v65, s79
	v_bfe_u32 v66, v67, 16, 1
	v_lshrrev_b32_e32 v65, 16, v65
	v_add3_u32 v66, v67, v66, s79
	v_and_or_b32 v65, v66, s75, v65
	global_store_dwordx2 v[90:91], v[64:65], off offset:2560 sc0 sc1
	ds_read_b128 v[64:67], v107 offset:38912
	ds_read_b128 v[68:71], v107 offset:30720
	v_pk_mul_f32 v[74:75], v[86:87], v[88:89] op_sel_hi:[1,0]
	v_pk_mul_f32 v[72:73], v[84:85], v[88:89] op_sel_hi:[1,0]
	v_pk_mul_f32 v[80:81], v[56:57], v[74:75]
	s_waitcnt lgkmcnt(1)
	v_pk_add_f32 v[86:87], v[64:65], 1.0 op_sel_hi:[1,0]
	v_pk_mul_f32 v[82:83], v[58:59], v[72:73]
	s_waitcnt lgkmcnt(0)
	v_pk_fma_f32 v[68:69], v[86:87], v[80:81], v[68:69]
	v_pk_add_f32 v[84:85], v[66:67], 1.0 op_sel_hi:[1,0]
	v_bfe_u32 v80, v68, 16, 1
	v_add3_u32 v68, v68, v80, s79
	v_bfe_u32 v80, v69, 16, 1
	ds_read_b128 v[72:75], v107 offset:39936
	ds_read_b128 v[64:67], v107 offset:31744
	v_pk_fma_f32 v[70:71], v[84:85], v[82:83], v[70:71]
	v_lshrrev_b32_e32 v68, 16, v68
	v_add3_u32 v69, v69, v80, s79
	v_and_or_b32 v68, v69, s75, v68
	v_bfe_u32 v69, v70, 16, 1
	v_add3_u32 v69, v70, v69, s79
	v_bfe_u32 v70, v71, 16, 1
	v_lshrrev_b32_e32 v69, 16, v69
	v_add3_u32 v70, v71, v70, s79
	v_and_or_b32 v69, v70, s75, v69
	v_pk_mul_f32 v[70:71], v[78:79], v[88:89] op_sel_hi:[1,0]
	global_store_dwordx2 v[90:91], v[68:69], off offset:3072 sc0 sc1
	v_pk_mul_f32 v[68:69], v[76:77], v[88:89] op_sel_hi:[1,0]
	v_pk_mul_f32 v[70:71], v[60:61], v[70:71]
	s_waitcnt lgkmcnt(1)
	v_pk_add_f32 v[72:73], v[72:73], 1.0 op_sel_hi:[1,0]
	v_pk_mul_f32 v[68:69], v[62:63], v[68:69]
	v_pk_add_f32 v[74:75], v[74:75], 1.0 op_sel_hi:[1,0]
	s_waitcnt lgkmcnt(0)
	v_pk_fma_f32 v[64:65], v[70:71], v[72:73], v[64:65]
	v_pk_fma_f32 v[66:67], v[68:69], v[74:75], v[66:67]
	v_bfe_u32 v68, v64, 16, 1
	v_add3_u32 v64, v64, v68, s79
	v_bfe_u32 v68, v65, 16, 1
	v_lshrrev_b32_e32 v64, 16, v64
	v_add3_u32 v65, v65, v68, s79
	v_and_or_b32 v64, v65, s75, v64
	v_bfe_u32 v65, v66, 16, 1
	v_add3_u32 v65, v66, v65, s79
	v_bfe_u32 v66, v67, 16, 1
	v_lshrrev_b32_e32 v65, 16, v65
	v_add3_u32 v66, v67, v66, s79
	v_and_or_b32 v65, v66, s75, v65
	global_store_dwordx2 v[90:91], v[64:65], off offset:3584 sc0 sc1
	s_branch .LBB0_960

; #define LAS __attribute__((address_space(3)))
; __device__ __forceinline__ void pass_post(const bf16* o16, const float* opart, const float* hlat, const float* hctx, const bf16* h16in, float* olat, float* octx, bf16* h16out, const float* gpost, const float* mod, int gt_off, ...
;     ...
;         for (int r = 0; r < 2; ++r) { const int m = mr[r]; ss[r] = 0.f;
;             const float* hs = m < MLAT ? hlat + (size_t)m * DM : hctx + (size_t)(m - MLAT) * DM;
;             if (m < MLAT) { const bf16* orow = o16 + (size_t)m * DM;
; #pragma unroll
;                 for (int j = 0; j < 8; ++j) { const v2u raw = *(const v2u*)(orow + 256 * j + 4 * lane);
;                     v[r][j] = (f32x4){__uint_as_float(raw.x << 16), __uint_as_float(raw.x & 0xffff0000u), __uint_as_float(raw.y << 16), __uint_as_float(raw.y & 0xffff0000u)}; }
;             } else { const float* orow = opart + (size_t)(m - MLAT) * DM;
; #pragma unroll
;                 for (int j = 0; j < 8; ++j) { const int ci = 256 * j + 4 * lane;
;                     v[r][j] = (*(const f32x4*)(orow + ci) + *(const f32x4*)(orow + ci + (size_t)512 * DM)) + (*(const f32x4*)(orow + ci + (size_t)1024 * DM) + *(const f32x4*)(orow + ci + (size_t)1536 * DM)); } }
;             if (h16in) { const bf16* hrow = h16in + (size_t)m * DM;
; #pragma unroll
;                 for (int j = 0; j < 8; ++j) { const v2u raw = *(const v2u*)(hrow + 256 * j + 4 * lane);
;                     hh[r][j] = (f32x4){__uint_as_float(raw.x << 16), __uint_as_float(raw.x & 0xffff0000u), __uint_as_float(raw.y << 16), __uint_as_float(raw.y & 0xffff0000u)}; }
;             } else {
; #pragma unroll
;                 for (int j = 0; j < 8; ++j) hh[r][j] = *(const f32x4*)(hs + 256 * j + 4 * lane); }
;         }
; #pragma unroll
;         for (int r = 0; r < 2; ++r)
; #pragma unroll
;             for (int j = 0; j < 8; ++j) ss[r] += (v[r][j][0] * v[r][j][0] + v[r][j][1] * v[r][j][1]) + (v[r][j][2] * v[r][j][2] + v[r][j][3] * v[r][j][3]);
; #pragma unroll
;         for (int r = 0; r < 2; ++r) { const int m = mr[r]; if (r == 1 && !two) break;
;             float* hd = m < MLAT ? olat + (size_t)m * DM : octx + (size_t)(m - MLAT) * DM; const int vi = (m < MLAT ? (m >> 13) : 2); const LAS float* mv = lp + 4096 + 3 * vi * 2048;
;             const float rstd = rsqrtf(wave_sum(ss[r], lane) * (1.0f / DM) + EPS); float s2 = 0.f;
; #pragma unroll
.LBB0_1216:
	s_waitcnt vmcnt(1)
	v_lshlrev_b32_e32 v150, 16, v98
	v_and_b32_e32 v151, 0xffff0000, v98
	v_lshlrev_b32_e32 v152, 16, v99
	v_and_b32_e32 v153, 0xffff0000, v99
	s_waitcnt vmcnt(0)
	v_lshlrev_b32_e32 v148, 16, v96
	v_and_b32_e32 v149, 0xffff0000, v96
	v_lshlrev_b32_e32 v146, 16, v97
	v_and_b32_e32 v147, 0xffff0000, v97
	v_lshl_add_u64 v[96:97], v[116:117], 0, s[56:57]
	v_mov_b32_e32 v98, v69
	v_mov_b32_e32 v99, v65
	v_lshlrev_b32_e32 v156, 16, v100
	v_and_b32_e32 v157, 0xffff0000, v100
	v_lshlrev_b32_e32 v154, 16, v101
	v_and_b32_e32 v155, 0xffff0000, v101
	global_load_dwordx2 v[144:145], v[96:97], off
	global_load_dwordx2 v[142:143], v[96:97], off offset:512
	global_load_dwordx2 v[140:141], v[96:97], off offset:1024
	global_load_dwordx2 v[138:139], v[96:97], off offset:1536
	global_load_dwordx2 v[136:137], v[96:97], off offset:2048
	global_load_dwordx2 v[134:135], v[96:97], off offset:2560
	global_load_dwordx2 v[132:133], v[96:97], off offset:3072
	global_load_dwordx2 v[130:131], v[96:97], off offset:3584
	v_mov_b32_e32 v96, v68
	v_mov_b32_e32 v97, v64
	v_pk_mul_f32 v[98:99], v[98:99], v[98:99]
	v_mov_b32_e32 v100, v71
	v_mov_b32_e32 v101, v67
	v_pk_fma_f32 v[96:97], v[96:97], v[96:97], v[98:99]
	v_mov_b32_e32 v98, v70
	v_mov_b32_e32 v99, v66
	v_pk_mul_f32 v[100:101], v[100:101], v[100:101]
	v_lshlrev_b32_e32 v158, 16, v102
	v_pk_fma_f32 v[98:99], v[98:99], v[98:99], v[100:101]
	v_pk_mul_f32 v[100:101], v[72:73], v[72:73]
	v_pk_add_f32 v[96:97], v[96:97], v[98:99]
	v_pk_mul_f32 v[98:99], v[74:75], v[74:75]
	v_pk_add_f32 v[96:97], v[96:97], v[96:97] op_sel_hi:[0,1]
	v_and_b32_e32 v159, 0xffff0000, v102
	v_lshlrev_b32_e32 v160, 16, v103
	v_and_b32_e32 v161, 0xffff0000, v103
	v_pk_mov_b32 v[102:103], v[100:101], v[98:99] op_sel:[1,0]
	v_mov_b32_e32 v101, v99
	v_mul_f32_e32 v96, v76, v76
	v_pk_add_f32 v[98:99], v[102:103], v[100:101]
	v_pk_fma_f32 v[100:101], v[76:77], v[76:77], v[96:97] op_sel_hi:[1,1,0]
	v_mul_f32_e32 v96, v78, v78
	v_pk_add_f32 v[98:99], v[98:99], v[98:99] op_sel_hi:[0,1]
	v_pk_fma_f32 v[102:103], v[78:79], v[78:79], v[96:97] op_sel_hi:[1,1,0]
	v_mul_f32_e32 v100, v80, v80
	v_mul_f32_e32 v102, v81, v81
	v_mul_f32_e32 v98, v82, v82
	v_mul_f32_e32 v96, v83, v83
	v_pk_add_f32 v[100:101], v[100:101], v[102:103]
	v_pk_add_f32 v[96:97], v[98:99], v[96:97]
	v_pk_mul_f32 v[98:99], v[86:87], v[86:87]
	v_pk_add_f32 v[96:97], v[100:101], v[96:97]
	v_pk_mul_f32 v[100:101], v[84:85], v[84:85]
	v_pk_add_f32 v[96:97], v[96:97], v[96:97] op_sel_hi:[0,1]
	v_pk_mov_b32 v[102:103], v[100:101], v[98:99] op_sel:[1,0]
	v_mov_b32_e32 v101, v99
	v_mul_f32_e32 v96, v88, v88
	v_pk_add_f32 v[98:99], v[102:103], v[100:101]
	v_pk_fma_f32 v[100:101], v[88:89], v[88:89], v[96:97] op_sel_hi:[1,1,0]
	v_mul_f32_e32 v96, v90, v90
	v_pk_add_f32 v[98:99], v[98:99], v[98:99] op_sel_hi:[0,1]
	v_pk_fma_f32 v[102:103], v[90:91], v[90:91], v[96:97] op_sel_hi:[1,1,0]
	v_mul_f32_e32 v100, v92, v92
	v_mul_f32_e32 v102, v93, v93
	v_mul_f32_e32 v98, v94, v94
	v_mul_f32_e32 v96, v95, v95
	v_pk_add_f32 v[100:101], v[100:101], v[102:103]
	v_pk_add_f32 v[96:97], v[98:99], v[96:97]
	s_lshl_b64 s[4:5], s[30:31], 13
	v_pk_add_f32 v[96:97], v[100:101], v[96:97]
	s_add_u32 s6, s61, s4
	v_add_f32_e32 v96, v96, v97
	ds_bpermute_b32 v97, v113, v96
	s_addc_u32 s7, s62, s5
	s_and_b64 s[4:5], s[48:49], exec
	s_cselect_b32 s55, s64, s7
	s_cselect_b32 s54, s63, s6
	s_waitcnt lgkmcnt(0)
	v_add_f32_e32 v96, v96, v97
	ds_bpermute_b32 v97, v176, v96
	s_min_i32 s4, s65, 0x4000
	s_lshr_b32 s4, s4, 13
	s_mulk_i32 s4, 0x6000
	v_add_u32_e32 v123, s4, v181
	s_waitcnt lgkmcnt(0)
	v_add_f32_e32 v96, v96, v97
	ds_bpermute_b32 v97, v177, v96
	v_lshlrev_b32_e32 v174, 16, v110
	v_and_b32_e32 v175, 0xffff0000, v110
	v_lshlrev_b32_e32 v110, 16, v111
	v_and_b32_e32 v111, 0xffff0000, v111
	s_waitcnt lgkmcnt(0)
	v_add_f32_e32 v96, v96, v97
	ds_bpermute_b32 v97, v178, v96
	v_lshlrev_b32_e32 v170, 16, v108
	v_and_b32_e32 v171, 0xffff0000, v108
	v_lshlrev_b32_e32 v172, 16, v109
	v_and_b32_e32 v173, 0xffff0000, v109
	s_waitcnt lgkmcnt(0)
	v_add_f32_e32 v96, v96, v97
	ds_bpermute_b32 v97, v179, v96
	v_lshlrev_b32_e32 v166, 16, v106
	v_and_b32_e32 v167, 0xffff0000, v106
	v_lshlrev_b32_e32 v168, 16, v107
	v_and_b32_e32 v169, 0xffff0000, v107
	s_waitcnt lgkmcnt(0)
	v_add_f32_e32 v96, v96, v97
	ds_bpermute_b32 v97, v180, v96
	v_lshlrev_b32_e32 v162, 16, v104
	v_and_b32_e32 v163, 0xffff0000, v104
	v_lshlrev_b32_e32 v164, 16, v105
	v_and_b32_e32 v165, 0xffff0000, v105
	s_waitcnt lgkmcnt(0)
	v_add_f32_e32 v96, v96, v97
	v_fmamk_f32 v96, v96, 0x3a000000, v196
	v_cmp_gt_f32_e32 vcc, s78, v96
	v_mul_f32_e32 v97, 0x4b800000, v96
	s_nop 0
	v_cndmask_b32_e32 v96, v96, v97, vcc
	v_rsq_f32_e32 v96, v96
	s_nop 0
	v_mul_f32_e32 v97, 0x45800000, v96
	v_cndmask_b32_e32 v182, v96, v97, vcc
	ds_read_b128 v[96:99], v123 offset:16384
	v_pk_mul_f32 v[66:67], v[66:67], v[182:183] op_sel_hi:[1,0]
	v_pk_mul_f32 v[64:65], v[64:65], v[182:183] op_sel_hi:[1,0]
	v_pk_mul_f32 v[66:67], v[2:3], v[66:67]
	v_pk_mul_f32 v[64:65], v[0:1], v[64:65]
	s_waitcnt lgkmcnt(0)
	v_pk_fma_f32 v[110:111], v[98:99], v[66:67], v[110:111]
	v_pk_fma_f32 v[108:109], v[96:97], v[64:65], v[174:175]
	ds_read_b128 v[64:67], v123 offset:17408
	v_pk_mul_f32 v[70:71], v[70:71], v[182:183] op_sel_hi:[1,0]
	v_pk_mul_f32 v[68:69], v[68:69], v[182:183] op_sel_hi:[1,0]
	v_pk_mul_f32 v[70:71], v[6:7], v[70:71]
	v_pk_mul_f32 v[68:69], v[4:5], v[68:69]
	s_waitcnt lgkmcnt(0)
; #define LAS __attribute__((address_space(3)))
; __device__ __forceinline__ unsigned pk2(float lo, float hi) { return f2bf(lo) | (f2bf(hi) << 16); }
; __device__ __forceinline__ void pass_post(const bf16* o16, const float* opart, const float* hlat, const float* hctx, const bf16* h16in, float* olat, float* octx, bf16* h16out, const float* gpost, const float* mod, int gt_off, ...
;     ...
;             const float rstd = rsqrtf(wave_sum(ss[r], lane) * (1.0f / DM) + EPS); float s2 = 0.f;
; #pragma unroll
;             for (int j = 0; j < 8; ++j) { const int ci = 256 * j + 4 * lane; const f32x4 g4 = *(const LAS f32x4*)(lp + ci), t4 = *(const LAS f32x4*)(mv + ci);
;                 const f32x4 nv = hh[r][j] + t4 * (v[r][j] * rstd * g4); v[r][j] = nv;
;                 if (h16out) { v2u w; w.x = pk2(nv[0], nv[1]); w.y = pk2(nv[2], nv[3]); *(v2u*)(h16out + (size_t)m * DM + ci) = w; } else *(f32x4*)(hd + ci) = nv;
;                 s2 += (nv[0] * nv[0] + nv[1] * nv[1]) + (nv[2] * nv[2] + nv[3] * nv[3]); }
;             if (U) { const float rstd2 = rsqrtf(wave_sum(s2, lane) * (1.0f / DM) + EPS); store_u(U + (size_t)m * DM, lane, v[r], rstd2, lp + 2048, mv + 2048, mv + 4096); }
	v_pk_fma_f32 v[106:107], v[66:67], v[70:71], v[172:173]
	v_pk_fma_f32 v[104:105], v[64:65], v[68:69], v[170:171]
	ds_read_b128 v[64:67], v123 offset:18432
	v_pk_mul_f32 v[68:69], v[74:75], v[182:183] op_sel_hi:[1,0]
	v_pk_mul_f32 v[70:71], v[72:73], v[182:183] op_sel_hi:[1,0]
	v_pk_mul_f32 v[68:69], v[10:11], v[68:69]
	v_pk_mul_f32 v[70:71], v[8:9], v[70:71]
	s_waitcnt lgkmcnt(0)
	v_pk_fma_f32 v[102:103], v[66:67], v[68:69], v[168:169]
	v_pk_fma_f32 v[100:101], v[64:65], v[70:71], v[166:167]
	ds_read_b128 v[64:67], v123 offset:19456
	v_pk_mul_f32 v[68:69], v[78:79], v[182:183] op_sel_hi:[1,0]
	v_pk_mul_f32 v[70:71], v[76:77], v[182:183] op_sel_hi:[1,0]
	v_pk_mul_f32 v[68:69], v[14:15], v[68:69]
	v_pk_mul_f32 v[70:71], v[12:13], v[70:71]
	s_waitcnt lgkmcnt(0)
	v_pk_fma_f32 v[98:99], v[66:67], v[68:69], v[164:165]
	v_pk_fma_f32 v[96:97], v[64:65], v[70:71], v[162:163]
	ds_read_b128 v[64:67], v123 offset:20480
	v_pk_mul_f32 v[68:69], v[80:81], v[182:183] op_sel_hi:[1,0]
	v_pk_mul_f32 v[70:71], v[82:83], v[182:183] op_sel_hi:[1,0]
	v_pk_mul_f32 v[68:69], v[68:69], v[16:17]
	v_pk_mul_f32 v[70:71], v[70:71], v[18:19]
	s_waitcnt lgkmcnt(0)
	v_pk_fma_f32 v[76:77], v[64:65], v[68:69], v[158:159]
	v_pk_fma_f32 v[78:79], v[66:67], v[70:71], v[160:161]
	ds_read_b128 v[64:67], v123 offset:21504
	v_pk_mul_f32 v[68:69], v[84:85], v[182:183] op_sel_hi:[1,0]
	v_pk_mul_f32 v[70:71], v[86:87], v[182:183] op_sel_hi:[1,0]
	v_pk_mul_f32 v[68:69], v[68:69], v[20:21]
	v_pk_mul_f32 v[70:71], v[70:71], v[22:23]
	s_waitcnt lgkmcnt(0)
	v_pk_fma_f32 v[72:73], v[64:65], v[68:69], v[156:157]
	v_pk_fma_f32 v[74:75], v[66:67], v[70:71], v[154:155]
	ds_read_b128 v[64:67], v123 offset:22528
	v_pk_mul_f32 v[68:69], v[88:89], v[182:183] op_sel_hi:[1,0]
	v_pk_mul_f32 v[70:71], v[90:91], v[182:183] op_sel_hi:[1,0]
	v_pk_mul_f32 v[68:69], v[68:69], v[24:25]
	v_pk_mul_f32 v[70:71], v[70:71], v[26:27]
	s_waitcnt lgkmcnt(0)
	v_pk_fma_f32 v[68:69], v[64:65], v[68:69], v[150:151]
	v_pk_fma_f32 v[70:71], v[66:67], v[70:71], v[152:153]
	ds_read_b128 v[64:67], v123 offset:23552
	v_pk_mul_f32 v[80:81], v[92:93], v[182:183] op_sel_hi:[1,0]
	v_pk_mul_f32 v[82:83], v[94:95], v[182:183] op_sel_hi:[1,0]
	v_pk_mul_f32 v[80:81], v[80:81], v[28:29]
	v_pk_mul_f32 v[82:83], v[82:83], v[30:31]
	s_waitcnt lgkmcnt(0)
	v_pk_fma_f32 v[64:65], v[64:65], v[80:81], v[148:149]
	v_pk_fma_f32 v[66:67], v[66:67], v[82:83], v[146:147]
	s_and_b64 vcc, exec, s[40:41]
	global_store_dwordx4 v194, v[108:111], s[54:55] sc0 sc1
	global_store_dwordx4 v194, v[104:107], s[54:55] offset:1024 sc0 sc1
	global_store_dwordx4 v194, v[100:103], s[54:55] offset:2048 sc0 sc1
	global_store_dwordx4 v194, v[96:99], s[54:55] offset:3072 sc0 sc1
	global_store_dwordx4 v122, v[76:79], s[54:55] sc0 sc1
	global_store_dwordx4 v124, v[72:75], s[54:55] sc0 sc1
	global_store_dwordx4 v126, v[68:71], s[54:55] sc0 sc1
	global_store_dwordx4 v128, v[64:67], s[54:55] sc0 sc1
	s_cbranch_vccnz .LBB0_1218
	v_mov_b32_e32 v82, v109
	v_mov_b32_e32 v83, v105
	v_mov_b32_e32 v80, v108
	v_mov_b32_e32 v81, v104
	v_pk_mul_f32 v[82:83], v[82:83], v[82:83]
	v_mov_b32_e32 v84, v111
	v_mov_b32_e32 v85, v107
	v_pk_fma_f32 v[80:81], v[80:81], v[80:81], v[82:83]
	v_mov_b32_e32 v82, v110
	v_mov_b32_e32 v83, v106
	v_pk_mul_f32 v[84:85], v[84:85], v[84:85]
	s_add_u32 s6, s18, s44
	v_pk_fma_f32 v[82:83], v[82:83], v[82:83], v[84:85]
	v_pk_mul_f32 v[84:85], v[100:101], v[100:101]
	v_pk_add_f32 v[80:81], v[80:81], v[82:83]
	v_pk_mul_f32 v[82:83], v[102:103], v[102:103]
	v_pk_add_f32 v[80:81], v[80:81], v[80:81] op_sel_hi:[0,1]
	v_pk_mov_b32 v[86:87], v[84:85], v[82:83] op_sel:[1,0]
	v_mov_b32_e32 v85, v83
	v_mul_f32_e32 v80, v96, v96
	v_pk_add_f32 v[82:83], v[86:87], v[84:85]
	v_pk_fma_f32 v[84:85], v[96:97], v[96:97], v[80:81] op_sel_hi:[1,1,0]
	v_mul_f32_e32 v80, v98, v98
	v_pk_add_f32 v[82:83], v[82:83], v[82:83] op_sel_hi:[0,1]
	v_pk_fma_f32 v[86:87], v[98:99], v[98:99], v[80:81] op_sel_hi:[1,1,0]
	v_mul_f32_e32 v84, v76, v76
	v_mul_f32_e32 v86, v77, v77
	v_mul_f32_e32 v82, v78, v78
	v_mul_f32_e32 v80, v79, v79
	v_pk_add_f32 v[84:85], v[84:85], v[86:87]
	v_pk_add_f32 v[80:81], v[82:83], v[80:81]
	v_pk_mul_f32 v[82:83], v[74:75], v[74:75]
	v_pk_add_f32 v[80:81], v[84:85], v[80:81]
	v_pk_mul_f32 v[84:85], v[72:73], v[72:73]
	v_pk_add_f32 v[80:81], v[80:81], v[80:81] op_sel:[0,1] op_sel_hi:[1,0]
	v_pk_mov_b32 v[86:87], v[84:85], v[82:83] op_sel:[1,0]
	v_mov_b32_e32 v85, v83
	v_pk_add_f32 v[82:83], v[86:87], v[84:85]
	v_mul_f32_e32 v84, v64, v64
	v_mul_f32_e32 v85, v65, v65
	v_pk_add_f32 v[82:83], v[82:83], v[82:83] op_sel:[0,1] op_sel_hi:[1,0]
	v_mov_b32_e32 v81, v84
	v_mov_b32_e32 v83, v85
	v_pk_add_f32 v[80:81], v[80:81], v[82:83]
	v_mul_f32_e32 v82, v69, v69
	v_mul_f32_e32 v84, v71, v71
	v_mul_f32_e32 v86, v66, v66
	v_mul_f32_e32 v87, v67, v67
	v_pk_fma_f32 v[82:83], v[68:69], v[68:69], v[82:83] op_sel_hi:[1,1,0]
	v_pk_fma_f32 v[84:85], v[70:71], v[70:71], v[84:85] op_sel_hi:[1,1,0]
	v_mov_b32_e32 v83, v86
	v_mov_b32_e32 v85, v87
	v_pk_add_f32 v[82:83], v[82:83], v[84:85]
	ds_read_b128 v[84:87], v181 offset:8192
	ds_read_b128 v[88:91], v123 offset:32768
	ds_read_b128 v[92:95], v123 offset:24576
	v_pk_add_f32 v[80:81], v[80:81], v[82:83]
	s_addc_u32 s7, s19, s45
	v_add_f32_e32 v80, v80, v81
	ds_bpermute_b32 v81, v113, v80
	s_waitcnt lgkmcnt(2)
	v_pk_add_f32 v[88:89], v[88:89], 1.0 op_sel_hi:[1,0]
	s_and_b64 s[4:5], s[48:49], exec
	s_cselect_b32 s5, s7, 0
	s_cselect_b32 s4, s6, s65
	s_waitcnt lgkmcnt(0)
	v_add_f32_e32 v80, v80, v81
	ds_bpermute_b32 v81, v176, v80
	s_lshl_b64 s[48:49], s[4:5], 12
	s_waitcnt lgkmcnt(0)
	v_add_f32_e32 v80, v80, v81
	ds_bpermute_b32 v81, v177, v80
	s_waitcnt lgkmcnt(0)
; #define LAS __attribute__((address_space(3)))
; __device__ __forceinline__ unsigned pk2(float lo, float hi) { return f2bf(lo) | (f2bf(hi) << 16); }
; __device__ __forceinline__ void store_u(bf16* urow, int lane, const f32x4 (&v)[8], float rstd, const LAS float* g, const LAS float* sh, const LAS float* sc) {
; #pragma unroll
;     for (int j = 0; j < 8; ++j) { const int ci = 256 * j + 4 * lane; const f32x4 g4 = *(const LAS f32x4*)(g + ci), s4 = *(const LAS f32x4*)(sc + ci), h4 = *(const LAS f32x4*)(sh + ci);
;         const f32x4 t = (v[j] * rstd * g4) * (1.0f + s4) + h4; v2u w; w.x = pk2(t[0], t[1]); w.y = pk2(t[2], t[3]); *(v2u*)(urow + ci) = w; }
; }
; __device__ __forceinline__ void pass_post(const bf16* o16, const float* opart, const float* hlat, const float* hctx, const bf16* h16in, float* olat, float* octx, bf16* h16out, const float* gpost, const float* mod, int gt_off, ...
;     ...
;             if (U) { const float rstd2 = rsqrtf(wave_sum(s2, lane) * (1.0f / DM) + EPS); store_u(U + (size_t)m * DM, lane, v[r], rstd2, lp + 2048, mv + 2048, mv + 4096); }
	v_add_f32_e32 v80, v80, v81
	ds_bpermute_b32 v81, v178, v80
	s_waitcnt lgkmcnt(0)
	v_add_f32_e32 v80, v80, v81
	ds_bpermute_b32 v81, v179, v80
	s_waitcnt lgkmcnt(0)
	v_add_f32_e32 v80, v80, v81
	ds_bpermute_b32 v81, v180, v80
	s_waitcnt lgkmcnt(0)
	v_add_f32_e32 v80, v80, v81
	v_fmamk_f32 v80, v80, 0x3a000000, v196
	v_cmp_gt_f32_e32 vcc, s78, v80
	v_mul_f32_e32 v81, 0x4b800000, v80
	s_nop 0
	v_cndmask_b32_e32 v80, v80, v81, vcc
	v_rsq_f32_e32 v80, v80
	s_nop 0
	v_mul_f32_e32 v81, 0x45800000, v80
	v_cndmask_b32_e32 v82, v80, v81, vcc
	v_pk_mul_f32 v[108:109], v[108:109], v[82:83] op_sel_hi:[1,0]
	v_pk_mul_f32 v[80:81], v[110:111], v[82:83] op_sel_hi:[1,0]
	v_pk_mul_f32 v[84:85], v[84:85], v[108:109]
	v_pk_mul_f32 v[80:81], v[86:87], v[80:81]
	v_pk_fma_f32 v[84:85], v[88:89], v[84:85], v[92:93]
	v_pk_add_f32 v[86:87], v[90:91], 1.0 op_sel_hi:[1,0]
	v_bfe_u32 v83, v84, 16, 1
	v_add3_u32 v83, v84, v83, s79
	v_bfe_u32 v84, v85, 16, 1
	v_pk_fma_f32 v[80:81], v[86:87], v[80:81], v[94:95]
	v_lshrrev_b32_e32 v83, 16, v83
	v_add3_u32 v84, v85, v84, s79
	v_and_or_b32 v84, v84, s75, v83
	v_bfe_u32 v83, v80, 16, 1
	v_add3_u32 v80, v80, v83, s79
	v_bfe_u32 v83, v81, 16, 1
	v_lshrrev_b32_e32 v80, 16, v80
	v_add3_u32 v81, v81, v83, s79
	v_and_or_b32 v85, v81, s75, v80
	v_lshl_add_u64 v[80:81], v[118:119], 0, s[48:49]
	global_store_dwordx2 v[80:81], v[84:85], off sc0 sc1
	ds_read_b128 v[84:87], v181 offset:9216
	ds_read_b128 v[88:91], v123 offset:33792
	ds_read_b128 v[92:95], v123 offset:25600
	v_pk_mul_f32 v[104:105], v[104:105], v[82:83] op_sel_hi:[1,0]
	v_pk_mul_f32 v[106:107], v[106:107], v[82:83] op_sel_hi:[1,0]
	s_waitcnt lgkmcnt(2)
	v_pk_mul_f32 v[84:85], v[84:85], v[104:105]
	s_waitcnt lgkmcnt(1)
	v_pk_add_f32 v[88:89], v[88:89], 1.0 op_sel_hi:[1,0]
	v_pk_mul_f32 v[86:87], v[86:87], v[106:107]
	s_waitcnt lgkmcnt(0)
	v_pk_fma_f32 v[84:85], v[88:89], v[84:85], v[92:93]
	v_pk_add_f32 v[90:91], v[90:91], 1.0 op_sel_hi:[1,0]
	v_bfe_u32 v83, v84, 16, 1
	v_add3_u32 v83, v84, v83, s79
	v_bfe_u32 v84, v85, 16, 1
	v_pk_fma_f32 v[86:87], v[90:91], v[86:87], v[94:95]
	v_lshrrev_b32_e32 v83, 16, v83
	v_add3_u32 v84, v85, v84, s79
	v_and_or_b32 v84, v84, s75, v83
	v_bfe_u32 v83, v86, 16, 1
	v_add3_u32 v83, v86, v83, s79
	v_bfe_u32 v85, v87, 16, 1
	v_lshrrev_b32_e32 v83, 16, v83
	v_add3_u32 v85, v87, v85, s79
	v_and_or_b32 v85, v85, s75, v83
	global_store_dwordx2 v[80:81], v[84:85], off offset:512 sc0 sc1
	ds_read_b128 v[84:87], v181 offset:10240
	ds_read_b128 v[88:91], v123 offset:34816
	ds_read_b128 v[92:95], v123 offset:26624
	v_pk_mul_f32 v[100:101], v[100:101], v[82:83] op_sel_hi:[1,0]
	v_pk_mul_f32 v[102:103], v[102:103], v[82:83] op_sel_hi:[1,0]
	s_waitcnt lgkmcnt(2)
	v_pk_mul_f32 v[84:85], v[84:85], v[100:101]
	s_waitcnt lgkmcnt(1)
	v_pk_add_f32 v[88:89], v[88:89], 1.0 op_sel_hi:[1,0]
	v_pk_mul_f32 v[86:87], v[86:87], v[102:103]
	s_waitcnt lgkmcnt(0)
	v_pk_fma_f32 v[84:85], v[88:89], v[84:85], v[92:93]
	v_pk_add_f32 v[90:91], v[90:91], 1.0 op_sel_hi:[1,0]
	v_bfe_u32 v83, v84, 16, 1
	v_add3_u32 v83, v84, v83, s79
	v_bfe_u32 v84, v85, 16, 1
	v_pk_fma_f32 v[86:87], v[90:91], v[86:87], v[94:95]
	v_lshrrev_b32_e32 v83, 16, v83
	v_add3_u32 v84, v85, v84, s79
	v_and_or_b32 v84, v84, s75, v83
	v_bfe_u32 v83, v86, 16, 1
	v_add3_u32 v83, v86, v83, s79
	v_bfe_u32 v85, v87, 16, 1
	v_lshrrev_b32_e32 v83, 16, v83
	v_add3_u32 v85, v87, v85, s79
	v_and_or_b32 v85, v85, s75, v83
	global_store_dwordx2 v[80:81], v[84:85], off offset:1024 sc0 sc1
	ds_read_b128 v[84:87], v181 offset:11264
	ds_read_b128 v[88:91], v123 offset:35840
	ds_read_b128 v[92:95], v123 offset:27648
	v_pk_mul_f32 v[96:97], v[96:97], v[82:83] op_sel_hi:[1,0]
	v_pk_mul_f32 v[98:99], v[98:99], v[82:83] op_sel_hi:[1,0]
	s_waitcnt lgkmcnt(2)
	v_pk_mul_f32 v[84:85], v[96:97], v[84:85]
	s_waitcnt lgkmcnt(1)
	v_pk_add_f32 v[88:89], v[88:89], 1.0 op_sel_hi:[1,0]
	v_pk_mul_f32 v[86:87], v[98:99], v[86:87]
	s_waitcnt lgkmcnt(0)
; #define LAS __attribute__((address_space(3)))
; __device__ __forceinline__ unsigned pk2(float lo, float hi) { return f2bf(lo) | (f2bf(hi) << 16); }
; __device__ __forceinline__ void store_u(bf16* urow, int lane, const f32x4 (&v)[8], float rstd, const LAS float* g, const LAS float* sh, const LAS float* sc) {
; #pragma unroll
;     for (int j = 0; j < 8; ++j) { const int ci = 256 * j + 4 * lane; const f32x4 g4 = *(const LAS f32x4*)(g + ci), s4 = *(const LAS f32x4*)(sc + ci), h4 = *(const LAS f32x4*)(sh + ci);
;         const f32x4 t = (v[j] * rstd * g4) * (1.0f + s4) + h4; v2u w; w.x = pk2(t[0], t[1]); w.y = pk2(t[2], t[3]); *(v2u*)(urow + ci) = w; }
; }
; __device__ __forceinline__ void pass_post(const bf16* o16, const float* opart, const float* hlat, const float* hctx, const bf16* h16in, float* olat, float* octx, bf16* h16out, const float* gpost, const float* mod, int gt_off, ...
;     ...
;         for (int r = 0; r < 2; ++r) { const int m = mr[r]; if (r == 1 && !two) break;
;             float* hd = m < MLAT ? olat + (size_t)m * DM : octx + (size_t)(m - MLAT) * DM; const int vi = (m < MLAT ? (m >> 13) : 2); const LAS float* mv = lp + 4096 + 3 * vi * 2048;
;             const float rstd = rsqrtf(wave_sum(ss[r], lane) * (1.0f / DM) + EPS); float s2 = 0.f;
; #pragma unroll
;             for (int j = 0; j < 8; ++j) { const int ci = 256 * j + 4 * lane; const f32x4 g4 = *(const LAS f32x4*)(lp + ci), t4 = *(const LAS f32x4*)(mv + ci);
;                 const f32x4 nv = hh[r][j] + t4 * (v[r][j] * rstd * g4); v[r][j] = nv;
;                 if (h16out) { v2u w; w.x = pk2(nv[0], nv[1]); w.y = pk2(nv[2], nv[3]); *(v2u*)(h16out + (size_t)m * DM + ci) = w; } else *(f32x4*)(hd + ci) = nv;
;                 s2 += (nv[0] * nv[0] + nv[1] * nv[1]) + (nv[2] * nv[2] + nv[3] * nv[3]); }
;             if (U) { const float rstd2 = rsqrtf(wave_sum(s2, lane) * (1.0f / DM) + EPS); store_u(U + (size_t)m * DM, lane, v[r], rstd2, lp + 2048, mv + 2048, mv + 4096); }
	v_pk_fma_f32 v[84:85], v[84:85], v[88:89], v[92:93]
	v_pk_add_f32 v[90:91], v[90:91], 1.0 op_sel_hi:[1,0]
	v_bfe_u32 v83, v84, 16, 1
	v_add3_u32 v83, v84, v83, s79
	v_bfe_u32 v84, v85, 16, 1
	v_pk_fma_f32 v[86:87], v[86:87], v[90:91], v[94:95]
	v_lshrrev_b32_e32 v83, 16, v83
	v_add3_u32 v84, v85, v84, s79
	v_and_or_b32 v84, v84, s75, v83
	v_bfe_u32 v83, v86, 16, 1
	v_add3_u32 v83, v86, v83, s79
	v_bfe_u32 v85, v87, 16, 1
	v_lshrrev_b32_e32 v83, 16, v83
	v_add3_u32 v85, v87, v85, s79
	v_and_or_b32 v85, v85, s75, v83
	global_store_dwordx2 v[80:81], v[84:85], off offset:1536 sc0 sc1
	ds_read_b128 v[84:87], v181 offset:12288
	ds_read_b128 v[88:91], v123 offset:36864
	ds_read_b128 v[92:95], v123 offset:28672
	v_pk_mul_f32 v[78:79], v[78:79], v[82:83] op_sel_hi:[1,0]
	v_pk_mul_f32 v[76:77], v[76:77], v[82:83] op_sel_hi:[1,0]
	s_waitcnt lgkmcnt(2)
	v_pk_mul_f32 v[78:79], v[78:79], v[86:87]
	v_pk_mul_f32 v[76:77], v[76:77], v[84:85]
	s_waitcnt lgkmcnt(1)
	v_pk_add_f32 v[86:87], v[88:89], 1.0 op_sel_hi:[1,0]
	v_pk_add_f32 v[84:85], v[90:91], 1.0 op_sel_hi:[1,0]
	s_waitcnt lgkmcnt(0)
	v_pk_fma_f32 v[76:77], v[76:77], v[86:87], v[92:93]
	v_pk_fma_f32 v[78:79], v[78:79], v[84:85], v[94:95]
	v_bfe_u32 v83, v76, 16, 1
	v_add3_u32 v76, v76, v83, s79
	v_bfe_u32 v83, v77, 16, 1
	v_lshrrev_b32_e32 v76, 16, v76
	v_add3_u32 v77, v77, v83, s79
	v_and_or_b32 v76, v77, s75, v76
	v_bfe_u32 v77, v78, 16, 1
	v_add3_u32 v77, v78, v77, s79
	v_bfe_u32 v78, v79, 16, 1
	v_lshrrev_b32_e32 v77, 16, v77
	v_add3_u32 v78, v79, v78, s79
	v_and_or_b32 v77, v78, s75, v77
	global_store_dwordx2 v[80:81], v[76:77], off offset:2048 sc0 sc1
	ds_read_b128 v[76:79], v181 offset:13312
	ds_read_b128 v[84:87], v123 offset:37888
	ds_read_b128 v[88:91], v123 offset:29696
	v_pk_mul_f32 v[74:75], v[74:75], v[82:83] op_sel_hi:[1,0]
	v_pk_mul_f32 v[72:73], v[72:73], v[82:83] op_sel_hi:[1,0]
	s_waitcnt lgkmcnt(2)
	v_pk_mul_f32 v[74:75], v[74:75], v[78:79]
	v_pk_mul_f32 v[72:73], v[72:73], v[76:77]
	s_waitcnt lgkmcnt(1)
	v_pk_add_f32 v[78:79], v[84:85], 1.0 op_sel_hi:[1,0]
	v_pk_add_f32 v[76:77], v[86:87], 1.0 op_sel_hi:[1,0]
	s_waitcnt lgkmcnt(0)
	v_pk_fma_f32 v[72:73], v[72:73], v[78:79], v[88:89]
	v_pk_fma_f32 v[74:75], v[74:75], v[76:77], v[90:91]
	v_bfe_u32 v76, v72, 16, 1
	v_add3_u32 v72, v72, v76, s79
	v_bfe_u32 v76, v73, 16, 1
	v_lshrrev_b32_e32 v72, 16, v72
	v_add3_u32 v73, v73, v76, s79
	v_and_or_b32 v72, v73, s75, v72
	v_bfe_u32 v73, v74, 16, 1
	v_add3_u32 v73, v74, v73, s79
	v_bfe_u32 v74, v75, 16, 1
	v_lshrrev_b32_e32 v73, 16, v73
	v_add3_u32 v74, v75, v74, s79
	v_and_or_b32 v73, v74, s75, v73
	global_store_dwordx2 v[80:81], v[72:73], off offset:2560 sc0 sc1
	ds_read_b128 v[72:75], v181 offset:14336
	ds_read_b128 v[76:79], v123 offset:38912
	ds_read_b128 v[84:87], v123 offset:30720
	v_pk_mul_f32 v[70:71], v[70:71], v[82:83] op_sel_hi:[1,0]
	v_pk_mul_f32 v[68:69], v[68:69], v[82:83] op_sel_hi:[1,0]
	s_waitcnt lgkmcnt(2)
	v_pk_mul_f32 v[70:71], v[70:71], v[74:75]
	v_pk_mul_f32 v[68:69], v[68:69], v[72:73]
	s_waitcnt lgkmcnt(1)
	v_pk_add_f32 v[74:75], v[76:77], 1.0 op_sel_hi:[1,0]
	v_pk_add_f32 v[72:73], v[78:79], 1.0 op_sel_hi:[1,0]
	s_waitcnt lgkmcnt(0)
	v_pk_fma_f32 v[68:69], v[68:69], v[74:75], v[84:85]
	v_pk_fma_f32 v[70:71], v[70:71], v[72:73], v[86:87]
	v_bfe_u32 v72, v68, 16, 1
	v_add3_u32 v68, v68, v72, s79
	v_bfe_u32 v72, v69, 16, 1
	v_lshrrev_b32_e32 v68, 16, v68
	v_add3_u32 v69, v69, v72, s79
	v_and_or_b32 v68, v69, s75, v68
	v_bfe_u32 v69, v70, 16, 1
	v_add3_u32 v69, v70, v69, s79
	v_bfe_u32 v70, v71, 16, 1
	v_lshrrev_b32_e32 v69, 16, v69
	v_add3_u32 v70, v71, v70, s79
	v_and_or_b32 v69, v70, s75, v69
	global_store_dwordx2 v[80:81], v[68:69], off offset:3072 sc0 sc1
	ds_read_b128 v[68:71], v181 offset:15360
	ds_read_b128 v[72:75], v123 offset:39936
	ds_read_b128 v[76:79], v123 offset:31744
	v_pk_mul_f32 v[66:67], v[66:67], v[82:83] op_sel_hi:[1,0]
	v_pk_mul_f32 v[64:65], v[64:65], v[82:83] op_sel_hi:[1,0]
	s_waitcnt lgkmcnt(2)
	v_pk_mul_f32 v[66:67], v[66:67], v[70:71]
	v_pk_mul_f32 v[64:65], v[64:65], v[68:69]
	s_waitcnt lgkmcnt(1)
	v_pk_add_f32 v[70:71], v[72:73], 1.0 op_sel_hi:[1,0]
	v_pk_add_f32 v[68:69], v[74:75], 1.0 op_sel_hi:[1,0]
	s_waitcnt lgkmcnt(0)
	v_pk_fma_f32 v[64:65], v[64:65], v[70:71], v[76:77]
	v_pk_fma_f32 v[66:67], v[66:67], v[68:69], v[78:79]
	v_bfe_u32 v68, v64, 16, 1
	v_add3_u32 v64, v64, v68, s79
	v_bfe_u32 v68, v65, 16, 1
	v_lshrrev_b32_e32 v64, 16, v64
	v_add3_u32 v65, v65, v68, s79
	v_and_or_b32 v64, v65, s75, v64
	v_bfe_u32 v65, v66, 16, 1
	v_add3_u32 v65, v66, v65, s79
	v_bfe_u32 v66, v67, 16, 1
	v_lshrrev_b32_e32 v65, 16, v65
	v_add3_u32 v66, v67, v66, s79
	v_and_or_b32 v65, v66, s75, v65
	global_store_dwordx2 v[80:81], v[64:65], off offset:3584 sc0 sc1

; #define LAS __attribute__((address_space(3)))
; __device__ __forceinline__ void pass_post(const bf16* o16, const float* opart, const float* hlat, const float* hctx, const bf16* h16in, float* olat, float* octx, bf16* h16out, const float* gpost, const float* mod, int gt_off, ...
;     ...
;             if (h16in) { const bf16* hrow = h16in + (size_t)m * DM;
; #pragma unroll
;                 for (int j = 0; j < 8; ++j) { const v2u raw = *(const v2u*)(hrow + 256 * j + 4 * lane);
;                     hh[r][j] = (f32x4){__uint_as_float(raw.x << 16), __uint_as_float(raw.x & 0xffff0000u), __uint_as_float(raw.y << 16), __uint_as_float(raw.y & 0xffff0000u)}; }
;             } else {
; #pragma unroll
;                 for (int j = 0; j < 8; ++j) hh[r][j] = *(const f32x4*)(hs + 256 * j + 4 * lane); }
;         }
; #pragma unroll
;         for (int r = 0; r < 2; ++r)
; #pragma unroll
;             for (int j = 0; j < 8; ++j) ss[r] += (v[r][j][0] * v[r][j][0] + v[r][j][1] * v[r][j][1]) + (v[r][j][2] * v[r][j][2] + v[r][j][3] * v[r][j][3]);
; #pragma unroll
;         for (int r = 0; r < 2; ++r) { const int m = mr[r]; if (r == 1 && !two) break;
;             float* hd = m < MLAT ? olat + (size_t)m * DM : octx + (size_t)(m - MLAT) * DM; const int vi = (m < MLAT ? (m >> 13) : 2); const LAS float* mv = lp + 4096 + 3 * vi * 2048;
;             const float rstd = rsqrtf(wave_sum(ss[r], lane) * (1.0f / DM) + EPS); float s2 = 0.f;
; #pragma unroll
;             for (int j = 0; j < 8; ++j) { const int ci = 256 * j + 4 * lane; const f32x4 g4 = *(const LAS f32x4*)(lp + ci), t4 = *(const LAS f32x4*)(mv + ci);
;                 const f32x4 nv = hh[r][j] + t4 * (v[r][j] * rstd * g4); v[r][j] = nv;
.LBB0_1223:
	v_mul_f32_e32 v96, v33, v33
	v_mul_f32_e32 v97, v35, v35
	v_fmac_f32_e32 v96, v32, v32
	v_fmac_f32_e32 v97, v34, v34
	v_add_f32_e32 v96, v96, v97
	v_mul_f32_e32 v97, v37, v37
	v_mul_f32_e32 v98, v39, v39
	v_fmac_f32_e32 v97, v36, v36
	v_fmac_f32_e32 v98, v38, v38
	v_add_f32_e32 v97, v97, v98
	v_add_f32_e32 v96, v97, v96
	v_mul_f32_e32 v97, v41, v41
	v_mul_f32_e32 v98, v43, v43
	v_fmac_f32_e32 v97, v40, v40
	v_fmac_f32_e32 v98, v42, v42
	v_add_f32_e32 v97, v97, v98
	v_add_f32_e32 v96, v97, v96
	v_mul_f32_e32 v97, v45, v45
	v_mul_f32_e32 v98, v47, v47
	v_fmac_f32_e32 v97, v44, v44
	v_fmac_f32_e32 v98, v46, v46
	v_add_f32_e32 v97, v97, v98
	v_add_f32_e32 v96, v97, v96
	v_mul_f32_e32 v97, v49, v49
	v_mul_f32_e32 v98, v51, v51
	v_fmac_f32_e32 v97, v48, v48
	v_fmac_f32_e32 v98, v50, v50
	v_add_f32_e32 v97, v97, v98
	v_add_f32_e32 v96, v97, v96
	v_mul_f32_e32 v97, v53, v53
	v_mul_f32_e32 v98, v55, v55
	v_fmac_f32_e32 v97, v52, v52
	v_fmac_f32_e32 v98, v54, v54
	v_add_f32_e32 v97, v97, v98
	v_add_f32_e32 v96, v97, v96
	v_mul_f32_e32 v97, v57, v57
	v_mul_f32_e32 v98, v59, v59
	v_fmac_f32_e32 v97, v56, v56
	v_fmac_f32_e32 v98, v58, v58
	v_add_f32_e32 v97, v97, v98
	v_add_f32_e32 v96, v97, v96
	v_mul_f32_e32 v97, v61, v61
	v_mul_f32_e32 v98, v63, v63
	v_fmac_f32_e32 v97, v60, v60
	v_fmac_f32_e32 v98, v62, v62
	v_add_f32_e32 v97, v97, v98
	v_add_f32_e32 v96, v97, v96
	ds_bpermute_b32 v97, v113, v96
	s_min_i32 s4, s46, 0x4000
	s_lshr_b32 s4, s4, 13
	s_mulk_i32 s4, 0x6000
	s_waitcnt vmcnt(15)
	v_lshlrev_b32_e32 v76, 16, v144
	s_waitcnt lgkmcnt(0)
	v_add_f32_e32 v96, v96, v97
	ds_bpermute_b32 v97, v176, v96
	v_and_b32_e32 v77, 0xffff0000, v144
	v_lshlrev_b32_e32 v78, 16, v145
	v_and_b32_e32 v79, 0xffff0000, v145
	s_waitcnt vmcnt(14)
	v_lshlrev_b32_e32 v72, 16, v142
	s_waitcnt lgkmcnt(0)
	v_add_f32_e32 v96, v96, v97
	ds_bpermute_b32 v97, v177, v96
	v_and_b32_e32 v73, 0xffff0000, v142
	v_lshlrev_b32_e32 v74, 16, v143
	v_and_b32_e32 v75, 0xffff0000, v143
	s_waitcnt vmcnt(13)
	v_lshlrev_b32_e32 v68, 16, v140
	s_waitcnt lgkmcnt(0)
	v_add_f32_e32 v96, v96, v97
	ds_bpermute_b32 v97, v178, v96
	v_and_b32_e32 v69, 0xffff0000, v140
	v_lshlrev_b32_e32 v70, 16, v141
	v_and_b32_e32 v71, 0xffff0000, v141
	s_waitcnt vmcnt(12)
	v_lshlrev_b32_e32 v64, 16, v138
	s_waitcnt lgkmcnt(0)
	v_add_f32_e32 v96, v96, v97
	ds_bpermute_b32 v97, v179, v96
	v_and_b32_e32 v65, 0xffff0000, v138
	v_lshlrev_b32_e32 v66, 16, v139
	v_and_b32_e32 v67, 0xffff0000, v139
	s_waitcnt vmcnt(11)
	v_lshlrev_b32_e32 v92, 16, v136
	s_waitcnt lgkmcnt(0)
	v_add_f32_e32 v96, v96, v97
	ds_bpermute_b32 v97, v180, v96
	v_and_b32_e32 v93, 0xffff0000, v136
	v_lshlrev_b32_e32 v94, 16, v137
	v_and_b32_e32 v95, 0xffff0000, v137
	s_waitcnt vmcnt(10)
	v_lshlrev_b32_e32 v88, 16, v134
	s_waitcnt lgkmcnt(0)
	v_add_f32_e32 v96, v96, v97
	v_fmamk_f32 v96, v96, 0x3a000000, v196
	v_cmp_gt_f32_e32 vcc, s78, v96
	v_mul_f32_e32 v97, 0x4b800000, v96
	v_and_b32_e32 v89, 0xffff0000, v134
	v_cndmask_b32_e32 v96, v96, v97, vcc
	v_rsq_f32_e32 v96, v96
	v_lshlrev_b32_e32 v90, 16, v135
	v_and_b32_e32 v91, 0xffff0000, v135
	s_waitcnt vmcnt(9)
	v_lshlrev_b32_e32 v84, 16, v132
	v_mul_f32_e32 v97, 0x45800000, v96
	v_cndmask_b32_e32 v102, v96, v97, vcc
	v_add_u32_e32 v96, s4, v181
	ds_read_b128 v[98:101], v96 offset:16384
	v_pk_mul_f32 v[34:35], v[34:35], v[102:103] op_sel_hi:[1,0]
	v_pk_mul_f32 v[32:33], v[32:33], v[102:103] op_sel_hi:[1,0]
	v_pk_mul_f32 v[34:35], v[2:3], v[34:35]
	v_pk_mul_f32 v[32:33], v[0:1], v[32:33]
	s_waitcnt lgkmcnt(0)
	v_pk_fma_f32 v[78:79], v[100:101], v[34:35], v[78:79]
	v_pk_fma_f32 v[76:77], v[98:99], v[32:33], v[76:77]
	ds_read_b128 v[32:35], v96 offset:17408
	v_pk_mul_f32 v[38:39], v[38:39], v[102:103] op_sel_hi:[1,0]
	v_pk_mul_f32 v[36:37], v[36:37], v[102:103] op_sel_hi:[1,0]
	v_pk_mul_f32 v[38:39], v[6:7], v[38:39]
	v_pk_mul_f32 v[36:37], v[4:5], v[36:37]
	s_waitcnt lgkmcnt(0)
	v_pk_fma_f32 v[74:75], v[34:35], v[38:39], v[74:75]
	v_pk_fma_f32 v[72:73], v[32:33], v[36:37], v[72:73]
	ds_read_b128 v[32:35], v96 offset:18432
	v_pk_mul_f32 v[36:37], v[42:43], v[102:103] op_sel_hi:[1,0]
	v_pk_mul_f32 v[38:39], v[40:41], v[102:103] op_sel_hi:[1,0]
	v_pk_mul_f32 v[36:37], v[10:11], v[36:37]
	v_pk_mul_f32 v[38:39], v[8:9], v[38:39]
	s_waitcnt lgkmcnt(0)
	v_pk_fma_f32 v[70:71], v[34:35], v[36:37], v[70:71]
	v_pk_fma_f32 v[68:69], v[32:33], v[38:39], v[68:69]
	ds_read_b128 v[32:35], v96 offset:19456
	v_pk_mul_f32 v[36:37], v[46:47], v[102:103] op_sel_hi:[1,0]
	v_pk_mul_f32 v[38:39], v[44:45], v[102:103] op_sel_hi:[1,0]
	v_pk_mul_f32 v[36:37], v[14:15], v[36:37]
	v_pk_mul_f32 v[38:39], v[12:13], v[38:39]
	s_waitcnt lgkmcnt(0)
	v_pk_fma_f32 v[66:67], v[34:35], v[36:37], v[66:67]
	v_pk_fma_f32 v[64:65], v[32:33], v[38:39], v[64:65]
	ds_read_b128 v[32:35], v96 offset:20480
	v_pk_mul_f32 v[36:37], v[50:51], v[102:103] op_sel_hi:[1,0]
	v_pk_mul_f32 v[38:39], v[48:49], v[102:103] op_sel_hi:[1,0]
	v_pk_mul_f32 v[36:37], v[18:19], v[36:37]
	v_pk_mul_f32 v[38:39], v[16:17], v[38:39]
	s_waitcnt lgkmcnt(0)
	v_pk_fma_f32 v[46:47], v[34:35], v[36:37], v[94:95]
	v_pk_fma_f32 v[44:45], v[32:33], v[38:39], v[92:93]
	ds_read_b128 v[32:35], v96 offset:21504
	v_pk_mul_f32 v[36:37], v[54:55], v[102:103] op_sel_hi:[1,0]
	v_pk_mul_f32 v[38:39], v[52:53], v[102:103] op_sel_hi:[1,0]
	v_pk_mul_f32 v[36:37], v[22:23], v[36:37]
	v_pk_mul_f32 v[38:39], v[20:21], v[38:39]
	s_waitcnt lgkmcnt(0)
; #define LAS __attribute__((address_space(3)))
; __device__ __forceinline__ unsigned pk2(float lo, float hi) { return f2bf(lo) | (f2bf(hi) << 16); }
; __device__ __forceinline__ void store_u(bf16* urow, int lane, const f32x4 (&v)[8], float rstd, const LAS float* g, const LAS float* sh, const LAS float* sc) {
; #pragma unroll
;     for (int j = 0; j < 8; ++j) { const int ci = 256 * j + 4 * lane; const f32x4 g4 = *(const LAS f32x4*)(g + ci), s4 = *(const LAS f32x4*)(sc + ci), h4 = *(const LAS f32x4*)(sh + ci);
;         const f32x4 t = (v[j] * rstd * g4) * (1.0f + s4) + h4; v2u w; w.x = pk2(t[0], t[1]); w.y = pk2(t[2], t[3]); *(v2u*)(urow + ci) = w; }
; }
; __device__ __forceinline__ void pass_post(const bf16* o16, const float* opart, const float* hlat, const float* hctx, const bf16* h16in, float* olat, float* octx, bf16* h16out, const float* gpost, const float* mod, int gt_off, ...
;     ...
;         for (int r = 0; r < 2; ++r) { const int m = mr[r]; if (r == 1 && !two) break;
;             float* hd = m < MLAT ? olat + (size_t)m * DM : octx + (size_t)(m - MLAT) * DM; const int vi = (m < MLAT ? (m >> 13) : 2); const LAS float* mv = lp + 4096 + 3 * vi * 2048;
;             const float rstd = rsqrtf(wave_sum(ss[r], lane) * (1.0f / DM) + EPS); float s2 = 0.f;
; #pragma unroll
;             for (int j = 0; j < 8; ++j) { const int ci = 256 * j + 4 * lane; const f32x4 g4 = *(const LAS f32x4*)(lp + ci), t4 = *(const LAS f32x4*)(mv + ci);
;                 const f32x4 nv = hh[r][j] + t4 * (v[r][j] * rstd * g4); v[r][j] = nv;
;                 if (h16out) { v2u w; w.x = pk2(nv[0], nv[1]); w.y = pk2(nv[2], nv[3]); *(v2u*)(h16out + (size_t)m * DM + ci) = w; } else *(f32x4*)(hd + ci) = nv;
;                 s2 += (nv[0] * nv[0] + nv[1] * nv[1]) + (nv[2] * nv[2] + nv[3] * nv[3]); }
;             if (U) { const float rstd2 = rsqrtf(wave_sum(s2, lane) * (1.0f / DM) + EPS); store_u(U + (size_t)m * DM, lane, v[r], rstd2, lp + 2048, mv + 2048, mv + 4096); }
	v_pk_fma_f32 v[42:43], v[34:35], v[36:37], v[90:91]
	v_pk_fma_f32 v[40:41], v[32:33], v[38:39], v[88:89]
	ds_read_b128 v[32:35], v96 offset:22528
	v_pk_mul_f32 v[36:37], v[58:59], v[102:103] op_sel_hi:[1,0]
	v_pk_mul_f32 v[38:39], v[56:57], v[102:103] op_sel_hi:[1,0]
	v_and_b32_e32 v85, 0xffff0000, v132
	v_lshlrev_b32_e32 v86, 16, v133
	v_and_b32_e32 v87, 0xffff0000, v133
	v_pk_mul_f32 v[48:49], v[24:25], v[38:39]
	v_pk_mul_f32 v[36:37], v[26:27], v[36:37]
	v_pk_mul_f32 v[50:51], v[60:61], v[102:103] op_sel_hi:[1,0]
	s_waitcnt lgkmcnt(0)
	v_pk_fma_f32 v[38:39], v[34:35], v[36:37], v[86:87]
	v_pk_fma_f32 v[36:37], v[32:33], v[48:49], v[84:85]
	ds_read_b128 v[32:35], v96 offset:23552
	v_pk_mul_f32 v[48:49], v[62:63], v[102:103] op_sel_hi:[1,0]
	s_waitcnt vmcnt(8)
	v_lshlrev_b32_e32 v80, 16, v130
	v_and_b32_e32 v81, 0xffff0000, v130
	v_lshlrev_b32_e32 v82, 16, v131
	v_and_b32_e32 v83, 0xffff0000, v131
	v_pk_mul_f32 v[50:51], v[28:29], v[50:51]
	v_pk_mul_f32 v[48:49], v[30:31], v[48:49]
	s_waitcnt lgkmcnt(0)
	v_pk_fma_f32 v[32:33], v[50:51], v[32:33], v[80:81]
	v_pk_fma_f32 v[34:35], v[48:49], v[34:35], v[82:83]
	s_and_b64 vcc, exec, s[40:41]
	global_store_dwordx4 v194, v[76:79], s[48:49] sc0 sc1
	global_store_dwordx4 v194, v[72:75], s[48:49] offset:1024 sc0 sc1
	global_store_dwordx4 v194, v[68:71], s[48:49] offset:2048 sc0 sc1
	global_store_dwordx4 v194, v[64:67], s[48:49] offset:3072 sc0 sc1
	global_store_dwordx4 v122, v[44:47], s[48:49] sc0 sc1
	global_store_dwordx4 v124, v[40:43], s[48:49] sc0 sc1
	global_store_dwordx4 v126, v[36:39], s[48:49] sc0 sc1
	global_store_dwordx4 v128, v[32:35], s[48:49] sc0 sc1
	s_cbranch_vccnz .LBB0_1207
	v_mov_b32_e32 v50, v77
	v_mov_b32_e32 v51, v73
	v_mov_b32_e32 v48, v76
	v_mov_b32_e32 v49, v72
	v_pk_mul_f32 v[50:51], v[50:51], v[50:51]
	v_mov_b32_e32 v52, v79
	v_mov_b32_e32 v53, v75
	v_pk_fma_f32 v[48:49], v[48:49], v[48:49], v[50:51]
	v_mov_b32_e32 v50, v78
	v_mov_b32_e32 v51, v74
	v_pk_mul_f32 v[52:53], v[52:53], v[52:53]
	s_lshl_b64 s[4:5], s[46:47], 12
	v_pk_fma_f32 v[50:51], v[50:51], v[50:51], v[52:53]
	v_pk_mul_f32 v[52:53], v[68:69], v[68:69]
	v_pk_add_f32 v[48:49], v[48:49], v[50:51]
	v_pk_mul_f32 v[50:51], v[70:71], v[70:71]
	v_pk_add_f32 v[48:49], v[48:49], v[48:49] op_sel_hi:[0,1]
	v_pk_mov_b32 v[54:55], v[52:53], v[50:51] op_sel:[1,0]
	v_mov_b32_e32 v53, v51
	v_mul_f32_e32 v48, v64, v64
	v_pk_add_f32 v[50:51], v[54:55], v[52:53]
	v_pk_fma_f32 v[52:53], v[64:65], v[64:65], v[48:49] op_sel_hi:[1,1,0]
	v_mul_f32_e32 v48, v66, v66
	v_pk_add_f32 v[50:51], v[50:51], v[50:51] op_sel_hi:[0,1]
	v_pk_fma_f32 v[54:55], v[66:67], v[66:67], v[48:49] op_sel_hi:[1,1,0]
	v_mul_f32_e32 v52, v44, v44
	v_mul_f32_e32 v54, v45, v45
	v_mul_f32_e32 v50, v46, v46
	v_mul_f32_e32 v48, v47, v47
	v_pk_add_f32 v[52:53], v[52:53], v[54:55]
	v_pk_add_f32 v[48:49], v[50:51], v[48:49]
	v_pk_mul_f32 v[50:51], v[42:43], v[42:43]
	v_pk_add_f32 v[48:49], v[52:53], v[48:49]
	v_pk_mul_f32 v[52:53], v[40:41], v[40:41]
	v_pk_add_f32 v[48:49], v[48:49], v[48:49] op_sel_hi:[0,1]
	v_pk_mov_b32 v[54:55], v[52:53], v[50:51] op_sel:[1,0]
	v_mov_b32_e32 v53, v51
	v_mul_f32_e32 v48, v36, v36
	v_pk_add_f32 v[50:51], v[54:55], v[52:53]
	v_pk_fma_f32 v[52:53], v[36:37], v[36:37], v[48:49] op_sel_hi:[1,1,0]
	v_mul_f32_e32 v48, v38, v38
	v_pk_add_f32 v[50:51], v[50:51], v[50:51] op_sel_hi:[0,1]
	v_pk_fma_f32 v[54:55], v[38:39], v[38:39], v[48:49] op_sel_hi:[1,1,0]
	v_mul_f32_e32 v52, v32, v32
	v_mul_f32_e32 v54, v33, v33
	v_mul_f32_e32 v50, v34, v34
	v_mul_f32_e32 v48, v35, v35
	v_pk_add_f32 v[52:53], v[52:53], v[54:55]
	v_pk_add_f32 v[48:49], v[50:51], v[48:49]
	s_nop 0
	v_pk_add_f32 v[48:49], v[52:53], v[48:49]
	ds_read_b128 v[52:55], v181 offset:8192
	ds_read_b128 v[56:59], v96 offset:32768
	ds_read_b128 v[60:63], v96 offset:24576
	v_add_f32_e32 v48, v48, v49
	ds_bpermute_b32 v49, v113, v48
	s_waitcnt lgkmcnt(2)
	v_pk_add_f32 v[56:57], v[56:57], 1.0 op_sel_hi:[1,0]
	s_waitcnt lgkmcnt(0)
	v_add_f32_e32 v48, v48, v49
	ds_bpermute_b32 v49, v176, v48
	s_waitcnt lgkmcnt(0)
	v_add_f32_e32 v48, v48, v49
	ds_bpermute_b32 v49, v177, v48
	s_waitcnt lgkmcnt(0)
	v_add_f32_e32 v48, v48, v49
	ds_bpermute_b32 v49, v178, v48
	s_waitcnt lgkmcnt(0)
	v_add_f32_e32 v48, v48, v49
	ds_bpermute_b32 v49, v179, v48
	s_waitcnt lgkmcnt(0)
	v_add_f32_e32 v48, v48, v49
	ds_bpermute_b32 v49, v180, v48
	s_waitcnt lgkmcnt(0)
	v_add_f32_e32 v48, v48, v49
	v_fmamk_f32 v48, v48, 0x3a000000, v196
	v_cmp_gt_f32_e32 vcc, s78, v48
	v_mul_f32_e32 v49, 0x4b800000, v48
	s_nop 0
	v_cndmask_b32_e32 v48, v48, v49, vcc
	v_rsq_f32_e32 v48, v48
	s_nop 0
	v_mul_f32_e32 v49, 0x45800000, v48
	v_cndmask_b32_e32 v50, v48, v49, vcc
	v_pk_mul_f32 v[76:77], v[76:77], v[50:51] op_sel_hi:[1,0]
	v_pk_mul_f32 v[48:49], v[78:79], v[50:51] op_sel_hi:[1,0]
	v_pk_mul_f32 v[52:53], v[52:53], v[76:77]
	v_pk_mul_f32 v[48:49], v[54:55], v[48:49]
	v_pk_fma_f32 v[52:53], v[56:57], v[52:53], v[60:61]
	v_pk_add_f32 v[54:55], v[58:59], 1.0 op_sel_hi:[1,0]
	v_bfe_u32 v51, v52, 16, 1
	v_add3_u32 v51, v52, v51, s79
	v_bfe_u32 v52, v53, 16, 1
	v_pk_fma_f32 v[48:49], v[54:55], v[48:49], v[62:63]
	v_lshrrev_b32_e32 v51, 16, v51
	v_add3_u32 v52, v53, v52, s79
	v_and_or_b32 v52, v52, s75, v51
	v_bfe_u32 v51, v48, 16, 1
	v_add3_u32 v48, v48, v51, s79
	v_bfe_u32 v51, v49, 16, 1
	v_lshrrev_b32_e32 v48, 16, v48
	v_add3_u32 v49, v49, v51, s79
	v_and_or_b32 v53, v49, s75, v48
	v_lshl_add_u64 v[48:49], v[118:119], 0, s[4:5]
	global_store_dwordx2 v[48:49], v[52:53], off sc0 sc1
	ds_read_b128 v[52:55], v181 offset:9216
	ds_read_b128 v[56:59], v96 offset:33792
	ds_read_b128 v[60:63], v96 offset:25600
	v_pk_mul_f32 v[72:73], v[72:73], v[50:51] op_sel_hi:[1,0]
	v_pk_mul_f32 v[74:75], v[74:75], v[50:51] op_sel_hi:[1,0]
	s_waitcnt lgkmcnt(2)
; #define LAS __attribute__((address_space(3)))
; __device__ __forceinline__ unsigned pk2(float lo, float hi) { return f2bf(lo) | (f2bf(hi) << 16); }
; __device__ __forceinline__ void store_u(bf16* urow, int lane, const f32x4 (&v)[8], float rstd, const LAS float* g, const LAS float* sh, const LAS float* sc) {
; #pragma unroll
;     for (int j = 0; j < 8; ++j) { const int ci = 256 * j + 4 * lane; const f32x4 g4 = *(const LAS f32x4*)(g + ci), s4 = *(const LAS f32x4*)(sc + ci), h4 = *(const LAS f32x4*)(sh + ci);
;         const f32x4 t = (v[j] * rstd * g4) * (1.0f + s4) + h4; v2u w; w.x = pk2(t[0], t[1]); w.y = pk2(t[2], t[3]); *(v2u*)(urow + ci) = w; }
; }
	v_pk_mul_f32 v[52:53], v[52:53], v[72:73]
	s_waitcnt lgkmcnt(1)
	v_pk_add_f32 v[56:57], v[56:57], 1.0 op_sel_hi:[1,0]
	v_pk_mul_f32 v[54:55], v[54:55], v[74:75]
	s_waitcnt lgkmcnt(0)
	v_pk_fma_f32 v[52:53], v[56:57], v[52:53], v[60:61]
	v_pk_add_f32 v[58:59], v[58:59], 1.0 op_sel_hi:[1,0]
	v_bfe_u32 v51, v52, 16, 1
	v_add3_u32 v51, v52, v51, s79
	v_bfe_u32 v52, v53, 16, 1
	v_pk_fma_f32 v[54:55], v[58:59], v[54:55], v[62:63]
	v_lshrrev_b32_e32 v51, 16, v51
	v_add3_u32 v52, v53, v52, s79
	v_and_or_b32 v52, v52, s75, v51
	v_bfe_u32 v51, v54, 16, 1
	v_add3_u32 v51, v54, v51, s79
	v_bfe_u32 v53, v55, 16, 1
	v_lshrrev_b32_e32 v51, 16, v51
	v_add3_u32 v53, v55, v53, s79
	v_and_or_b32 v53, v53, s75, v51
	global_store_dwordx2 v[48:49], v[52:53], off offset:512 sc0 sc1
	ds_read_b128 v[52:55], v181 offset:10240
	ds_read_b128 v[56:59], v96 offset:34816
	ds_read_b128 v[60:63], v96 offset:26624
	v_pk_mul_f32 v[68:69], v[68:69], v[50:51] op_sel_hi:[1,0]
	v_pk_mul_f32 v[70:71], v[70:71], v[50:51] op_sel_hi:[1,0]
	s_waitcnt lgkmcnt(2)
	v_pk_mul_f32 v[52:53], v[52:53], v[68:69]
	s_waitcnt lgkmcnt(1)
	v_pk_add_f32 v[56:57], v[56:57], 1.0 op_sel_hi:[1,0]
	v_pk_mul_f32 v[54:55], v[54:55], v[70:71]
	s_waitcnt lgkmcnt(0)
	v_pk_fma_f32 v[52:53], v[56:57], v[52:53], v[60:61]
	v_pk_add_f32 v[58:59], v[58:59], 1.0 op_sel_hi:[1,0]
	v_bfe_u32 v51, v52, 16, 1
	v_add3_u32 v51, v52, v51, s79
	v_bfe_u32 v52, v53, 16, 1
	v_pk_fma_f32 v[54:55], v[58:59], v[54:55], v[62:63]
	v_lshrrev_b32_e32 v51, 16, v51
	v_add3_u32 v52, v53, v52, s79
	v_and_or_b32 v52, v52, s75, v51
	v_bfe_u32 v51, v54, 16, 1
	v_add3_u32 v51, v54, v51, s79
	v_bfe_u32 v53, v55, 16, 1
	v_lshrrev_b32_e32 v51, 16, v51
	v_add3_u32 v53, v55, v53, s79
	v_and_or_b32 v53, v53, s75, v51
	global_store_dwordx2 v[48:49], v[52:53], off offset:1024 sc0 sc1
	ds_read_b128 v[52:55], v181 offset:11264
	ds_read_b128 v[56:59], v96 offset:35840
	ds_read_b128 v[60:63], v96 offset:27648
	v_pk_mul_f32 v[64:65], v[64:65], v[50:51] op_sel_hi:[1,0]
	v_pk_mul_f32 v[66:67], v[66:67], v[50:51] op_sel_hi:[1,0]
	s_waitcnt lgkmcnt(2)
	v_pk_mul_f32 v[52:53], v[64:65], v[52:53]
	s_waitcnt lgkmcnt(1)
	v_pk_add_f32 v[56:57], v[56:57], 1.0 op_sel_hi:[1,0]
	v_pk_mul_f32 v[54:55], v[66:67], v[54:55]
	s_waitcnt lgkmcnt(0)
	v_pk_fma_f32 v[52:53], v[52:53], v[56:57], v[60:61]
	v_pk_add_f32 v[58:59], v[58:59], 1.0 op_sel_hi:[1,0]
	v_bfe_u32 v51, v52, 16, 1
	v_add3_u32 v51, v52, v51, s79
	v_bfe_u32 v52, v53, 16, 1
	v_pk_fma_f32 v[54:55], v[54:55], v[58:59], v[62:63]
	v_lshrrev_b32_e32 v51, 16, v51
	v_add3_u32 v52, v53, v52, s79
	v_and_or_b32 v52, v52, s75, v51
	v_bfe_u32 v51, v54, 16, 1
	v_add3_u32 v51, v54, v51, s79
	v_bfe_u32 v53, v55, 16, 1
	v_lshrrev_b32_e32 v51, 16, v51
	v_add3_u32 v53, v55, v53, s79
	v_and_or_b32 v53, v53, s75, v51
	global_store_dwordx2 v[48:49], v[52:53], off offset:1536 sc0 sc1
	ds_read_b128 v[52:55], v181 offset:12288
	ds_read_b128 v[56:59], v96 offset:36864
	ds_read_b128 v[60:63], v96 offset:28672
	v_pk_mul_f32 v[46:47], v[46:47], v[50:51] op_sel_hi:[1,0]
	v_pk_mul_f32 v[44:45], v[44:45], v[50:51] op_sel_hi:[1,0]
	s_waitcnt lgkmcnt(2)
	v_pk_mul_f32 v[46:47], v[46:47], v[54:55]
	v_pk_mul_f32 v[44:45], v[44:45], v[52:53]
	s_waitcnt lgkmcnt(1)
	v_pk_add_f32 v[54:55], v[56:57], 1.0 op_sel_hi:[1,0]
	v_pk_add_f32 v[52:53], v[58:59], 1.0 op_sel_hi:[1,0]
	s_waitcnt lgkmcnt(0)
	v_pk_fma_f32 v[44:45], v[44:45], v[54:55], v[60:61]
	v_pk_fma_f32 v[46:47], v[46:47], v[52:53], v[62:63]
	v_bfe_u32 v51, v44, 16, 1
	v_add3_u32 v44, v44, v51, s79
	v_bfe_u32 v51, v45, 16, 1
	v_lshrrev_b32_e32 v44, 16, v44
	v_add3_u32 v45, v45, v51, s79
	v_and_or_b32 v44, v45, s75, v44
	v_bfe_u32 v45, v46, 16, 1
	v_add3_u32 v45, v46, v45, s79
	v_bfe_u32 v46, v47, 16, 1
	v_lshrrev_b32_e32 v45, 16, v45
	v_add3_u32 v46, v47, v46, s79
	v_and_or_b32 v45, v46, s75, v45
	global_store_dwordx2 v[48:49], v[44:45], off offset:2048 sc0 sc1
	ds_read_b128 v[44:47], v181 offset:13312
	ds_read_b128 v[52:55], v96 offset:37888
	ds_read_b128 v[56:59], v96 offset:29696
	v_pk_mul_f32 v[42:43], v[42:43], v[50:51] op_sel_hi:[1,0]
	v_pk_mul_f32 v[40:41], v[40:41], v[50:51] op_sel_hi:[1,0]
	s_waitcnt lgkmcnt(2)
	v_pk_mul_f32 v[42:43], v[42:43], v[46:47]
	v_pk_mul_f32 v[40:41], v[40:41], v[44:45]
	s_waitcnt lgkmcnt(1)
	v_pk_add_f32 v[46:47], v[52:53], 1.0 op_sel_hi:[1,0]
	v_pk_add_f32 v[44:45], v[54:55], 1.0 op_sel_hi:[1,0]
	s_waitcnt lgkmcnt(0)
	v_pk_fma_f32 v[40:41], v[40:41], v[46:47], v[56:57]
	v_pk_fma_f32 v[42:43], v[42:43], v[44:45], v[58:59]
	v_bfe_u32 v44, v40, 16, 1
	v_add3_u32 v40, v40, v44, s79
	v_bfe_u32 v44, v41, 16, 1
	v_lshrrev_b32_e32 v40, 16, v40
	v_add3_u32 v41, v41, v44, s79
	v_and_or_b32 v40, v41, s75, v40
	v_bfe_u32 v41, v42, 16, 1
	v_add3_u32 v41, v42, v41, s79
	v_bfe_u32 v42, v43, 16, 1
	v_lshrrev_b32_e32 v41, 16, v41
	v_add3_u32 v42, v43, v42, s79
	v_and_or_b32 v41, v42, s75, v41
	global_store_dwordx2 v[48:49], v[40:41], off offset:2560 sc0 sc1
	ds_read_b128 v[40:43], v181 offset:14336
	ds_read_b128 v[44:47], v96 offset:38912
	ds_read_b128 v[52:55], v96 offset:30720
	v_pk_mul_f32 v[38:39], v[38:39], v[50:51] op_sel_hi:[1,0]
	v_pk_mul_f32 v[36:37], v[36:37], v[50:51] op_sel_hi:[1,0]
	s_waitcnt lgkmcnt(2)
	v_pk_mul_f32 v[38:39], v[38:39], v[42:43]
	v_pk_mul_f32 v[36:37], v[36:37], v[40:41]
	s_waitcnt lgkmcnt(1)
	v_pk_add_f32 v[42:43], v[44:45], 1.0 op_sel_hi:[1,0]
	v_pk_add_f32 v[40:41], v[46:47], 1.0 op_sel_hi:[1,0]
	s_waitcnt lgkmcnt(0)
	v_pk_fma_f32 v[36:37], v[36:37], v[42:43], v[52:53]
	v_pk_fma_f32 v[38:39], v[38:39], v[40:41], v[54:55]
	v_bfe_u32 v40, v36, 16, 1
	v_add3_u32 v36, v36, v40, s79
	v_bfe_u32 v40, v37, 16, 1
	v_lshrrev_b32_e32 v36, 16, v36
	v_add3_u32 v37, v37, v40, s79
	v_and_or_b32 v36, v37, s75, v36
	v_bfe_u32 v37, v38, 16, 1
	v_add3_u32 v37, v38, v37, s79
	v_bfe_u32 v38, v39, 16, 1
	v_lshrrev_b32_e32 v37, 16, v37
	v_add3_u32 v38, v39, v38, s79
	v_and_or_b32 v37, v38, s75, v37
	global_store_dwordx2 v[48:49], v[36:37], off offset:3072 sc0 sc1
	ds_read_b128 v[36:39], v181 offset:15360
	ds_read_b128 v[40:43], v96 offset:39936
	ds_read_b128 v[44:47], v96 offset:31744
	v_pk_mul_f32 v[34:35], v[34:35], v[50:51] op_sel_hi:[1,0]
	v_pk_mul_f32 v[32:33], v[32:33], v[50:51] op_sel_hi:[1,0]
	s_waitcnt lgkmcnt(2)
	v_pk_mul_f32 v[34:35], v[34:35], v[38:39]
	v_pk_mul_f32 v[32:33], v[32:33], v[36:37]
	s_waitcnt lgkmcnt(1)
	v_pk_add_f32 v[38:39], v[40:41], 1.0 op_sel_hi:[1,0]
	v_pk_add_f32 v[36:37], v[42:43], 1.0 op_sel_hi:[1,0]
	s_waitcnt lgkmcnt(0)
	v_pk_fma_f32 v[32:33], v[32:33], v[38:39], v[44:45]
	v_pk_fma_f32 v[34:35], v[34:35], v[36:37], v[46:47]
	v_bfe_u32 v36, v32, 16, 1
	v_add3_u32 v32, v32, v36, s79
	v_bfe_u32 v36, v33, 16, 1
	v_lshrrev_b32_e32 v32, 16, v32
	v_add3_u32 v33, v33, v36, s79
	v_and_or_b32 v32, v33, s75, v32
	v_bfe_u32 v33, v34, 16, 1
	v_add3_u32 v33, v34, v33, s79
	v_bfe_u32 v34, v35, 16, 1
	v_lshrrev_b32_e32 v33, 16, v33
	v_add3_u32 v34, v35, v34, s79
	v_and_or_b32 v33, v34, s75, v33
	global_store_dwordx2 v[48:49], v[32:33], off offset:3584 sc0 sc1
	s_branch .LBB0_1207
